# attention: one packed multiply-add chain per key batch interleaved with the conversions, first P.V batch multiplies instead of accumulating onto zeros; plus DPP min/max in top-k compaction
# speedup vs baseline: 1.0224x; 1.0224x over previous
; #define LDS_WAIT() asm volatile("s_waitcnt lgkmcnt(0)" ::: "memory")
; __device__ __forceinline__ int lane_id() { int l; asm volatile("v_mbcnt_lo_u32_b32 %0, -1, 0\n\tv_mbcnt_hi_u32_b32 %0, -1, %0\n\ts_nop 1" : "=v"(l)); return l; }
; __device__ __forceinline__ unsigned f2ord(float f) { const unsigned u = __float_as_uint(f); return u ^ ((u >> 31) ? 0xFFFFFFFFu : 0x80000000u); }
; __device__ __forceinline__ int topk_compact(LAS u32x2* buf, int cnt, float& tau) {
;     const int lane = lane_id();
;     LDS_WAIT();
;     unsigned key[12], idx[12];
;     unsigned kmin = 0xFFFFFFFFu, kmax = 0u;
; #pragma unroll
;     for (int j = 0; j < 12; ++j) { const int e = j * 64 + lane; const u32x2 v = buf[e]; const bool ok = e < cnt; const unsigned k = f2ord(__uint_as_float(v.x)); key[j] = ok ? k : 0u; idx[j] = v.y;
;         kmin = (ok && k < kmin) ? k : kmin; kmax = (ok && k > kmax) ? k : kmax; }
; #pragma unroll
;     for (int o = 1; o < 64; o <<= 1) { const unsigned a = (unsigned)__shfl_xor((int)kmin, o), b = (unsigned)__shfl_xor((int)kmax, o); kmin = a < kmin ? a : kmin; kmax = b > kmax ? b : kmax; }
;     const unsigned diff = (unsigned)__builtin_amdgcn_readfirstlane((int)(kmin ^ kmax));
;     int bit = diff ? (31 - __builtin_clz(diff)) : -1;
;     unsigned T = (bit >= 0) ? (unsigned)__builtin_amdgcn_readfirstlane((int)kmin) & ~((2u << bit) - 1u) : (unsigned)__builtin_amdgcn_readfirstlane((int)kmin);
.Lidx_compact:
	s_cmpk_lt_i32 s74, 0x101
	s_cbranch_scc1 .LBB0_485
	v_mbcnt_lo_u32_b32 v25, -1, 0
	v_mbcnt_hi_u32_b32 v25, -1, v25
	s_nop 1
	s_waitcnt lgkmcnt(0)
	s_nop 0
	v_lshl_add_u32 v0, v25, 3, s97
	ds_read2st64_b64 v[20:23], v0 offset1:1
	ds_read2st64_b64 v[8:11], v0 offset0:2 offset1:3
	v_add_u32_e32 v2, 64, v25
	v_cmp_gt_i32_e64 s[12:13], s74, v2
	ds_read2st64_b64 v[16:19], v0 offset0:4 offset1:5
	ds_read2st64_b64 v[12:15], v0 offset0:6 offset1:7
	s_waitcnt lgkmcnt(3)
	v_cmp_lt_i32_e32 vcc, -1, v20
	v_add_u32_e32 v27, 0x200, v25
	v_cmp_gt_i32_e64 s[26:27], s74, v27
	v_cndmask_b32_e32 v1, -1, v123, vcc
	v_xor_b32_e32 v1, v1, v20
	v_cmp_gt_i32_e32 vcc, s74, v25
	s_nop 1
	v_cndmask_b32_e32 v24, 0, v1, vcc
	v_cndmask_b32_e32 v1, -1, v1, vcc
	v_cmp_lt_i32_e32 vcc, -1, v22
	s_nop 1
	v_cndmask_b32_e32 v3, -1, v123, vcc
	v_xor_b32_e32 v20, v3, v22
	s_waitcnt lgkmcnt(2)
	v_cmp_lt_i32_e32 vcc, -1, v8
	v_min_u32_e32 v3, v20, v1
	v_cndmask_b32_e64 v1, v1, v3, s[12:13]
	v_cndmask_b32_e32 v4, -1, v123, vcc
	v_max_u32_e32 v2, v20, v24
	v_add_u32_e32 v3, 0x80, v25
	v_xor_b32_e32 v8, v4, v8
	v_cndmask_b32_e64 v2, v24, v2, s[12:13]
	v_min_u32_e32 v4, v8, v1
	v_cmp_gt_i32_e64 s[14:15], s74, v3
	v_cmp_lt_i32_e32 vcc, -1, v10
	v_max_u32_e32 v3, v8, v2
	v_cndmask_b32_e64 v1, v1, v4, s[14:15]
	v_cndmask_b32_e32 v4, -1, v123, vcc
	v_cndmask_b32_e64 v2, v2, v3, s[14:15]
	v_add_u32_e32 v3, 0xc0, v25
	v_xor_b32_e32 v10, v4, v10
	v_min_u32_e32 v4, v10, v1
	v_cmp_gt_i32_e64 s[16:17], s74, v3
	s_waitcnt lgkmcnt(1)
	v_cmp_lt_i32_e32 vcc, -1, v16
	v_max_u32_e32 v3, v10, v2
	v_cndmask_b32_e64 v1, v1, v4, s[16:17]
	v_cndmask_b32_e32 v4, -1, v123, vcc
	v_cndmask_b32_e64 v2, v2, v3, s[16:17]
	v_add_u32_e32 v3, 0x100, v25
	v_xor_b32_e32 v16, v4, v16
	v_min_u32_e32 v4, v16, v1
	v_cmp_gt_i32_e64 s[18:19], s74, v3
	v_cmp_lt_i32_e32 vcc, -1, v18
	v_max_u32_e32 v3, v16, v2
	v_cndmask_b32_e64 v1, v1, v4, s[18:19]
	v_cndmask_b32_e32 v4, -1, v123, vcc
	v_cndmask_b32_e64 v2, v2, v3, s[18:19]
	v_add_u32_e32 v3, 0x140, v25
	v_xor_b32_e32 v18, v4, v18
	v_min_u32_e32 v4, v18, v1
	v_cmp_gt_i32_e64 s[20:21], s74, v3
	s_waitcnt lgkmcnt(0)
	v_cmp_lt_i32_e32 vcc, -1, v12
	v_max_u32_e32 v3, v18, v2
	v_cndmask_b32_e64 v1, v1, v4, s[20:21]
	v_cndmask_b32_e32 v4, -1, v123, vcc
	v_cndmask_b32_e64 v2, v2, v3, s[20:21]
	v_add_u32_e32 v3, 0x180, v25
	v_xor_b32_e32 v12, v4, v12
	v_min_u32_e32 v4, v12, v1
	v_cmp_gt_i32_e64 s[22:23], s74, v3
	v_cmp_lt_i32_e32 vcc, -1, v14
	v_max_u32_e32 v3, v12, v2
	v_cndmask_b32_e64 v1, v1, v4, s[22:23]
	v_cndmask_b32_e32 v4, -1, v123, vcc
	v_cndmask_b32_e64 v2, v2, v3, s[22:23]
	v_add_u32_e32 v3, 0x1c0, v25
	v_xor_b32_e32 v14, v4, v14
	v_min_u32_e32 v4, v14, v1
	v_cmp_gt_i32_e64 s[24:25], s74, v3
	s_nop 1
	v_cndmask_b32_e64 v22, v1, v4, s[24:25]
	ds_read2st64_b64 v[4:7], v0 offset0:8 offset1:9
	v_max_u32_e32 v1, v14, v2
	v_cndmask_b32_e64 v26, v2, v1, s[24:25]
	ds_read2st64_b64 v[0:3], v0 offset0:10 offset1:11
	s_waitcnt lgkmcnt(1)
	v_cmp_lt_i32_e32 vcc, -1, v4
	s_nop 1
	v_cndmask_b32_e32 v28, -1, v123, vcc
	v_xor_b32_e32 v4, v28, v4
	v_min_u32_e32 v28, v4, v22
	v_cmp_lt_i32_e32 vcc, -1, v6
	v_cndmask_b32_e64 v22, v22, v28, s[26:27]
	v_max_u32_e32 v27, v4, v26
	v_cndmask_b32_e32 v28, -1, v123, vcc
	v_cndmask_b32_e64 v26, v26, v27, s[26:27]
	v_add_u32_e32 v27, 0x240, v25
	v_xor_b32_e32 v6, v28, v6
	v_min_u32_e32 v28, v6, v22
	v_cmp_gt_i32_e64 s[28:29], s74, v27
	s_waitcnt lgkmcnt(0)
	v_cmp_lt_i32_e32 vcc, -1, v0
	v_max_u32_e32 v27, v6, v26
	v_cndmask_b32_e64 v22, v22, v28, s[28:29]
	v_cndmask_b32_e32 v28, -1, v123, vcc
	v_cndmask_b32_e64 v26, v26, v27, s[28:29]
	v_add_u32_e32 v27, 0x280, v25
	v_xor_b32_e32 v0, v28, v0
	v_cmp_gt_i32_e64 s[30:31], s74, v27
	v_max_u32_e32 v27, v0, v26
	v_cmp_lt_i32_e32 vcc, -1, v2
	v_cndmask_b32_e64 v26, v26, v27, s[30:31]
	v_min_u32_e32 v28, v0, v22
	v_cndmask_b32_e32 v27, -1, v123, vcc
	v_add_u32_e32 v25, 0x2c0, v25
	v_xor_b32_e32 v2, v27, v2
	v_cndmask_b32_e64 v22, v22, v28, s[30:31]
	v_cmp_gt_i32_e64 s[34:35], s74, v25
	v_max_u32_e32 v25, v2, v26
	v_min_u32_e32 v27, v2, v22
	v_cndmask_b32_e64 v25, v26, v25, s[34:35]
	v_and_b32_e32 v26, 64, v144
	v_cndmask_b32_e64 v22, v22, v27, s[34:35]
	v_add_u32_e32 v26, 64, v26
	s_nop 1
	v_min_u32_dpp v22, v22, v22 row_shr:1 row_mask:0xf bank_mask:0xf
	v_max_u32_dpp v25, v25, v25 row_shr:1 row_mask:0xf bank_mask:0xf
	s_nop 0
	v_min_u32_dpp v22, v22, v22 row_shr:2 row_mask:0xf bank_mask:0xf
	v_max_u32_dpp v25, v25, v25 row_shr:2 row_mask:0xf bank_mask:0xf
	s_nop 0
	v_min_u32_dpp v22, v22, v22 row_shr:4 row_mask:0xf bank_mask:0xf
	v_max_u32_dpp v25, v25, v25 row_shr:4 row_mask:0xf bank_mask:0xf
	s_nop 0
	v_min_u32_dpp v22, v22, v22 row_shr:8 row_mask:0xf bank_mask:0xf
	v_max_u32_dpp v25, v25, v25 row_shr:8 row_mask:0xf bank_mask:0xf
	s_nop 0
	v_readlane_b32 s4, v22, 15
	v_readlane_b32 s5, v22, 31
	s_min_u32 s4, s4, s5
	v_readlane_b32 s5, v22, 47
	s_min_u32 s4, s4, s5
	v_readlane_b32 s5, v22, 63
	s_min_u32 s4, s4, s5
	v_mov_b32_e32 v22, s4
	v_readlane_b32 s4, v25, 15
	v_readlane_b32 s5, v25, 31
	s_max_u32 s4, s4, s5
	v_readlane_b32 s5, v25, 47
	s_max_u32 s4, s4, s5
	v_readlane_b32 s5, v25, 63
	s_max_u32 s4, s4, s5
	v_mov_b32_e32 v25, s4
	v_xor_b32_e32 v25, v22, v25
	s_nop 0
	v_readfirstlane_b32 s5, v25
	s_cmp_lg_u32 s5, 0
	s_flbit_i32_b32 s4, s5
	s_cselect_b64 s[36:37], -1, 0
	s_xor_b32 s4, s4, 31
	s_cmp_eq_u32 s5, 0
	s_cbranch_scc1 .LBB0_456
	v_readfirstlane_b32 s5, v22
	s_lshl_b32 s94, -2, s4
	s_and_b32 s5, s5, s94
	s_cbranch_execnz .LBB0_395

; #define LDS_WAIT() asm volatile("s_waitcnt lgkmcnt(0)" ::: "memory")
; __device__ __forceinline__ int lane_id() { int l; asm volatile("v_mbcnt_lo_u32_b32 %0, -1, 0\n\tv_mbcnt_hi_u32_b32 %0, -1, %0\n\ts_nop 1" : "=v"(l)); return l; }
; __device__ __forceinline__ unsigned f2ord(float f) { const unsigned u = __float_as_uint(f); return u ^ ((u >> 31) ? 0xFFFFFFFFu : 0x80000000u); }
; __device__ __forceinline__ int topk_compact(LAS u32x2* buf, int cnt, float& tau) {
;     const int lane = lane_id();
;     LDS_WAIT();
;     unsigned key[12], idx[12];
;     unsigned kmin = 0xFFFFFFFFu, kmax = 0u;
; #pragma unroll
;     for (int j = 0; j < 12; ++j) { const int e = j * 64 + lane; const u32x2 v = buf[e]; const bool ok = e < cnt; const unsigned k = f2ord(__uint_as_float(v.x)); key[j] = ok ? k : 0u; idx[j] = v.y;
;         kmin = (ok && k < kmin) ? k : kmin; kmax = (ok && k > kmax) ? k : kmax; }
; #pragma unroll
;     for (int o = 1; o < 64; o <<= 1) { const unsigned a = (unsigned)__shfl_xor((int)kmin, o), b = (unsigned)__shfl_xor((int)kmax, o); kmin = a < kmin ? a : kmin; kmax = b > kmax ? b : kmax; }
;     const unsigned diff = (unsigned)__builtin_amdgcn_readfirstlane((int)(kmin ^ kmax));
;     int bit = diff ? (31 - __builtin_clz(diff)) : -1;
;     unsigned T = (bit >= 0) ? (unsigned)__builtin_amdgcn_readfirstlane((int)kmin) & ~((2u << bit) - 1u) : (unsigned)__builtin_amdgcn_readfirstlane((int)kmin);
.LBB0_485:
	s_cmpk_lt_i32 s75, 0x101
	s_cbranch_scc1 .LBB0_571
	v_mbcnt_lo_u32_b32 v25, -1, 0
	v_mbcnt_hi_u32_b32 v25, -1, v25
	s_nop 1
	s_waitcnt lgkmcnt(0)
	s_nop 0
	v_lshl_add_u32 v0, v25, 3, s97
	ds_read2st64_b64 v[20:23], v0 offset0:12 offset1:13
	ds_read2st64_b64 v[8:11], v0 offset0:14 offset1:15
	v_add_u32_e32 v2, 64, v25
	v_cmp_gt_i32_e64 s[12:13], s75, v2
	ds_read2st64_b64 v[16:19], v0 offset0:16 offset1:17
	ds_read2st64_b64 v[12:15], v0 offset0:18 offset1:19
	s_waitcnt lgkmcnt(3)
	v_cmp_lt_i32_e32 vcc, -1, v20
	v_add_u32_e32 v27, 0x200, v25
	v_cmp_gt_i32_e64 s[26:27], s75, v27
	v_cndmask_b32_e32 v1, -1, v123, vcc
	v_xor_b32_e32 v1, v1, v20
	v_cmp_gt_i32_e32 vcc, s75, v25
	s_nop 1
	v_cndmask_b32_e32 v24, 0, v1, vcc
	v_cndmask_b32_e32 v1, -1, v1, vcc
	v_cmp_lt_i32_e32 vcc, -1, v22
	s_nop 1
	v_cndmask_b32_e32 v3, -1, v123, vcc
	v_xor_b32_e32 v20, v3, v22
	s_waitcnt lgkmcnt(2)
	v_cmp_lt_i32_e32 vcc, -1, v8
	v_min_u32_e32 v3, v20, v1
	v_cndmask_b32_e64 v1, v1, v3, s[12:13]
	v_cndmask_b32_e32 v4, -1, v123, vcc
	v_max_u32_e32 v2, v20, v24
	v_add_u32_e32 v3, 0x80, v25
	v_xor_b32_e32 v8, v4, v8
	v_cndmask_b32_e64 v2, v24, v2, s[12:13]
	v_min_u32_e32 v4, v8, v1
	v_cmp_gt_i32_e64 s[14:15], s75, v3
	v_cmp_lt_i32_e32 vcc, -1, v10
	v_max_u32_e32 v3, v8, v2
	v_cndmask_b32_e64 v1, v1, v4, s[14:15]
	v_cndmask_b32_e32 v4, -1, v123, vcc
	v_cndmask_b32_e64 v2, v2, v3, s[14:15]
	v_add_u32_e32 v3, 0xc0, v25
	v_xor_b32_e32 v10, v4, v10
	v_min_u32_e32 v4, v10, v1
	v_cmp_gt_i32_e64 s[16:17], s75, v3
	s_waitcnt lgkmcnt(1)
	v_cmp_lt_i32_e32 vcc, -1, v16
	v_max_u32_e32 v3, v10, v2
	v_cndmask_b32_e64 v1, v1, v4, s[16:17]
	v_cndmask_b32_e32 v4, -1, v123, vcc
	v_cndmask_b32_e64 v2, v2, v3, s[16:17]
	v_add_u32_e32 v3, 0x100, v25
	v_xor_b32_e32 v16, v4, v16
	v_min_u32_e32 v4, v16, v1
	v_cmp_gt_i32_e64 s[18:19], s75, v3
	v_cmp_lt_i32_e32 vcc, -1, v18
	v_max_u32_e32 v3, v16, v2
	v_cndmask_b32_e64 v1, v1, v4, s[18:19]
	v_cndmask_b32_e32 v4, -1, v123, vcc
	v_cndmask_b32_e64 v2, v2, v3, s[18:19]
	v_add_u32_e32 v3, 0x140, v25
	v_xor_b32_e32 v18, v4, v18
	v_min_u32_e32 v4, v18, v1
	v_cmp_gt_i32_e64 s[20:21], s75, v3
	s_waitcnt lgkmcnt(0)
	v_cmp_lt_i32_e32 vcc, -1, v12
	v_max_u32_e32 v3, v18, v2
	v_cndmask_b32_e64 v1, v1, v4, s[20:21]
	v_cndmask_b32_e32 v4, -1, v123, vcc
	v_cndmask_b32_e64 v2, v2, v3, s[20:21]
	v_add_u32_e32 v3, 0x180, v25
	v_xor_b32_e32 v12, v4, v12
	v_min_u32_e32 v4, v12, v1
	v_cmp_gt_i32_e64 s[22:23], s75, v3
	v_cmp_lt_i32_e32 vcc, -1, v14
	v_max_u32_e32 v3, v12, v2
	v_cndmask_b32_e64 v1, v1, v4, s[22:23]
	v_cndmask_b32_e32 v4, -1, v123, vcc
	v_cndmask_b32_e64 v2, v2, v3, s[22:23]
	v_add_u32_e32 v3, 0x1c0, v25
	v_xor_b32_e32 v14, v4, v14
	v_min_u32_e32 v4, v14, v1
	v_cmp_gt_i32_e64 s[24:25], s75, v3
	s_nop 1
	v_cndmask_b32_e64 v22, v1, v4, s[24:25]
	ds_read2st64_b64 v[4:7], v0 offset0:20 offset1:21
	v_max_u32_e32 v1, v14, v2
	v_cndmask_b32_e64 v26, v2, v1, s[24:25]
	ds_read2st64_b64 v[0:3], v0 offset0:22 offset1:23
	s_waitcnt lgkmcnt(1)
	v_cmp_lt_i32_e32 vcc, -1, v4
	s_nop 1
	v_cndmask_b32_e32 v28, -1, v123, vcc
	v_xor_b32_e32 v4, v28, v4
	v_min_u32_e32 v28, v4, v22
	v_cmp_lt_i32_e32 vcc, -1, v6
	v_cndmask_b32_e64 v22, v22, v28, s[26:27]
	v_max_u32_e32 v27, v4, v26
	v_cndmask_b32_e32 v28, -1, v123, vcc
	v_cndmask_b32_e64 v26, v26, v27, s[26:27]
	v_add_u32_e32 v27, 0x240, v25
	v_xor_b32_e32 v6, v28, v6
	v_min_u32_e32 v28, v6, v22
	v_cmp_gt_i32_e64 s[28:29], s75, v27
	s_waitcnt lgkmcnt(0)
	v_cmp_lt_i32_e32 vcc, -1, v0
	v_max_u32_e32 v27, v6, v26
	v_cndmask_b32_e64 v22, v22, v28, s[28:29]
	v_cndmask_b32_e32 v28, -1, v123, vcc
	v_cndmask_b32_e64 v26, v26, v27, s[28:29]
	v_add_u32_e32 v27, 0x280, v25
	v_xor_b32_e32 v0, v28, v0
	v_cmp_gt_i32_e64 s[30:31], s75, v27
	v_max_u32_e32 v27, v0, v26
	v_cmp_lt_i32_e32 vcc, -1, v2
	v_cndmask_b32_e64 v26, v26, v27, s[30:31]
	v_min_u32_e32 v28, v0, v22
	v_cndmask_b32_e32 v27, -1, v123, vcc
	v_add_u32_e32 v25, 0x2c0, v25
	v_xor_b32_e32 v2, v27, v2
	v_cndmask_b32_e64 v22, v22, v28, s[30:31]
	v_cmp_gt_i32_e64 s[34:35], s75, v25
	v_max_u32_e32 v25, v2, v26
	v_min_u32_e32 v27, v2, v22
	v_cndmask_b32_e64 v25, v26, v25, s[34:35]
	v_and_b32_e32 v26, 64, v144
	v_cndmask_b32_e64 v22, v22, v27, s[34:35]
	v_add_u32_e32 v26, 64, v26
	s_nop 1
	v_min_u32_dpp v22, v22, v22 row_shr:1 row_mask:0xf bank_mask:0xf
	v_max_u32_dpp v25, v25, v25 row_shr:1 row_mask:0xf bank_mask:0xf
	s_nop 0
	v_min_u32_dpp v22, v22, v22 row_shr:2 row_mask:0xf bank_mask:0xf
	v_max_u32_dpp v25, v25, v25 row_shr:2 row_mask:0xf bank_mask:0xf
	s_nop 0
	v_min_u32_dpp v22, v22, v22 row_shr:4 row_mask:0xf bank_mask:0xf
	v_max_u32_dpp v25, v25, v25 row_shr:4 row_mask:0xf bank_mask:0xf
	s_nop 0
	v_min_u32_dpp v22, v22, v22 row_shr:8 row_mask:0xf bank_mask:0xf
	v_max_u32_dpp v25, v25, v25 row_shr:8 row_mask:0xf bank_mask:0xf
	s_nop 0
	v_readlane_b32 s4, v22, 15
	v_readlane_b32 s5, v22, 31
	s_min_u32 s4, s4, s5
	v_readlane_b32 s5, v22, 47
	s_min_u32 s4, s4, s5
	v_readlane_b32 s5, v22, 63
	s_min_u32 s4, s4, s5
	v_mov_b32_e32 v22, s4
	v_readlane_b32 s4, v25, 15
	v_readlane_b32 s5, v25, 31
	s_max_u32 s4, s4, s5
	v_readlane_b32 s5, v25, 47
	s_max_u32 s4, s4, s5
	v_readlane_b32 s5, v25, 63
	s_max_u32 s4, s4, s5
	v_mov_b32_e32 v25, s4
	v_xor_b32_e32 v25, v22, v25
	s_nop 0
	v_readfirstlane_b32 s5, v25
	s_cmp_lg_u32 s5, 0
	s_flbit_i32_b32 s4, s5
	s_cselect_b64 s[36:37], -1, 0
	s_xor_b32 s4, s4, 31
	s_cmp_eq_u32 s5, 0
	s_cbranch_scc1 .LBB0_542
	v_readfirstlane_b32 s5, v22
	s_lshl_b32 s94, -2, s4
	s_and_b32 s5, s5, s94
	s_cbranch_execnz .LBB0_489

; #define LDS_WAIT() asm volatile("s_waitcnt lgkmcnt(0)" ::: "memory")
; __device__ __forceinline__ int lane_id() { int l; asm volatile("v_mbcnt_lo_u32_b32 %0, -1, 0\n\tv_mbcnt_hi_u32_b32 %0, -1, %0\n\ts_nop 1" : "=v"(l)); return l; }
; __device__ __forceinline__ unsigned f2ord(float f) { const unsigned u = __float_as_uint(f); return u ^ ((u >> 31) ? 0xFFFFFFFFu : 0x80000000u); }
; __device__ __forceinline__ int topk_compact(LAS u32x2* buf, int cnt, float& tau) {
;     const int lane = lane_id();
;     LDS_WAIT();
;     unsigned key[12], idx[12];
;     unsigned kmin = 0xFFFFFFFFu, kmax = 0u;
; #pragma unroll
;     for (int j = 0; j < 12; ++j) { const int e = j * 64 + lane; const u32x2 v = buf[e]; const bool ok = e < cnt; const unsigned k = f2ord(__uint_as_float(v.x)); key[j] = ok ? k : 0u; idx[j] = v.y;
;         kmin = (ok && k < kmin) ? k : kmin; kmax = (ok && k > kmax) ? k : kmax; }
; #pragma unroll
;     for (int o = 1; o < 64; o <<= 1) { const unsigned a = (unsigned)__shfl_xor((int)kmin, o), b = (unsigned)__shfl_xor((int)kmax, o); kmin = a < kmin ? a : kmin; kmax = b > kmax ? b : kmax; }
;     const unsigned diff = (unsigned)__builtin_amdgcn_readfirstlane((int)(kmin ^ kmax));
;     int bit = diff ? (31 - __builtin_clz(diff)) : -1;
;     unsigned T = (bit >= 0) ? (unsigned)__builtin_amdgcn_readfirstlane((int)kmin) & ~((2u << bit) - 1u) : (unsigned)__builtin_amdgcn_readfirstlane((int)kmin);
.LBB0_573:
	s_cmpk_gt_i32 s74, 0x100
	s_cbranch_scc0 .LBB0_659
	v_mbcnt_lo_u32_b32 v25, -1, 0
	v_mbcnt_hi_u32_b32 v25, -1, v25
	s_nop 1
	s_waitcnt lgkmcnt(0)
	s_waitcnt vmcnt(0)
	v_lshl_add_u32 v0, v25, 3, s97
	ds_read2st64_b64 v[20:23], v0 offset1:1
	ds_read2st64_b64 v[8:11], v0 offset0:2 offset1:3
	v_add_u32_e32 v2, 64, v25
	v_cmp_gt_i32_e64 s[6:7], s74, v2
	ds_read2st64_b64 v[16:19], v0 offset0:4 offset1:5
	ds_read2st64_b64 v[12:15], v0 offset0:6 offset1:7
	s_waitcnt lgkmcnt(3)
	v_cmp_lt_i32_e32 vcc, -1, v20
	v_add_u32_e32 v27, 0x200, v25
	v_cmp_gt_i32_e64 s[20:21], s74, v27
	v_cndmask_b32_e32 v1, -1, v123, vcc
	v_xor_b32_e32 v1, v1, v20
	v_cmp_gt_i32_e32 vcc, s74, v25
	s_nop 1
	v_cndmask_b32_e32 v24, 0, v1, vcc
	v_cndmask_b32_e32 v1, -1, v1, vcc
	v_cmp_lt_i32_e32 vcc, -1, v22
	s_nop 1
	v_cndmask_b32_e32 v3, -1, v123, vcc
	v_xor_b32_e32 v20, v3, v22
	s_waitcnt lgkmcnt(2)
	v_cmp_lt_i32_e32 vcc, -1, v8
	v_min_u32_e32 v3, v20, v1
	v_cndmask_b32_e64 v1, v1, v3, s[6:7]
	v_cndmask_b32_e32 v4, -1, v123, vcc
	v_max_u32_e32 v2, v20, v24
	v_add_u32_e32 v3, 0x80, v25
	v_xor_b32_e32 v8, v4, v8
	v_cndmask_b32_e64 v2, v24, v2, s[6:7]
	v_min_u32_e32 v4, v8, v1
	v_cmp_gt_i32_e64 s[8:9], s74, v3
	v_cmp_lt_i32_e32 vcc, -1, v10
	v_max_u32_e32 v3, v8, v2
	v_cndmask_b32_e64 v1, v1, v4, s[8:9]
	v_cndmask_b32_e32 v4, -1, v123, vcc
	v_cndmask_b32_e64 v2, v2, v3, s[8:9]
	v_add_u32_e32 v3, 0xc0, v25
	v_xor_b32_e32 v10, v4, v10
	v_min_u32_e32 v4, v10, v1
	v_cmp_gt_i32_e64 s[10:11], s74, v3
	s_waitcnt lgkmcnt(1)
	v_cmp_lt_i32_e32 vcc, -1, v16
	v_max_u32_e32 v3, v10, v2
	v_cndmask_b32_e64 v1, v1, v4, s[10:11]
	v_cndmask_b32_e32 v4, -1, v123, vcc
	v_cndmask_b32_e64 v2, v2, v3, s[10:11]
	v_add_u32_e32 v3, 0x100, v25
	v_xor_b32_e32 v16, v4, v16
	v_min_u32_e32 v4, v16, v1
	v_cmp_gt_i32_e64 s[12:13], s74, v3
	v_cmp_lt_i32_e32 vcc, -1, v18
	v_max_u32_e32 v3, v16, v2
	v_cndmask_b32_e64 v1, v1, v4, s[12:13]
	v_cndmask_b32_e32 v4, -1, v123, vcc
	v_cndmask_b32_e64 v2, v2, v3, s[12:13]
	v_add_u32_e32 v3, 0x140, v25
	v_xor_b32_e32 v18, v4, v18
	v_min_u32_e32 v4, v18, v1
	v_cmp_gt_i32_e64 s[14:15], s74, v3
	s_waitcnt lgkmcnt(0)
	v_cmp_lt_i32_e32 vcc, -1, v12
	v_max_u32_e32 v3, v18, v2
	v_cndmask_b32_e64 v1, v1, v4, s[14:15]
	v_cndmask_b32_e32 v4, -1, v123, vcc
	v_cndmask_b32_e64 v2, v2, v3, s[14:15]
	v_add_u32_e32 v3, 0x180, v25
	v_xor_b32_e32 v12, v4, v12
	v_min_u32_e32 v4, v12, v1
	v_cmp_gt_i32_e64 s[16:17], s74, v3
	v_cmp_lt_i32_e32 vcc, -1, v14
	v_max_u32_e32 v3, v12, v2
	v_cndmask_b32_e64 v1, v1, v4, s[16:17]
	v_cndmask_b32_e32 v4, -1, v123, vcc
	v_cndmask_b32_e64 v2, v2, v3, s[16:17]
	v_add_u32_e32 v3, 0x1c0, v25
	v_xor_b32_e32 v14, v4, v14
	v_min_u32_e32 v4, v14, v1
	v_cmp_gt_i32_e64 s[18:19], s74, v3
	s_nop 1
	v_cndmask_b32_e64 v22, v1, v4, s[18:19]
	ds_read2st64_b64 v[4:7], v0 offset0:8 offset1:9
	v_max_u32_e32 v1, v14, v2
	v_cndmask_b32_e64 v26, v2, v1, s[18:19]
	ds_read2st64_b64 v[0:3], v0 offset0:10 offset1:11
	s_waitcnt lgkmcnt(1)
	v_cmp_lt_i32_e32 vcc, -1, v4
	s_nop 1
	v_cndmask_b32_e32 v28, -1, v123, vcc
	v_xor_b32_e32 v4, v28, v4
	v_min_u32_e32 v28, v4, v22
	v_cmp_lt_i32_e32 vcc, -1, v6
	v_cndmask_b32_e64 v22, v22, v28, s[20:21]
	v_max_u32_e32 v27, v4, v26
	v_cndmask_b32_e32 v28, -1, v123, vcc
	v_cndmask_b32_e64 v26, v26, v27, s[20:21]
	v_add_u32_e32 v27, 0x240, v25
	v_xor_b32_e32 v6, v28, v6
	v_min_u32_e32 v28, v6, v22
	v_cmp_gt_i32_e64 s[22:23], s74, v27
	s_waitcnt lgkmcnt(0)
	v_cmp_lt_i32_e32 vcc, -1, v0
	v_max_u32_e32 v27, v6, v26
	v_cndmask_b32_e64 v22, v22, v28, s[22:23]
	v_cndmask_b32_e32 v28, -1, v123, vcc
	v_cndmask_b32_e64 v26, v26, v27, s[22:23]
	v_add_u32_e32 v27, 0x280, v25
	v_xor_b32_e32 v0, v28, v0
	v_cmp_gt_i32_e64 s[24:25], s74, v27
	v_max_u32_e32 v27, v0, v26
	v_cmp_lt_i32_e32 vcc, -1, v2
	v_cndmask_b32_e64 v26, v26, v27, s[24:25]
	v_min_u32_e32 v28, v0, v22
	v_cndmask_b32_e32 v27, -1, v123, vcc
	v_add_u32_e32 v25, 0x2c0, v25
	v_xor_b32_e32 v2, v27, v2
	v_cndmask_b32_e64 v22, v22, v28, s[24:25]
	v_cmp_gt_i32_e64 s[26:27], s74, v25
	v_max_u32_e32 v25, v2, v26
	v_min_u32_e32 v27, v2, v22
	v_cndmask_b32_e64 v25, v26, v25, s[26:27]
	v_and_b32_e32 v26, 64, v144
	v_cndmask_b32_e64 v22, v22, v27, s[26:27]
	v_add_u32_e32 v26, 64, v26
	s_nop 1
	v_min_u32_dpp v22, v22, v22 row_shr:1 row_mask:0xf bank_mask:0xf
	v_max_u32_dpp v25, v25, v25 row_shr:1 row_mask:0xf bank_mask:0xf
	s_nop 0
	v_min_u32_dpp v22, v22, v22 row_shr:2 row_mask:0xf bank_mask:0xf
	v_max_u32_dpp v25, v25, v25 row_shr:2 row_mask:0xf bank_mask:0xf
	s_nop 0
	v_min_u32_dpp v22, v22, v22 row_shr:4 row_mask:0xf bank_mask:0xf
	v_max_u32_dpp v25, v25, v25 row_shr:4 row_mask:0xf bank_mask:0xf
	s_nop 0
	v_min_u32_dpp v22, v22, v22 row_shr:8 row_mask:0xf bank_mask:0xf
	v_max_u32_dpp v25, v25, v25 row_shr:8 row_mask:0xf bank_mask:0xf
	s_nop 0
	v_readlane_b32 s4, v22, 15
	v_readlane_b32 s5, v22, 31
	s_min_u32 s4, s4, s5
	v_readlane_b32 s5, v22, 47
	s_min_u32 s4, s4, s5
	v_readlane_b32 s5, v22, 63
	s_min_u32 s4, s4, s5
	v_mov_b32_e32 v22, s4
	v_readlane_b32 s4, v25, 15
	v_readlane_b32 s5, v25, 31
	s_max_u32 s4, s4, s5
	v_readlane_b32 s5, v25, 47
	s_max_u32 s4, s4, s5
	v_readlane_b32 s5, v25, 63
	s_max_u32 s4, s4, s5
	v_mov_b32_e32 v25, s4
	v_xor_b32_e32 v25, v22, v25
	s_nop 0
	v_readfirstlane_b32 s5, v25
	s_cmp_lg_u32 s5, 0
	s_flbit_i32_b32 s4, s5
	s_cselect_b64 s[28:29], -1, 0
	s_xor_b32 s4, s4, 31
	s_cmp_eq_u32 s5, 0
	s_cbranch_scc1 .LBB0_630
	v_readfirstlane_b32 s5, v22
	s_lshl_b32 s30, -2, s4
	s_and_b32 s5, s5, s30
	s_cbranch_execnz .LBB0_577

; #define LDS_WAIT() asm volatile("s_waitcnt lgkmcnt(0)" ::: "memory")
; __device__ __forceinline__ int lane_id() { int l; asm volatile("v_mbcnt_lo_u32_b32 %0, -1, 0\n\tv_mbcnt_hi_u32_b32 %0, -1, %0\n\ts_nop 1" : "=v"(l)); return l; }
; __device__ __forceinline__ unsigned f2ord(float f) { const unsigned u = __float_as_uint(f); return u ^ ((u >> 31) ? 0xFFFFFFFFu : 0x80000000u); }
; __device__ __forceinline__ int topk_compact(LAS u32x2* buf, int cnt, float& tau) {
;     const int lane = lane_id();
;     LDS_WAIT();
;     unsigned key[12], idx[12];
;     unsigned kmin = 0xFFFFFFFFu, kmax = 0u;
; #pragma unroll
;     for (int j = 0; j < 12; ++j) { const int e = j * 64 + lane; const u32x2 v = buf[e]; const bool ok = e < cnt; const unsigned k = f2ord(__uint_as_float(v.x)); key[j] = ok ? k : 0u; idx[j] = v.y;
;         kmin = (ok && k < kmin) ? k : kmin; kmax = (ok && k > kmax) ? k : kmax; }
; #pragma unroll
;     for (int o = 1; o < 64; o <<= 1) { const unsigned a = (unsigned)__shfl_xor((int)kmin, o), b = (unsigned)__shfl_xor((int)kmax, o); kmin = a < kmin ? a : kmin; kmax = b > kmax ? b : kmax; }
;     const unsigned diff = (unsigned)__builtin_amdgcn_readfirstlane((int)(kmin ^ kmax));
;     int bit = diff ? (31 - __builtin_clz(diff)) : -1;
;     unsigned T = (bit >= 0) ? (unsigned)__builtin_amdgcn_readfirstlane((int)kmin) & ~((2u << bit) - 1u) : (unsigned)__builtin_amdgcn_readfirstlane((int)kmin);
.LBB0_659:
	s_cmpk_lt_i32 s75, 0x101
	s_cbranch_scc1 .LBB0_745
	v_mbcnt_lo_u32_b32 v25, -1, 0
	v_mbcnt_hi_u32_b32 v25, -1, v25
	s_nop 1
	s_waitcnt lgkmcnt(0)
	s_waitcnt vmcnt(0)
	v_lshl_add_u32 v0, v25, 3, s97
	ds_read2st64_b64 v[20:23], v0 offset0:12 offset1:13
	ds_read2st64_b64 v[8:11], v0 offset0:14 offset1:15
	v_add_u32_e32 v2, 64, v25
	v_cmp_gt_i32_e64 s[6:7], s75, v2
	ds_read2st64_b64 v[16:19], v0 offset0:16 offset1:17
	ds_read2st64_b64 v[12:15], v0 offset0:18 offset1:19
	s_waitcnt lgkmcnt(3)
	v_cmp_lt_i32_e32 vcc, -1, v20
	v_add_u32_e32 v27, 0x200, v25
	v_cmp_gt_i32_e64 s[20:21], s75, v27
	v_cndmask_b32_e32 v1, -1, v123, vcc
	v_xor_b32_e32 v1, v1, v20
	v_cmp_gt_i32_e32 vcc, s75, v25
	s_nop 1
	v_cndmask_b32_e32 v24, 0, v1, vcc
	v_cndmask_b32_e32 v1, -1, v1, vcc
	v_cmp_lt_i32_e32 vcc, -1, v22
	s_nop 1
	v_cndmask_b32_e32 v3, -1, v123, vcc
	v_xor_b32_e32 v20, v3, v22
	s_waitcnt lgkmcnt(2)
	v_cmp_lt_i32_e32 vcc, -1, v8
	v_min_u32_e32 v3, v20, v1
	v_cndmask_b32_e64 v1, v1, v3, s[6:7]
	v_cndmask_b32_e32 v4, -1, v123, vcc
	v_max_u32_e32 v2, v20, v24
	v_add_u32_e32 v3, 0x80, v25
	v_xor_b32_e32 v8, v4, v8
	v_cndmask_b32_e64 v2, v24, v2, s[6:7]
	v_min_u32_e32 v4, v8, v1
	v_cmp_gt_i32_e64 s[8:9], s75, v3
	v_cmp_lt_i32_e32 vcc, -1, v10
	v_max_u32_e32 v3, v8, v2
	v_cndmask_b32_e64 v1, v1, v4, s[8:9]
	v_cndmask_b32_e32 v4, -1, v123, vcc
	v_cndmask_b32_e64 v2, v2, v3, s[8:9]
	v_add_u32_e32 v3, 0xc0, v25
	v_xor_b32_e32 v10, v4, v10
	v_min_u32_e32 v4, v10, v1
	v_cmp_gt_i32_e64 s[10:11], s75, v3
	s_waitcnt lgkmcnt(1)
	v_cmp_lt_i32_e32 vcc, -1, v16
	v_max_u32_e32 v3, v10, v2
	v_cndmask_b32_e64 v1, v1, v4, s[10:11]
	v_cndmask_b32_e32 v4, -1, v123, vcc
	v_cndmask_b32_e64 v2, v2, v3, s[10:11]
	v_add_u32_e32 v3, 0x100, v25
	v_xor_b32_e32 v16, v4, v16
	v_min_u32_e32 v4, v16, v1
	v_cmp_gt_i32_e64 s[12:13], s75, v3
	v_cmp_lt_i32_e32 vcc, -1, v18
	v_max_u32_e32 v3, v16, v2
	v_cndmask_b32_e64 v1, v1, v4, s[12:13]
	v_cndmask_b32_e32 v4, -1, v123, vcc
	v_cndmask_b32_e64 v2, v2, v3, s[12:13]
	v_add_u32_e32 v3, 0x140, v25
	v_xor_b32_e32 v18, v4, v18
	v_min_u32_e32 v4, v18, v1
	v_cmp_gt_i32_e64 s[14:15], s75, v3
	s_waitcnt lgkmcnt(0)
	v_cmp_lt_i32_e32 vcc, -1, v12
	v_max_u32_e32 v3, v18, v2
	v_cndmask_b32_e64 v1, v1, v4, s[14:15]
	v_cndmask_b32_e32 v4, -1, v123, vcc
	v_cndmask_b32_e64 v2, v2, v3, s[14:15]
	v_add_u32_e32 v3, 0x180, v25
	v_xor_b32_e32 v12, v4, v12
	v_min_u32_e32 v4, v12, v1
	v_cmp_gt_i32_e64 s[16:17], s75, v3
	v_cmp_lt_i32_e32 vcc, -1, v14
	v_max_u32_e32 v3, v12, v2
	v_cndmask_b32_e64 v1, v1, v4, s[16:17]
	v_cndmask_b32_e32 v4, -1, v123, vcc
	v_cndmask_b32_e64 v2, v2, v3, s[16:17]
	v_add_u32_e32 v3, 0x1c0, v25
	v_xor_b32_e32 v14, v4, v14
	v_min_u32_e32 v4, v14, v1
	v_cmp_gt_i32_e64 s[18:19], s75, v3
	s_nop 1
	v_cndmask_b32_e64 v22, v1, v4, s[18:19]
	ds_read2st64_b64 v[4:7], v0 offset0:20 offset1:21
	v_max_u32_e32 v1, v14, v2
	v_cndmask_b32_e64 v26, v2, v1, s[18:19]
	ds_read2st64_b64 v[0:3], v0 offset0:22 offset1:23
	s_waitcnt lgkmcnt(1)
	v_cmp_lt_i32_e32 vcc, -1, v4
	s_nop 1
	v_cndmask_b32_e32 v28, -1, v123, vcc
	v_xor_b32_e32 v4, v28, v4
	v_min_u32_e32 v28, v4, v22
	v_cmp_lt_i32_e32 vcc, -1, v6
	v_cndmask_b32_e64 v22, v22, v28, s[20:21]
	v_max_u32_e32 v27, v4, v26
	v_cndmask_b32_e32 v28, -1, v123, vcc
	v_cndmask_b32_e64 v26, v26, v27, s[20:21]
	v_add_u32_e32 v27, 0x240, v25
	v_xor_b32_e32 v6, v28, v6
	v_min_u32_e32 v28, v6, v22
	v_cmp_gt_i32_e64 s[22:23], s75, v27
	s_waitcnt lgkmcnt(0)
	v_cmp_lt_i32_e32 vcc, -1, v0
	v_max_u32_e32 v27, v6, v26
	v_cndmask_b32_e64 v22, v22, v28, s[22:23]
	v_cndmask_b32_e32 v28, -1, v123, vcc
	v_cndmask_b32_e64 v26, v26, v27, s[22:23]
	v_add_u32_e32 v27, 0x280, v25
	v_xor_b32_e32 v0, v28, v0
	v_cmp_gt_i32_e64 s[24:25], s75, v27
	v_max_u32_e32 v27, v0, v26
	v_cmp_lt_i32_e32 vcc, -1, v2
	v_cndmask_b32_e64 v26, v26, v27, s[24:25]
	v_min_u32_e32 v28, v0, v22
	v_cndmask_b32_e32 v27, -1, v123, vcc
	v_add_u32_e32 v25, 0x2c0, v25
	v_xor_b32_e32 v2, v27, v2
	v_cndmask_b32_e64 v22, v22, v28, s[24:25]
	v_cmp_gt_i32_e64 s[26:27], s75, v25
	v_max_u32_e32 v25, v2, v26
	v_min_u32_e32 v27, v2, v22
	v_cndmask_b32_e64 v25, v26, v25, s[26:27]
	v_and_b32_e32 v26, 64, v144
	v_cndmask_b32_e64 v22, v22, v27, s[26:27]
	v_add_u32_e32 v26, 64, v26
	s_nop 1
	v_min_u32_dpp v22, v22, v22 row_shr:1 row_mask:0xf bank_mask:0xf
	v_max_u32_dpp v25, v25, v25 row_shr:1 row_mask:0xf bank_mask:0xf
	s_nop 0
	v_min_u32_dpp v22, v22, v22 row_shr:2 row_mask:0xf bank_mask:0xf
	v_max_u32_dpp v25, v25, v25 row_shr:2 row_mask:0xf bank_mask:0xf
	s_nop 0
	v_min_u32_dpp v22, v22, v22 row_shr:4 row_mask:0xf bank_mask:0xf
	v_max_u32_dpp v25, v25, v25 row_shr:4 row_mask:0xf bank_mask:0xf
	s_nop 0
	v_min_u32_dpp v22, v22, v22 row_shr:8 row_mask:0xf bank_mask:0xf
	v_max_u32_dpp v25, v25, v25 row_shr:8 row_mask:0xf bank_mask:0xf
	s_nop 0
	v_readlane_b32 s4, v22, 15
	v_readlane_b32 s5, v22, 31
	s_min_u32 s4, s4, s5
	v_readlane_b32 s5, v22, 47
	s_min_u32 s4, s4, s5
	v_readlane_b32 s5, v22, 63
	s_min_u32 s4, s4, s5
	v_mov_b32_e32 v22, s4
	v_readlane_b32 s4, v25, 15
	v_readlane_b32 s5, v25, 31
	s_max_u32 s4, s4, s5
	v_readlane_b32 s5, v25, 47
	s_max_u32 s4, s4, s5
	v_readlane_b32 s5, v25, 63
	s_max_u32 s4, s4, s5
	v_mov_b32_e32 v25, s4
	v_xor_b32_e32 v25, v22, v25
	s_nop 0
	v_readfirstlane_b32 s5, v25
	s_cmp_lg_u32 s5, 0
	s_flbit_i32_b32 s4, s5
	s_cselect_b64 s[28:29], -1, 0
	s_xor_b32 s4, s4, 31
	s_cmp_eq_u32 s5, 0
	s_cbranch_scc1 .LBB0_716
	v_readfirstlane_b32 s5, v22
	s_lshl_b32 s30, -2, s4
	s_and_b32 s5, s5, s30
	s_cbranch_execnz .LBB0_663

; __device__ __forceinline__ float bf_lo(unsigned v) { return __uint_as_float(v << 16); }
; __device__ __forceinline__ float bf_hi(unsigned v) { return __uint_as_float(v & 0xffff0000u); }
; __device__ __forceinline__ float red8(float v) { v += dpp_f<0xB1>(v); v += dpp_f<0x4E>(v); v += dpp_f<0x141>(v); return v; }
; __device__ __forceinline__ void kv8_qk(const u32x4 (&buf)[8], const f32x2v (&q2)[8], LAS float* srow, int b, int lane) {
;     ...
;     for (int u = 0; u < 8; ++u) {
;         const u32x4 k = buf[u];
;         f32x2v s0 = q2[0] * __builtin_amdgcn_cvt_pk_f32_fp8(k.x, false), s1 = q2[1] * __builtin_amdgcn_cvt_pk_f32_fp8(k.x, true);
;         s0 = __builtin_elementwise_fma(q2[2], __builtin_amdgcn_cvt_pk_f32_fp8(k.y, false), s0); s1 = __builtin_elementwise_fma(q2[3], __builtin_amdgcn_cvt_pk_f32_fp8(k.y, true), s1);
;         s0 = __builtin_elementwise_fma(q2[4], __builtin_amdgcn_cvt_pk_f32_fp8(k.z, false), s0); s1 = __builtin_elementwise_fma(q2[5], __builtin_amdgcn_cvt_pk_f32_fp8(k.z, true), s1);
;         s0 = __builtin_elementwise_fma(q2[6], __builtin_amdgcn_cvt_pk_f32_fp8(k.w, false), s0); s1 = __builtin_elementwise_fma(q2[7], __builtin_amdgcn_cvt_pk_f32_fp8(k.w, true), s1);
;         const f32x2v t = s0 + s1;
;         const float s = red8(t.x + t.y);
;         if ((lane & 7) == 0) srow[b * 8 + u] = s;
;     }
; __device__ __forceinline__ void attn_query8(const unsigned char* __restrict__ KV8, const bf16_t* __restrict__ Z, const int* __restrict__ SEL, bf16_t* __restrict__ YMIX, int t, LAS float* sbuf  ) {
;     ...
;     const int nsel = (t + 1 < 256) ? (t + 1) : 256, nb = (nsel + 7) >> 3;
;     int iv[4];
; #pragma unroll
;     for (int jj = 0; jj < 4; ++jj) { const int e = lane + 64 * jj; iv[jj] = (e < nsel) ? SEL[(size_t)t * 256 + e] : 0; }
;     f32x2v qf[8];
;     { const u32x4* qp = (const u32x4*)(Z + (size_t)t * ZLD + OFF_Q + lane * 16); const u32x4 a = qp[0], b = qp[1];
;       qf[0] = (f32x2v){bf_lo(a.x), bf_hi(a.x)}; qf[1] = (f32x2v){bf_lo(a.y), bf_hi(a.y)}; qf[2] = (f32x2v){bf_lo(a.z), bf_hi(a.z)}; qf[3] = (f32x2v){bf_lo(a.w), bf_hi(a.w)};
;       qf[4] = (f32x2v){bf_lo(b.x), bf_hi(b.x)}; qf[5] = (f32x2v){bf_lo(b.y), bf_hi(b.y)}; qf[6] = (f32x2v){bf_lo(b.z), bf_hi(b.z)}; qf[7] = (f32x2v){bf_lo(b.w), bf_hi(b.w)}; }
.Latt_unit:
	s_min_i32 s4, s80, 0xff
	s_add_i32 s4, s4, 1
	v_sub_u32_e32 v143, s4, v145
	s_waitcnt vmcnt(32)
	v_lshlrev_b32_e32 v182, 16, v244
	v_and_b32_e32 v183, 0xffff0000, v244
	v_lshlrev_b32_e32 v184, 16, v245
	v_and_b32_e32 v185, 0xffff0000, v245
	v_lshlrev_b32_e32 v186, 16, v246
	v_and_b32_e32 v187, 0xffff0000, v246
	v_lshlrev_b32_e32 v188, 16, v247
	v_and_b32_e32 v189, 0xffff0000, v247
	v_lshlrev_b32_e32 v190, 16, v230
	v_and_b32_e32 v191, 0xffff0000, v230
	v_lshlrev_b32_e32 v192, 16, v231
	v_and_b32_e32 v193, 0xffff0000, v231
	v_lshlrev_b32_e32 v194, 16, v232
	v_and_b32_e32 v195, 0xffff0000, v232
	v_lshlrev_b32_e32 v196, 16, v233
	v_and_b32_e32 v197, 0xffff0000, v233
	s_add_i32 s6, s80, 0x100
	s_min_i32 s6, s6, 0x3fff
	s_min_i32 s8, s6, 0xff
	s_add_i32 s8, s8, 1
	s_lshl_b32 s10, s6, 10
	s_add_u32 s10, s1, s10
	s_addc_u32 s11, s73, 0
	v_mov_b32_e32 v240, 0
	v_add_u32_e32 v133, 0, v144
	v_cmp_gt_i32_e32 vcc, s8, v133
	s_and_saveexec_b64 s[12:13], vcc
	global_load_dword v240, v147, s[10:11] offset:0
	s_mov_b64 exec, s[12:13]
	v_mov_b32_e32 v241, 0
	v_add_u32_e32 v133, 64, v144
	v_cmp_gt_i32_e32 vcc, s8, v133
	s_and_saveexec_b64 s[12:13], vcc
	global_load_dword v241, v147, s[10:11] offset:256
	s_mov_b64 exec, s[12:13]
	v_mov_b32_e32 v242, 0
	v_add_u32_e32 v133, 128, v144
	v_cmp_gt_i32_e32 vcc, s8, v133
	s_and_saveexec_b64 s[12:13], vcc
	global_load_dword v242, v147, s[10:11] offset:512
	s_mov_b64 exec, s[12:13]
	v_mov_b32_e32 v243, 0
	v_add_u32_e32 v133, 192, v144
	v_cmp_gt_i32_e32 vcc, s8, v133
	s_and_saveexec_b64 s[12:13], vcc
	global_load_dword v243, v147, s[10:11] offset:768
	s_mov_b64 exec, s[12:13]
	s_mul_i32 s10, s6, 0x2a00
	s_mul_hi_i32 s11, s6, 0x2a00
	s_add_u32 s10, s42, s10
	s_addc_u32 s11, s43, s11
	global_load_dwordx4 v[244:247], v146, s[10:11] offset:2048
	global_load_dwordx4 v[230:233], v146, s[10:11] offset:2064
	s_waitcnt vmcnt(37)
	v_cvt_pk_f32_fp8_e32 v[214:215], v0
	v_cvt_pk_f32_fp8_sdwa v[216:217], v0 src0_sel:WORD_1
	v_pk_mul_f32 v[128:129], v[214:215], v[182:183]
	v_cvt_pk_f32_fp8_e32 v[218:219], v1
	s_nop 0
	v_pk_fma_f32 v[128:129], v[184:185], v[216:217], v[128:129]
	v_cvt_pk_f32_fp8_sdwa v[220:221], v1 src0_sel:WORD_1
	v_pk_fma_f32 v[128:129], v[186:187], v[218:219], v[128:129]
	v_cvt_pk_f32_fp8_e32 v[222:223], v2
	v_pk_fma_f32 v[128:129], v[188:189], v[220:221], v[128:129]
	v_cvt_pk_f32_fp8_sdwa v[224:225], v2 src0_sel:WORD_1
	s_nop 0
	v_pk_fma_f32 v[128:129], v[190:191], v[222:223], v[128:129]
	v_cvt_pk_f32_fp8_e32 v[226:227], v3
	v_pk_fma_f32 v[128:129], v[192:193], v[224:225], v[128:129]
	v_cvt_pk_f32_fp8_sdwa v[228:229], v3 src0_sel:WORD_1
	v_pk_fma_f32 v[128:129], v[194:195], v[226:227], v[128:129]
	v_pk_fma_f32 v[128:129], v[196:197], v[228:229], v[128:129]
	buffer_load_dwordx4 v[0:3], v150, s[16:19], s27 offen sc0
	s_nop 0
	v_add_f32_e32 v132, v128, v129
	s_waitcnt vmcnt(37)
	v_cvt_pk_f32_fp8_e32 v[214:215], v4
	v_cvt_pk_f32_fp8_sdwa v[216:217], v4 src0_sel:WORD_1
	v_pk_mul_f32 v[128:129], v[214:215], v[182:183]
	v_cvt_pk_f32_fp8_e32 v[218:219], v5
	v_add_f32_dpp v132, v132, v132 quad_perm:[1,0,3,2] row_mask:0xf bank_mask:0xf
	v_pk_fma_f32 v[128:129], v[184:185], v[216:217], v[128:129]
	v_cvt_pk_f32_fp8_sdwa v[220:221], v5 src0_sel:WORD_1
	v_pk_fma_f32 v[128:129], v[186:187], v[218:219], v[128:129]
	v_cvt_pk_f32_fp8_e32 v[222:223], v6
	v_pk_fma_f32 v[128:129], v[188:189], v[220:221], v[128:129]
	v_cvt_pk_f32_fp8_sdwa v[224:225], v6 src0_sel:WORD_1
	v_add_f32_dpp v132, v132, v132 quad_perm:[2,3,0,1] row_mask:0xf bank_mask:0xf
	v_pk_fma_f32 v[128:129], v[190:191], v[222:223], v[128:129]
	v_cvt_pk_f32_fp8_e32 v[226:227], v7
	v_pk_fma_f32 v[128:129], v[192:193], v[224:225], v[128:129]
	v_cvt_pk_f32_fp8_sdwa v[228:229], v7 src0_sel:WORD_1
	v_pk_fma_f32 v[128:129], v[194:195], v[226:227], v[128:129]
	v_pk_fma_f32 v[128:129], v[196:197], v[228:229], v[128:129]
	buffer_load_dwordx4 v[4:7], v151, s[16:19], s27 offen sc0
	v_add_f32_dpp v150, v132, v132 row_half_mirror row_mask:0xf bank_mask:0xf
	v_add_f32_e32 v133, v128, v129
	s_waitcnt vmcnt(37)
	v_cvt_pk_f32_fp8_e32 v[214:215], v8
	v_cvt_pk_f32_fp8_sdwa v[216:217], v8 src0_sel:WORD_1
	v_pk_mul_f32 v[128:129], v[214:215], v[182:183]
	v_cvt_pk_f32_fp8_e32 v[218:219], v9
	v_add_f32_dpp v133, v133, v133 quad_perm:[1,0,3,2] row_mask:0xf bank_mask:0xf
	v_pk_fma_f32 v[128:129], v[184:185], v[216:217], v[128:129]
	v_cvt_pk_f32_fp8_sdwa v[220:221], v9 src0_sel:WORD_1
	v_pk_fma_f32 v[128:129], v[186:187], v[218:219], v[128:129]
	v_cvt_pk_f32_fp8_e32 v[222:223], v10
	v_pk_fma_f32 v[128:129], v[188:189], v[220:221], v[128:129]
	v_cvt_pk_f32_fp8_sdwa v[224:225], v10 src0_sel:WORD_1
	v_add_f32_dpp v133, v133, v133 quad_perm:[2,3,0,1] row_mask:0xf bank_mask:0xf
	v_pk_fma_f32 v[128:129], v[190:191], v[222:223], v[128:129]
	v_cvt_pk_f32_fp8_e32 v[226:227], v11
	v_pk_fma_f32 v[128:129], v[192:193], v[224:225], v[128:129]
	v_cvt_pk_f32_fp8_sdwa v[228:229], v11 src0_sel:WORD_1
	v_pk_fma_f32 v[128:129], v[194:195], v[226:227], v[128:129]
	v_pk_fma_f32 v[128:129], v[196:197], v[228:229], v[128:129]
	buffer_load_dwordx4 v[8:11], v152, s[16:19], s27 offen sc0
	v_add_f32_dpp v151, v133, v133 row_half_mirror row_mask:0xf bank_mask:0xf
	v_add_f32_e32 v132, v128, v129
	s_waitcnt vmcnt(37)
; #define LAS __attribute__((address_space(3)))
; __device__ __forceinline__ float red8(float v) { v += dpp_f<0xB1>(v); v += dpp_f<0x4E>(v); v += dpp_f<0x141>(v); return v; }
; __device__ __forceinline__ void kv8_issue(u32x4 (&buf)[8], __amdgpu_buffer_rsrc_t rs, int voff  , int sbase  , const int (&iv)[4], int b) {
;     ...
;     for (int u = 0; u < 8; ++u) { const int si = __builtin_amdgcn_readlane(ivb, l0 + u); buf[u] = __builtin_amdgcn_raw_buffer_load_b128(rs, voff, si * 2048 + sbase, KV8_AUX); }
; }
; __device__ __forceinline__ void kv8_qk(const u32x4 (&buf)[8], const f32x2v (&q2)[8], LAS float* srow, int b, int lane) {
; #pragma unroll
;     for (int u = 0; u < 8; ++u) {
;         const u32x4 k = buf[u];
;         f32x2v s0 = q2[0] * __builtin_amdgcn_cvt_pk_f32_fp8(k.x, false), s1 = q2[1] * __builtin_amdgcn_cvt_pk_f32_fp8(k.x, true);
;         s0 = __builtin_elementwise_fma(q2[2], __builtin_amdgcn_cvt_pk_f32_fp8(k.y, false), s0); s1 = __builtin_elementwise_fma(q2[3], __builtin_amdgcn_cvt_pk_f32_fp8(k.y, true), s1);
;         s0 = __builtin_elementwise_fma(q2[4], __builtin_amdgcn_cvt_pk_f32_fp8(k.z, false), s0); s1 = __builtin_elementwise_fma(q2[5], __builtin_amdgcn_cvt_pk_f32_fp8(k.z, true), s1);
;         s0 = __builtin_elementwise_fma(q2[6], __builtin_amdgcn_cvt_pk_f32_fp8(k.w, false), s0); s1 = __builtin_elementwise_fma(q2[7], __builtin_amdgcn_cvt_pk_f32_fp8(k.w, true), s1);
;         const f32x2v t = s0 + s1;
;         const float s = red8(t.x + t.y);
;         if ((lane & 7) == 0) srow[b * 8 + u] = s;
;     }
	v_cvt_pk_f32_fp8_e32 v[214:215], v12
	v_cvt_pk_f32_fp8_sdwa v[216:217], v12 src0_sel:WORD_1
	v_pk_mul_f32 v[128:129], v[214:215], v[182:183]
	v_cvt_pk_f32_fp8_e32 v[218:219], v13
	v_add_f32_dpp v132, v132, v132 quad_perm:[1,0,3,2] row_mask:0xf bank_mask:0xf
	v_pk_fma_f32 v[128:129], v[184:185], v[216:217], v[128:129]
	v_cvt_pk_f32_fp8_sdwa v[220:221], v13 src0_sel:WORD_1
	v_pk_fma_f32 v[128:129], v[186:187], v[218:219], v[128:129]
	v_cvt_pk_f32_fp8_e32 v[222:223], v14
	v_pk_fma_f32 v[128:129], v[188:189], v[220:221], v[128:129]
	v_cvt_pk_f32_fp8_sdwa v[224:225], v14 src0_sel:WORD_1
	v_add_f32_dpp v132, v132, v132 quad_perm:[2,3,0,1] row_mask:0xf bank_mask:0xf
	v_pk_fma_f32 v[128:129], v[190:191], v[222:223], v[128:129]
	v_cvt_pk_f32_fp8_e32 v[226:227], v15
	v_pk_fma_f32 v[128:129], v[192:193], v[224:225], v[128:129]
	v_cvt_pk_f32_fp8_sdwa v[228:229], v15 src0_sel:WORD_1
	v_pk_fma_f32 v[128:129], v[194:195], v[226:227], v[128:129]
	v_pk_fma_f32 v[128:129], v[196:197], v[228:229], v[128:129]
	buffer_load_dwordx4 v[12:15], v153, s[16:19], s27 offen sc0
	v_add_f32_dpp v152, v132, v132 row_half_mirror row_mask:0xf bank_mask:0xf
	v_add_f32_e32 v133, v128, v129
	s_waitcnt vmcnt(37)
	v_cvt_pk_f32_fp8_e32 v[214:215], v16
	v_cvt_pk_f32_fp8_sdwa v[216:217], v16 src0_sel:WORD_1
	v_pk_mul_f32 v[128:129], v[214:215], v[182:183]
	v_cvt_pk_f32_fp8_e32 v[218:219], v17
	v_add_f32_dpp v133, v133, v133 quad_perm:[1,0,3,2] row_mask:0xf bank_mask:0xf
	v_pk_fma_f32 v[128:129], v[184:185], v[216:217], v[128:129]
	v_cvt_pk_f32_fp8_sdwa v[220:221], v17 src0_sel:WORD_1
	v_pk_fma_f32 v[128:129], v[186:187], v[218:219], v[128:129]
	v_cvt_pk_f32_fp8_e32 v[222:223], v18
	v_pk_fma_f32 v[128:129], v[188:189], v[220:221], v[128:129]
	v_cvt_pk_f32_fp8_sdwa v[224:225], v18 src0_sel:WORD_1
	v_add_f32_dpp v133, v133, v133 quad_perm:[2,3,0,1] row_mask:0xf bank_mask:0xf
	v_pk_fma_f32 v[128:129], v[190:191], v[222:223], v[128:129]
	v_cvt_pk_f32_fp8_e32 v[226:227], v19
	v_pk_fma_f32 v[128:129], v[192:193], v[224:225], v[128:129]
	v_cvt_pk_f32_fp8_sdwa v[228:229], v19 src0_sel:WORD_1
	v_pk_fma_f32 v[128:129], v[194:195], v[226:227], v[128:129]
	v_pk_fma_f32 v[128:129], v[196:197], v[228:229], v[128:129]
	buffer_load_dwordx4 v[16:19], v154, s[16:19], s27 offen sc0
	v_add_f32_dpp v153, v133, v133 row_half_mirror row_mask:0xf bank_mask:0xf
	v_add_f32_e32 v132, v128, v129
	s_waitcnt vmcnt(37)
	v_cvt_pk_f32_fp8_e32 v[214:215], v20
	v_cvt_pk_f32_fp8_sdwa v[216:217], v20 src0_sel:WORD_1
	v_pk_mul_f32 v[128:129], v[214:215], v[182:183]
	v_cvt_pk_f32_fp8_e32 v[218:219], v21
	v_add_f32_dpp v132, v132, v132 quad_perm:[1,0,3,2] row_mask:0xf bank_mask:0xf
	v_pk_fma_f32 v[128:129], v[184:185], v[216:217], v[128:129]
	v_cvt_pk_f32_fp8_sdwa v[220:221], v21 src0_sel:WORD_1
	v_pk_fma_f32 v[128:129], v[186:187], v[218:219], v[128:129]
	v_cvt_pk_f32_fp8_e32 v[222:223], v22
	v_pk_fma_f32 v[128:129], v[188:189], v[220:221], v[128:129]
	v_cvt_pk_f32_fp8_sdwa v[224:225], v22 src0_sel:WORD_1
	v_add_f32_dpp v132, v132, v132 quad_perm:[2,3,0,1] row_mask:0xf bank_mask:0xf
	v_pk_fma_f32 v[128:129], v[190:191], v[222:223], v[128:129]
	v_cvt_pk_f32_fp8_e32 v[226:227], v23
	v_pk_fma_f32 v[128:129], v[192:193], v[224:225], v[128:129]
	v_cvt_pk_f32_fp8_sdwa v[228:229], v23 src0_sel:WORD_1
	v_pk_fma_f32 v[128:129], v[194:195], v[226:227], v[128:129]
	v_pk_fma_f32 v[128:129], v[196:197], v[228:229], v[128:129]
	buffer_load_dwordx4 v[20:23], v155, s[16:19], s27 offen sc0
	v_add_f32_dpp v154, v132, v132 row_half_mirror row_mask:0xf bank_mask:0xf
	v_add_f32_e32 v133, v128, v129
	s_waitcnt vmcnt(37)
	v_cvt_pk_f32_fp8_e32 v[214:215], v24
	v_cvt_pk_f32_fp8_sdwa v[216:217], v24 src0_sel:WORD_1
	v_pk_mul_f32 v[128:129], v[214:215], v[182:183]
	v_cvt_pk_f32_fp8_e32 v[218:219], v25
	v_add_f32_dpp v133, v133, v133 quad_perm:[1,0,3,2] row_mask:0xf bank_mask:0xf
	v_pk_fma_f32 v[128:129], v[184:185], v[216:217], v[128:129]
	v_cvt_pk_f32_fp8_sdwa v[220:221], v25 src0_sel:WORD_1
	v_pk_fma_f32 v[128:129], v[186:187], v[218:219], v[128:129]
	v_cvt_pk_f32_fp8_e32 v[222:223], v26
	v_pk_fma_f32 v[128:129], v[188:189], v[220:221], v[128:129]
	v_cvt_pk_f32_fp8_sdwa v[224:225], v26 src0_sel:WORD_1
	v_add_f32_dpp v133, v133, v133 quad_perm:[2,3,0,1] row_mask:0xf bank_mask:0xf
	v_pk_fma_f32 v[128:129], v[190:191], v[222:223], v[128:129]
	v_cvt_pk_f32_fp8_e32 v[226:227], v27
	v_pk_fma_f32 v[128:129], v[192:193], v[224:225], v[128:129]
	v_cvt_pk_f32_fp8_sdwa v[228:229], v27 src0_sel:WORD_1
	v_pk_fma_f32 v[128:129], v[194:195], v[226:227], v[128:129]
	v_pk_fma_f32 v[128:129], v[196:197], v[228:229], v[128:129]
	buffer_load_dwordx4 v[24:27], v156, s[16:19], s27 offen sc0
	v_add_f32_dpp v155, v133, v133 row_half_mirror row_mask:0xf bank_mask:0xf
	v_add_f32_e32 v132, v128, v129
	s_waitcnt vmcnt(37)
	v_cvt_pk_f32_fp8_e32 v[214:215], v28
	v_cvt_pk_f32_fp8_sdwa v[216:217], v28 src0_sel:WORD_1
	v_pk_mul_f32 v[128:129], v[214:215], v[182:183]
	v_cvt_pk_f32_fp8_e32 v[218:219], v29
	v_add_f32_dpp v132, v132, v132 quad_perm:[1,0,3,2] row_mask:0xf bank_mask:0xf
	v_pk_fma_f32 v[128:129], v[184:185], v[216:217], v[128:129]
	v_cvt_pk_f32_fp8_sdwa v[220:221], v29 src0_sel:WORD_1
	v_pk_fma_f32 v[128:129], v[186:187], v[218:219], v[128:129]
	v_cvt_pk_f32_fp8_e32 v[222:223], v30
	v_pk_fma_f32 v[128:129], v[188:189], v[220:221], v[128:129]
	v_cvt_pk_f32_fp8_sdwa v[224:225], v30 src0_sel:WORD_1
	v_add_f32_dpp v132, v132, v132 quad_perm:[2,3,0,1] row_mask:0xf bank_mask:0xf
	v_pk_fma_f32 v[128:129], v[190:191], v[222:223], v[128:129]
	v_cvt_pk_f32_fp8_e32 v[226:227], v31
	v_pk_fma_f32 v[128:129], v[192:193], v[224:225], v[128:129]
	v_cvt_pk_f32_fp8_sdwa v[228:229], v31 src0_sel:WORD_1
	v_pk_fma_f32 v[128:129], v[194:195], v[226:227], v[128:129]
	v_pk_fma_f32 v[128:129], v[196:197], v[228:229], v[128:129]
	buffer_load_dwordx4 v[28:31], v157, s[16:19], s27 offen sc0
	v_add_f32_dpp v156, v132, v132 row_half_mirror row_mask:0xf bank_mask:0xf
	v_add_f32_e32 v133, v128, v129
	s_waitcnt vmcnt(37)
; #define LAS __attribute__((address_space(3)))
; __device__ __forceinline__ float red8(float v) { v += dpp_f<0xB1>(v); v += dpp_f<0x4E>(v); v += dpp_f<0x141>(v); return v; }
; __device__ __forceinline__ void kv8_issue(u32x4 (&buf)[8], __amdgpu_buffer_rsrc_t rs, int voff  , int sbase  , const int (&iv)[4], int b) {
;     ...
;     for (int u = 0; u < 8; ++u) { const int si = __builtin_amdgcn_readlane(ivb, l0 + u); buf[u] = __builtin_amdgcn_raw_buffer_load_b128(rs, voff, si * 2048 + sbase, KV8_AUX); }
; }
; __device__ __forceinline__ void kv8_qk(const u32x4 (&buf)[8], const f32x2v (&q2)[8], LAS float* srow, int b, int lane) {
; #pragma unroll
;     for (int u = 0; u < 8; ++u) {
;         const u32x4 k = buf[u];
;         f32x2v s0 = q2[0] * __builtin_amdgcn_cvt_pk_f32_fp8(k.x, false), s1 = q2[1] * __builtin_amdgcn_cvt_pk_f32_fp8(k.x, true);
;         s0 = __builtin_elementwise_fma(q2[2], __builtin_amdgcn_cvt_pk_f32_fp8(k.y, false), s0); s1 = __builtin_elementwise_fma(q2[3], __builtin_amdgcn_cvt_pk_f32_fp8(k.y, true), s1);
;         s0 = __builtin_elementwise_fma(q2[4], __builtin_amdgcn_cvt_pk_f32_fp8(k.z, false), s0); s1 = __builtin_elementwise_fma(q2[5], __builtin_amdgcn_cvt_pk_f32_fp8(k.z, true), s1);
;         s0 = __builtin_elementwise_fma(q2[6], __builtin_amdgcn_cvt_pk_f32_fp8(k.w, false), s0); s1 = __builtin_elementwise_fma(q2[7], __builtin_amdgcn_cvt_pk_f32_fp8(k.w, true), s1);
;         const f32x2v t = s0 + s1;
;         const float s = red8(t.x + t.y);
;         if ((lane & 7) == 0) srow[b * 8 + u] = s;
;     }
	v_cvt_pk_f32_fp8_e32 v[214:215], v32
	v_cvt_pk_f32_fp8_sdwa v[216:217], v32 src0_sel:WORD_1
	v_pk_mul_f32 v[128:129], v[214:215], v[182:183]
	v_cvt_pk_f32_fp8_e32 v[218:219], v33
	v_add_f32_dpp v133, v133, v133 quad_perm:[1,0,3,2] row_mask:0xf bank_mask:0xf
	v_pk_fma_f32 v[128:129], v[184:185], v[216:217], v[128:129]
	v_cvt_pk_f32_fp8_sdwa v[220:221], v33 src0_sel:WORD_1
	v_pk_fma_f32 v[128:129], v[186:187], v[218:219], v[128:129]
	v_cvt_pk_f32_fp8_e32 v[222:223], v34
	v_pk_fma_f32 v[128:129], v[188:189], v[220:221], v[128:129]
	v_cvt_pk_f32_fp8_sdwa v[224:225], v34 src0_sel:WORD_1
	v_add_f32_dpp v133, v133, v133 quad_perm:[2,3,0,1] row_mask:0xf bank_mask:0xf
	v_pk_fma_f32 v[128:129], v[190:191], v[222:223], v[128:129]
	v_cvt_pk_f32_fp8_e32 v[226:227], v35
	v_pk_fma_f32 v[128:129], v[192:193], v[224:225], v[128:129]
	v_cvt_pk_f32_fp8_sdwa v[228:229], v35 src0_sel:WORD_1
	v_pk_fma_f32 v[128:129], v[194:195], v[226:227], v[128:129]
	v_pk_fma_f32 v[128:129], v[196:197], v[228:229], v[128:129]
	buffer_load_dwordx4 v[32:35], v158, s[16:19], s27 offen sc0
	v_add_f32_dpp v157, v133, v133 row_half_mirror row_mask:0xf bank_mask:0xf
	v_add_f32_e32 v132, v128, v129
	s_waitcnt vmcnt(37)
	v_cvt_pk_f32_fp8_e32 v[214:215], v36
	v_cvt_pk_f32_fp8_sdwa v[216:217], v36 src0_sel:WORD_1
	v_pk_mul_f32 v[128:129], v[214:215], v[182:183]
	v_cvt_pk_f32_fp8_e32 v[218:219], v37
	v_add_f32_dpp v132, v132, v132 quad_perm:[1,0,3,2] row_mask:0xf bank_mask:0xf
	v_pk_fma_f32 v[128:129], v[184:185], v[216:217], v[128:129]
	v_cvt_pk_f32_fp8_sdwa v[220:221], v37 src0_sel:WORD_1
	v_pk_fma_f32 v[128:129], v[186:187], v[218:219], v[128:129]
	v_cvt_pk_f32_fp8_e32 v[222:223], v38
	v_pk_fma_f32 v[128:129], v[188:189], v[220:221], v[128:129]
	v_cvt_pk_f32_fp8_sdwa v[224:225], v38 src0_sel:WORD_1
	v_add_f32_dpp v132, v132, v132 quad_perm:[2,3,0,1] row_mask:0xf bank_mask:0xf
	v_pk_fma_f32 v[128:129], v[190:191], v[222:223], v[128:129]
	v_cvt_pk_f32_fp8_e32 v[226:227], v39
	v_pk_fma_f32 v[128:129], v[192:193], v[224:225], v[128:129]
	v_cvt_pk_f32_fp8_sdwa v[228:229], v39 src0_sel:WORD_1
	v_pk_fma_f32 v[128:129], v[194:195], v[226:227], v[128:129]
	v_pk_fma_f32 v[128:129], v[196:197], v[228:229], v[128:129]
	buffer_load_dwordx4 v[36:39], v159, s[16:19], s27 offen sc0
	v_add_f32_dpp v158, v132, v132 row_half_mirror row_mask:0xf bank_mask:0xf
	v_add_f32_e32 v133, v128, v129
	s_waitcnt vmcnt(37)
	v_cvt_pk_f32_fp8_e32 v[214:215], v40
	v_cvt_pk_f32_fp8_sdwa v[216:217], v40 src0_sel:WORD_1
	v_pk_mul_f32 v[128:129], v[214:215], v[182:183]
	v_cvt_pk_f32_fp8_e32 v[218:219], v41
	v_add_f32_dpp v133, v133, v133 quad_perm:[1,0,3,2] row_mask:0xf bank_mask:0xf
	v_pk_fma_f32 v[128:129], v[184:185], v[216:217], v[128:129]
	v_cvt_pk_f32_fp8_sdwa v[220:221], v41 src0_sel:WORD_1
	v_pk_fma_f32 v[128:129], v[186:187], v[218:219], v[128:129]
	v_cvt_pk_f32_fp8_e32 v[222:223], v42
	v_pk_fma_f32 v[128:129], v[188:189], v[220:221], v[128:129]
	v_cvt_pk_f32_fp8_sdwa v[224:225], v42 src0_sel:WORD_1
	v_add_f32_dpp v133, v133, v133 quad_perm:[2,3,0,1] row_mask:0xf bank_mask:0xf
	v_pk_fma_f32 v[128:129], v[190:191], v[222:223], v[128:129]
	v_cvt_pk_f32_fp8_e32 v[226:227], v43
	v_pk_fma_f32 v[128:129], v[192:193], v[224:225], v[128:129]
	v_cvt_pk_f32_fp8_sdwa v[228:229], v43 src0_sel:WORD_1
	v_pk_fma_f32 v[128:129], v[194:195], v[226:227], v[128:129]
	v_pk_fma_f32 v[128:129], v[196:197], v[228:229], v[128:129]
	buffer_load_dwordx4 v[40:43], v160, s[16:19], s27 offen sc0
	v_add_f32_dpp v159, v133, v133 row_half_mirror row_mask:0xf bank_mask:0xf
	v_add_f32_e32 v132, v128, v129
	s_waitcnt vmcnt(37)
	v_cvt_pk_f32_fp8_e32 v[214:215], v44
	v_cvt_pk_f32_fp8_sdwa v[216:217], v44 src0_sel:WORD_1
	v_pk_mul_f32 v[128:129], v[214:215], v[182:183]
	v_cvt_pk_f32_fp8_e32 v[218:219], v45
	v_add_f32_dpp v132, v132, v132 quad_perm:[1,0,3,2] row_mask:0xf bank_mask:0xf
	v_pk_fma_f32 v[128:129], v[184:185], v[216:217], v[128:129]
	v_cvt_pk_f32_fp8_sdwa v[220:221], v45 src0_sel:WORD_1
	v_pk_fma_f32 v[128:129], v[186:187], v[218:219], v[128:129]
	v_cvt_pk_f32_fp8_e32 v[222:223], v46
	v_pk_fma_f32 v[128:129], v[188:189], v[220:221], v[128:129]
	v_cvt_pk_f32_fp8_sdwa v[224:225], v46 src0_sel:WORD_1
	v_add_f32_dpp v132, v132, v132 quad_perm:[2,3,0,1] row_mask:0xf bank_mask:0xf
	v_pk_fma_f32 v[128:129], v[190:191], v[222:223], v[128:129]
	v_cvt_pk_f32_fp8_e32 v[226:227], v47
	v_pk_fma_f32 v[128:129], v[192:193], v[224:225], v[128:129]
	v_cvt_pk_f32_fp8_sdwa v[228:229], v47 src0_sel:WORD_1
	v_pk_fma_f32 v[128:129], v[194:195], v[226:227], v[128:129]
	v_pk_fma_f32 v[128:129], v[196:197], v[228:229], v[128:129]
	buffer_load_dwordx4 v[44:47], v161, s[16:19], s27 offen sc0
	v_add_f32_dpp v160, v132, v132 row_half_mirror row_mask:0xf bank_mask:0xf
	v_add_f32_e32 v133, v128, v129
	s_waitcnt vmcnt(37)
	v_cvt_pk_f32_fp8_e32 v[214:215], v48
	v_cvt_pk_f32_fp8_sdwa v[216:217], v48 src0_sel:WORD_1
	v_pk_mul_f32 v[128:129], v[214:215], v[182:183]
	v_cvt_pk_f32_fp8_e32 v[218:219], v49
	v_add_f32_dpp v133, v133, v133 quad_perm:[1,0,3,2] row_mask:0xf bank_mask:0xf
	v_pk_fma_f32 v[128:129], v[184:185], v[216:217], v[128:129]
	v_cvt_pk_f32_fp8_sdwa v[220:221], v49 src0_sel:WORD_1
	v_pk_fma_f32 v[128:129], v[186:187], v[218:219], v[128:129]
	v_cvt_pk_f32_fp8_e32 v[222:223], v50
	v_pk_fma_f32 v[128:129], v[188:189], v[220:221], v[128:129]
	v_cvt_pk_f32_fp8_sdwa v[224:225], v50 src0_sel:WORD_1
	v_add_f32_dpp v133, v133, v133 quad_perm:[2,3,0,1] row_mask:0xf bank_mask:0xf
	v_pk_fma_f32 v[128:129], v[190:191], v[222:223], v[128:129]
	v_cvt_pk_f32_fp8_e32 v[226:227], v51
	v_pk_fma_f32 v[128:129], v[192:193], v[224:225], v[128:129]
	v_cvt_pk_f32_fp8_sdwa v[228:229], v51 src0_sel:WORD_1
	v_pk_fma_f32 v[128:129], v[194:195], v[226:227], v[128:129]
	v_pk_fma_f32 v[128:129], v[196:197], v[228:229], v[128:129]
	buffer_load_dwordx4 v[48:51], v162, s[16:19], s27 offen sc0
	v_add_f32_dpp v161, v133, v133 row_half_mirror row_mask:0xf bank_mask:0xf
	v_add_f32_e32 v132, v128, v129
	s_waitcnt vmcnt(37)
; #define LAS __attribute__((address_space(3)))
; __device__ __forceinline__ float red8(float v) { v += dpp_f<0xB1>(v); v += dpp_f<0x4E>(v); v += dpp_f<0x141>(v); return v; }
; __device__ __forceinline__ void kv8_qk(const u32x4 (&buf)[8], const f32x2v (&q2)[8], LAS float* srow, int b, int lane) {
; #pragma unroll
;     for (int u = 0; u < 8; ++u) {
;         const u32x4 k = buf[u];
;         f32x2v s0 = q2[0] * __builtin_amdgcn_cvt_pk_f32_fp8(k.x, false), s1 = q2[1] * __builtin_amdgcn_cvt_pk_f32_fp8(k.x, true);
;         s0 = __builtin_elementwise_fma(q2[2], __builtin_amdgcn_cvt_pk_f32_fp8(k.y, false), s0); s1 = __builtin_elementwise_fma(q2[3], __builtin_amdgcn_cvt_pk_f32_fp8(k.y, true), s1);
;         s0 = __builtin_elementwise_fma(q2[4], __builtin_amdgcn_cvt_pk_f32_fp8(k.z, false), s0); s1 = __builtin_elementwise_fma(q2[5], __builtin_amdgcn_cvt_pk_f32_fp8(k.z, true), s1);
;         s0 = __builtin_elementwise_fma(q2[6], __builtin_amdgcn_cvt_pk_f32_fp8(k.w, false), s0); s1 = __builtin_elementwise_fma(q2[7], __builtin_amdgcn_cvt_pk_f32_fp8(k.w, true), s1);
;         const f32x2v t = s0 + s1;
;         const float s = red8(t.x + t.y);
;         if ((lane & 7) == 0) srow[b * 8 + u] = s;
;     }
; }
	v_cvt_pk_f32_fp8_e32 v[214:215], v52
	v_cvt_pk_f32_fp8_sdwa v[216:217], v52 src0_sel:WORD_1
	v_pk_mul_f32 v[128:129], v[214:215], v[182:183]
	v_cvt_pk_f32_fp8_e32 v[218:219], v53
	v_add_f32_dpp v132, v132, v132 quad_perm:[1,0,3,2] row_mask:0xf bank_mask:0xf
	v_pk_fma_f32 v[128:129], v[184:185], v[216:217], v[128:129]
	v_cvt_pk_f32_fp8_sdwa v[220:221], v53 src0_sel:WORD_1
	v_pk_fma_f32 v[128:129], v[186:187], v[218:219], v[128:129]
	v_cvt_pk_f32_fp8_e32 v[222:223], v54
	v_pk_fma_f32 v[128:129], v[188:189], v[220:221], v[128:129]
	v_cvt_pk_f32_fp8_sdwa v[224:225], v54 src0_sel:WORD_1
	v_add_f32_dpp v132, v132, v132 quad_perm:[2,3,0,1] row_mask:0xf bank_mask:0xf
	v_pk_fma_f32 v[128:129], v[190:191], v[222:223], v[128:129]
	v_cvt_pk_f32_fp8_e32 v[226:227], v55
	v_pk_fma_f32 v[128:129], v[192:193], v[224:225], v[128:129]
	v_cvt_pk_f32_fp8_sdwa v[228:229], v55 src0_sel:WORD_1
	v_pk_fma_f32 v[128:129], v[194:195], v[226:227], v[128:129]
	v_pk_fma_f32 v[128:129], v[196:197], v[228:229], v[128:129]
	buffer_load_dwordx4 v[52:55], v163, s[16:19], s27 offen sc0
	v_add_f32_dpp v162, v132, v132 row_half_mirror row_mask:0xf bank_mask:0xf
	v_add_f32_e32 v133, v128, v129
	s_waitcnt vmcnt(37)
	v_cvt_pk_f32_fp8_e32 v[214:215], v56
	v_cvt_pk_f32_fp8_sdwa v[216:217], v56 src0_sel:WORD_1
	v_pk_mul_f32 v[128:129], v[214:215], v[182:183]
	v_cvt_pk_f32_fp8_e32 v[218:219], v57
	v_add_f32_dpp v133, v133, v133 quad_perm:[1,0,3,2] row_mask:0xf bank_mask:0xf
	v_pk_fma_f32 v[128:129], v[184:185], v[216:217], v[128:129]
	v_cvt_pk_f32_fp8_sdwa v[220:221], v57 src0_sel:WORD_1
	v_pk_fma_f32 v[128:129], v[186:187], v[218:219], v[128:129]
	v_cvt_pk_f32_fp8_e32 v[222:223], v58
	v_pk_fma_f32 v[128:129], v[188:189], v[220:221], v[128:129]
	v_cvt_pk_f32_fp8_sdwa v[224:225], v58 src0_sel:WORD_1
	v_add_f32_dpp v133, v133, v133 quad_perm:[2,3,0,1] row_mask:0xf bank_mask:0xf
	v_pk_fma_f32 v[128:129], v[190:191], v[222:223], v[128:129]
	v_cvt_pk_f32_fp8_e32 v[226:227], v59
	v_pk_fma_f32 v[128:129], v[192:193], v[224:225], v[128:129]
	v_cvt_pk_f32_fp8_sdwa v[228:229], v59 src0_sel:WORD_1
	v_pk_fma_f32 v[128:129], v[194:195], v[226:227], v[128:129]
	v_pk_fma_f32 v[128:129], v[196:197], v[228:229], v[128:129]
	buffer_load_dwordx4 v[56:59], v164, s[16:19], s27 offen sc0
	v_add_f32_dpp v163, v133, v133 row_half_mirror row_mask:0xf bank_mask:0xf
	v_add_f32_e32 v132, v128, v129
	s_waitcnt vmcnt(37)
	v_cvt_pk_f32_fp8_e32 v[214:215], v60
	v_cvt_pk_f32_fp8_sdwa v[216:217], v60 src0_sel:WORD_1
	v_pk_mul_f32 v[128:129], v[214:215], v[182:183]
	v_cvt_pk_f32_fp8_e32 v[218:219], v61
	v_add_f32_dpp v132, v132, v132 quad_perm:[1,0,3,2] row_mask:0xf bank_mask:0xf
	v_pk_fma_f32 v[128:129], v[184:185], v[216:217], v[128:129]
	v_cvt_pk_f32_fp8_sdwa v[220:221], v61 src0_sel:WORD_1
	v_pk_fma_f32 v[128:129], v[186:187], v[218:219], v[128:129]
	v_cvt_pk_f32_fp8_e32 v[222:223], v62
	v_pk_fma_f32 v[128:129], v[188:189], v[220:221], v[128:129]
	v_cvt_pk_f32_fp8_sdwa v[224:225], v62 src0_sel:WORD_1
	v_add_f32_dpp v132, v132, v132 quad_perm:[2,3,0,1] row_mask:0xf bank_mask:0xf
	v_pk_fma_f32 v[128:129], v[190:191], v[222:223], v[128:129]
	v_cvt_pk_f32_fp8_e32 v[226:227], v63
	v_pk_fma_f32 v[128:129], v[192:193], v[224:225], v[128:129]
	v_cvt_pk_f32_fp8_sdwa v[228:229], v63 src0_sel:WORD_1
	v_pk_fma_f32 v[128:129], v[194:195], v[226:227], v[128:129]
	v_pk_fma_f32 v[128:129], v[196:197], v[228:229], v[128:129]
	buffer_load_dwordx4 v[60:63], v165, s[16:19], s27 offen sc0
	v_add_f32_dpp v164, v132, v132 row_half_mirror row_mask:0xf bank_mask:0xf
	v_add_f32_e32 v133, v128, v129
	s_waitcnt vmcnt(37)
	v_cvt_pk_f32_fp8_e32 v[214:215], v64
	v_cvt_pk_f32_fp8_sdwa v[216:217], v64 src0_sel:WORD_1
	v_pk_mul_f32 v[128:129], v[214:215], v[182:183]
	v_cvt_pk_f32_fp8_e32 v[218:219], v65
	v_add_f32_dpp v133, v133, v133 quad_perm:[1,0,3,2] row_mask:0xf bank_mask:0xf
	v_pk_fma_f32 v[128:129], v[184:185], v[216:217], v[128:129]
	v_cvt_pk_f32_fp8_sdwa v[220:221], v65 src0_sel:WORD_1
	v_pk_fma_f32 v[128:129], v[186:187], v[218:219], v[128:129]
	v_cvt_pk_f32_fp8_e32 v[222:223], v66
	v_pk_fma_f32 v[128:129], v[188:189], v[220:221], v[128:129]
	v_cvt_pk_f32_fp8_sdwa v[224:225], v66 src0_sel:WORD_1
	v_add_f32_dpp v133, v133, v133 quad_perm:[2,3,0,1] row_mask:0xf bank_mask:0xf
	v_pk_fma_f32 v[128:129], v[190:191], v[222:223], v[128:129]
	v_cvt_pk_f32_fp8_e32 v[226:227], v67
	v_pk_fma_f32 v[128:129], v[192:193], v[224:225], v[128:129]
	v_cvt_pk_f32_fp8_sdwa v[228:229], v67 src0_sel:WORD_1
	v_pk_fma_f32 v[128:129], v[194:195], v[226:227], v[128:129]
	v_pk_fma_f32 v[128:129], v[196:197], v[228:229], v[128:129]
	buffer_load_dwordx4 v[64:67], v166, s[16:19], s27 offen sc0
	v_add_f32_dpp v165, v133, v133 row_half_mirror row_mask:0xf bank_mask:0xf
	v_add_f32_e32 v132, v128, v129
	s_waitcnt vmcnt(37)
	v_cvt_pk_f32_fp8_e32 v[214:215], v68
	v_cvt_pk_f32_fp8_sdwa v[216:217], v68 src0_sel:WORD_1
	v_pk_mul_f32 v[128:129], v[214:215], v[182:183]
	v_cvt_pk_f32_fp8_e32 v[218:219], v69
	v_add_f32_dpp v132, v132, v132 quad_perm:[1,0,3,2] row_mask:0xf bank_mask:0xf
	v_pk_fma_f32 v[128:129], v[184:185], v[216:217], v[128:129]
	v_cvt_pk_f32_fp8_sdwa v[220:221], v69 src0_sel:WORD_1
	v_pk_fma_f32 v[128:129], v[186:187], v[218:219], v[128:129]
	v_cvt_pk_f32_fp8_e32 v[222:223], v70
	v_pk_fma_f32 v[128:129], v[188:189], v[220:221], v[128:129]
	v_cvt_pk_f32_fp8_sdwa v[224:225], v70 src0_sel:WORD_1
	v_add_f32_dpp v132, v132, v132 quad_perm:[2,3,0,1] row_mask:0xf bank_mask:0xf
	v_pk_fma_f32 v[128:129], v[190:191], v[222:223], v[128:129]
	v_cvt_pk_f32_fp8_e32 v[226:227], v71
	v_pk_fma_f32 v[128:129], v[192:193], v[224:225], v[128:129]
	v_cvt_pk_f32_fp8_sdwa v[228:229], v71 src0_sel:WORD_1
	v_pk_fma_f32 v[128:129], v[194:195], v[226:227], v[128:129]
	v_pk_fma_f32 v[128:129], v[196:197], v[228:229], v[128:129]
	buffer_load_dwordx4 v[68:71], v167, s[16:19], s27 offen sc0
	v_add_f32_dpp v166, v132, v132 row_half_mirror row_mask:0xf bank_mask:0xf
	v_add_f32_e32 v133, v128, v129
	s_waitcnt vmcnt(37)
; #define LAS __attribute__((address_space(3)))
; __device__ __forceinline__ float red8(float v) { v += dpp_f<0xB1>(v); v += dpp_f<0x4E>(v); v += dpp_f<0x141>(v); return v; }
; __device__ __forceinline__ void kv8_qk(const u32x4 (&buf)[8], const f32x2v (&q2)[8], LAS float* srow, int b, int lane) {
; #pragma unroll
;     for (int u = 0; u < 8; ++u) {
;         const u32x4 k = buf[u];
;         f32x2v s0 = q2[0] * __builtin_amdgcn_cvt_pk_f32_fp8(k.x, false), s1 = q2[1] * __builtin_amdgcn_cvt_pk_f32_fp8(k.x, true);
;         s0 = __builtin_elementwise_fma(q2[2], __builtin_amdgcn_cvt_pk_f32_fp8(k.y, false), s0); s1 = __builtin_elementwise_fma(q2[3], __builtin_amdgcn_cvt_pk_f32_fp8(k.y, true), s1);
;         s0 = __builtin_elementwise_fma(q2[4], __builtin_amdgcn_cvt_pk_f32_fp8(k.z, false), s0); s1 = __builtin_elementwise_fma(q2[5], __builtin_amdgcn_cvt_pk_f32_fp8(k.z, true), s1);
;         s0 = __builtin_elementwise_fma(q2[6], __builtin_amdgcn_cvt_pk_f32_fp8(k.w, false), s0); s1 = __builtin_elementwise_fma(q2[7], __builtin_amdgcn_cvt_pk_f32_fp8(k.w, true), s1);
;         const f32x2v t = s0 + s1;
;         const float s = red8(t.x + t.y);
;         if ((lane & 7) == 0) srow[b * 8 + u] = s;
;     }
; }
	v_cvt_pk_f32_fp8_e32 v[214:215], v72
	v_cvt_pk_f32_fp8_sdwa v[216:217], v72 src0_sel:WORD_1
	v_pk_mul_f32 v[128:129], v[214:215], v[182:183]
	v_cvt_pk_f32_fp8_e32 v[218:219], v73
	v_add_f32_dpp v133, v133, v133 quad_perm:[1,0,3,2] row_mask:0xf bank_mask:0xf
	v_pk_fma_f32 v[128:129], v[184:185], v[216:217], v[128:129]
	v_cvt_pk_f32_fp8_sdwa v[220:221], v73 src0_sel:WORD_1
	v_pk_fma_f32 v[128:129], v[186:187], v[218:219], v[128:129]
	v_cvt_pk_f32_fp8_e32 v[222:223], v74
	v_pk_fma_f32 v[128:129], v[188:189], v[220:221], v[128:129]
	v_cvt_pk_f32_fp8_sdwa v[224:225], v74 src0_sel:WORD_1
	v_add_f32_dpp v133, v133, v133 quad_perm:[2,3,0,1] row_mask:0xf bank_mask:0xf
	v_pk_fma_f32 v[128:129], v[190:191], v[222:223], v[128:129]
	v_cvt_pk_f32_fp8_e32 v[226:227], v75
	v_pk_fma_f32 v[128:129], v[192:193], v[224:225], v[128:129]
	v_cvt_pk_f32_fp8_sdwa v[228:229], v75 src0_sel:WORD_1
	v_pk_fma_f32 v[128:129], v[194:195], v[226:227], v[128:129]
	v_pk_fma_f32 v[128:129], v[196:197], v[228:229], v[128:129]
	buffer_load_dwordx4 v[72:75], v168, s[16:19], s27 offen sc0
	v_add_f32_dpp v167, v133, v133 row_half_mirror row_mask:0xf bank_mask:0xf
	v_add_f32_e32 v132, v128, v129
	s_waitcnt vmcnt(37)
	v_cvt_pk_f32_fp8_e32 v[214:215], v76
	v_cvt_pk_f32_fp8_sdwa v[216:217], v76 src0_sel:WORD_1
	v_pk_mul_f32 v[128:129], v[214:215], v[182:183]
	v_cvt_pk_f32_fp8_e32 v[218:219], v77
	v_add_f32_dpp v132, v132, v132 quad_perm:[1,0,3,2] row_mask:0xf bank_mask:0xf
	v_pk_fma_f32 v[128:129], v[184:185], v[216:217], v[128:129]
	v_cvt_pk_f32_fp8_sdwa v[220:221], v77 src0_sel:WORD_1
	v_pk_fma_f32 v[128:129], v[186:187], v[218:219], v[128:129]
	v_cvt_pk_f32_fp8_e32 v[222:223], v78
	v_pk_fma_f32 v[128:129], v[188:189], v[220:221], v[128:129]
	v_cvt_pk_f32_fp8_sdwa v[224:225], v78 src0_sel:WORD_1
	v_add_f32_dpp v132, v132, v132 quad_perm:[2,3,0,1] row_mask:0xf bank_mask:0xf
	v_pk_fma_f32 v[128:129], v[190:191], v[222:223], v[128:129]
	v_cvt_pk_f32_fp8_e32 v[226:227], v79
	v_pk_fma_f32 v[128:129], v[192:193], v[224:225], v[128:129]
	v_cvt_pk_f32_fp8_sdwa v[228:229], v79 src0_sel:WORD_1
	v_pk_fma_f32 v[128:129], v[194:195], v[226:227], v[128:129]
	v_pk_fma_f32 v[128:129], v[196:197], v[228:229], v[128:129]
	buffer_load_dwordx4 v[76:79], v169, s[16:19], s27 offen sc0
	v_add_f32_dpp v168, v132, v132 row_half_mirror row_mask:0xf bank_mask:0xf
	v_add_f32_e32 v133, v128, v129
	s_waitcnt vmcnt(37)
	v_cvt_pk_f32_fp8_e32 v[214:215], v80
	v_cvt_pk_f32_fp8_sdwa v[216:217], v80 src0_sel:WORD_1
	v_pk_mul_f32 v[128:129], v[214:215], v[182:183]
	v_cvt_pk_f32_fp8_e32 v[218:219], v81
	v_add_f32_dpp v133, v133, v133 quad_perm:[1,0,3,2] row_mask:0xf bank_mask:0xf
	v_pk_fma_f32 v[128:129], v[184:185], v[216:217], v[128:129]
	v_cvt_pk_f32_fp8_sdwa v[220:221], v81 src0_sel:WORD_1
	v_pk_fma_f32 v[128:129], v[186:187], v[218:219], v[128:129]
	v_cvt_pk_f32_fp8_e32 v[222:223], v82
	v_pk_fma_f32 v[128:129], v[188:189], v[220:221], v[128:129]
	v_cvt_pk_f32_fp8_sdwa v[224:225], v82 src0_sel:WORD_1
	v_add_f32_dpp v133, v133, v133 quad_perm:[2,3,0,1] row_mask:0xf bank_mask:0xf
	v_pk_fma_f32 v[128:129], v[190:191], v[222:223], v[128:129]
	v_cvt_pk_f32_fp8_e32 v[226:227], v83
	v_pk_fma_f32 v[128:129], v[192:193], v[224:225], v[128:129]
	v_cvt_pk_f32_fp8_sdwa v[228:229], v83 src0_sel:WORD_1
	v_pk_fma_f32 v[128:129], v[194:195], v[226:227], v[128:129]
	v_pk_fma_f32 v[128:129], v[196:197], v[228:229], v[128:129]
	buffer_load_dwordx4 v[80:83], v170, s[16:19], s27 offen sc0
	v_add_f32_dpp v169, v133, v133 row_half_mirror row_mask:0xf bank_mask:0xf
	v_add_f32_e32 v132, v128, v129
	s_waitcnt vmcnt(37)
	v_cvt_pk_f32_fp8_e32 v[214:215], v84
	v_cvt_pk_f32_fp8_sdwa v[216:217], v84 src0_sel:WORD_1
	v_pk_mul_f32 v[128:129], v[214:215], v[182:183]
	v_cvt_pk_f32_fp8_e32 v[218:219], v85
	v_add_f32_dpp v132, v132, v132 quad_perm:[1,0,3,2] row_mask:0xf bank_mask:0xf
	v_pk_fma_f32 v[128:129], v[184:185], v[216:217], v[128:129]
	v_cvt_pk_f32_fp8_sdwa v[220:221], v85 src0_sel:WORD_1
	v_pk_fma_f32 v[128:129], v[186:187], v[218:219], v[128:129]
	v_cvt_pk_f32_fp8_e32 v[222:223], v86
	v_pk_fma_f32 v[128:129], v[188:189], v[220:221], v[128:129]
	v_cvt_pk_f32_fp8_sdwa v[224:225], v86 src0_sel:WORD_1
	v_add_f32_dpp v132, v132, v132 quad_perm:[2,3,0,1] row_mask:0xf bank_mask:0xf
	v_pk_fma_f32 v[128:129], v[190:191], v[222:223], v[128:129]
	v_cvt_pk_f32_fp8_e32 v[226:227], v87
	v_pk_fma_f32 v[128:129], v[192:193], v[224:225], v[128:129]
	v_cvt_pk_f32_fp8_sdwa v[228:229], v87 src0_sel:WORD_1
	v_pk_fma_f32 v[128:129], v[194:195], v[226:227], v[128:129]
	v_pk_fma_f32 v[128:129], v[196:197], v[228:229], v[128:129]
	buffer_load_dwordx4 v[84:87], v171, s[16:19], s27 offen sc0
	v_add_f32_dpp v170, v132, v132 row_half_mirror row_mask:0xf bank_mask:0xf
	v_add_f32_e32 v133, v128, v129
	s_waitcnt vmcnt(37)
	v_cvt_pk_f32_fp8_e32 v[214:215], v88
	v_cvt_pk_f32_fp8_sdwa v[216:217], v88 src0_sel:WORD_1
	v_pk_mul_f32 v[128:129], v[214:215], v[182:183]
	v_cvt_pk_f32_fp8_e32 v[218:219], v89
	v_add_f32_dpp v133, v133, v133 quad_perm:[1,0,3,2] row_mask:0xf bank_mask:0xf
	v_pk_fma_f32 v[128:129], v[184:185], v[216:217], v[128:129]
	v_cvt_pk_f32_fp8_sdwa v[220:221], v89 src0_sel:WORD_1
	v_pk_fma_f32 v[128:129], v[186:187], v[218:219], v[128:129]
	v_cvt_pk_f32_fp8_e32 v[222:223], v90
	v_pk_fma_f32 v[128:129], v[188:189], v[220:221], v[128:129]
	v_cvt_pk_f32_fp8_sdwa v[224:225], v90 src0_sel:WORD_1
	v_add_f32_dpp v133, v133, v133 quad_perm:[2,3,0,1] row_mask:0xf bank_mask:0xf
	v_pk_fma_f32 v[128:129], v[190:191], v[222:223], v[128:129]
	v_cvt_pk_f32_fp8_e32 v[226:227], v91
	v_pk_fma_f32 v[128:129], v[192:193], v[224:225], v[128:129]
	v_cvt_pk_f32_fp8_sdwa v[228:229], v91 src0_sel:WORD_1
	v_pk_fma_f32 v[128:129], v[194:195], v[226:227], v[128:129]
	v_pk_fma_f32 v[128:129], v[196:197], v[228:229], v[128:129]
	buffer_load_dwordx4 v[88:91], v172, s[16:19], s27 offen sc0
	v_add_f32_dpp v171, v133, v133 row_half_mirror row_mask:0xf bank_mask:0xf
	v_add_f32_e32 v132, v128, v129
	s_waitcnt vmcnt(37)
; #define LAS __attribute__((address_space(3)))
; __device__ __forceinline__ float red8(float v) { v += dpp_f<0xB1>(v); v += dpp_f<0x4E>(v); v += dpp_f<0x141>(v); return v; }
; __device__ __forceinline__ void kv8_qk(const u32x4 (&buf)[8], const f32x2v (&q2)[8], LAS float* srow, int b, int lane) {
; #pragma unroll
;     for (int u = 0; u < 8; ++u) {
;         const u32x4 k = buf[u];
;         f32x2v s0 = q2[0] * __builtin_amdgcn_cvt_pk_f32_fp8(k.x, false), s1 = q2[1] * __builtin_amdgcn_cvt_pk_f32_fp8(k.x, true);
;         s0 = __builtin_elementwise_fma(q2[2], __builtin_amdgcn_cvt_pk_f32_fp8(k.y, false), s0); s1 = __builtin_elementwise_fma(q2[3], __builtin_amdgcn_cvt_pk_f32_fp8(k.y, true), s1);
;         s0 = __builtin_elementwise_fma(q2[4], __builtin_amdgcn_cvt_pk_f32_fp8(k.z, false), s0); s1 = __builtin_elementwise_fma(q2[5], __builtin_amdgcn_cvt_pk_f32_fp8(k.z, true), s1);
;         s0 = __builtin_elementwise_fma(q2[6], __builtin_amdgcn_cvt_pk_f32_fp8(k.w, false), s0); s1 = __builtin_elementwise_fma(q2[7], __builtin_amdgcn_cvt_pk_f32_fp8(k.w, true), s1);
;         const f32x2v t = s0 + s1;
;         const float s = red8(t.x + t.y);
;         if ((lane & 7) == 0) srow[b * 8 + u] = s;
;     }
; }
	v_cvt_pk_f32_fp8_e32 v[214:215], v92
	v_cvt_pk_f32_fp8_sdwa v[216:217], v92 src0_sel:WORD_1
	v_pk_mul_f32 v[128:129], v[214:215], v[182:183]
	v_cvt_pk_f32_fp8_e32 v[218:219], v93
	v_add_f32_dpp v132, v132, v132 quad_perm:[1,0,3,2] row_mask:0xf bank_mask:0xf
	v_pk_fma_f32 v[128:129], v[184:185], v[216:217], v[128:129]
	v_cvt_pk_f32_fp8_sdwa v[220:221], v93 src0_sel:WORD_1
	v_pk_fma_f32 v[128:129], v[186:187], v[218:219], v[128:129]
	v_cvt_pk_f32_fp8_e32 v[222:223], v94
	v_pk_fma_f32 v[128:129], v[188:189], v[220:221], v[128:129]
	v_cvt_pk_f32_fp8_sdwa v[224:225], v94 src0_sel:WORD_1
	v_add_f32_dpp v132, v132, v132 quad_perm:[2,3,0,1] row_mask:0xf bank_mask:0xf
	v_pk_fma_f32 v[128:129], v[190:191], v[222:223], v[128:129]
	v_cvt_pk_f32_fp8_e32 v[226:227], v95
	v_pk_fma_f32 v[128:129], v[192:193], v[224:225], v[128:129]
	v_cvt_pk_f32_fp8_sdwa v[228:229], v95 src0_sel:WORD_1
	v_pk_fma_f32 v[128:129], v[194:195], v[226:227], v[128:129]
	v_pk_fma_f32 v[128:129], v[196:197], v[228:229], v[128:129]
	buffer_load_dwordx4 v[92:95], v173, s[16:19], s27 offen sc0
	v_add_f32_dpp v172, v132, v132 row_half_mirror row_mask:0xf bank_mask:0xf
	v_add_f32_e32 v133, v128, v129
	s_waitcnt vmcnt(37)
	v_cvt_pk_f32_fp8_e32 v[214:215], v96
	v_cvt_pk_f32_fp8_sdwa v[216:217], v96 src0_sel:WORD_1
	v_pk_mul_f32 v[128:129], v[214:215], v[182:183]
	v_cvt_pk_f32_fp8_e32 v[218:219], v97
	v_add_f32_dpp v133, v133, v133 quad_perm:[1,0,3,2] row_mask:0xf bank_mask:0xf
	v_pk_fma_f32 v[128:129], v[184:185], v[216:217], v[128:129]
	v_cvt_pk_f32_fp8_sdwa v[220:221], v97 src0_sel:WORD_1
	v_pk_fma_f32 v[128:129], v[186:187], v[218:219], v[128:129]
	v_cvt_pk_f32_fp8_e32 v[222:223], v98
	v_pk_fma_f32 v[128:129], v[188:189], v[220:221], v[128:129]
	v_cvt_pk_f32_fp8_sdwa v[224:225], v98 src0_sel:WORD_1
	v_add_f32_dpp v133, v133, v133 quad_perm:[2,3,0,1] row_mask:0xf bank_mask:0xf
	v_pk_fma_f32 v[128:129], v[190:191], v[222:223], v[128:129]
	v_cvt_pk_f32_fp8_e32 v[226:227], v99
	v_pk_fma_f32 v[128:129], v[192:193], v[224:225], v[128:129]
	v_cvt_pk_f32_fp8_sdwa v[228:229], v99 src0_sel:WORD_1
	v_pk_fma_f32 v[128:129], v[194:195], v[226:227], v[128:129]
	v_pk_fma_f32 v[128:129], v[196:197], v[228:229], v[128:129]
	buffer_load_dwordx4 v[96:99], v174, s[16:19], s27 offen sc0
	v_add_f32_dpp v173, v133, v133 row_half_mirror row_mask:0xf bank_mask:0xf
	v_add_f32_e32 v132, v128, v129
	s_waitcnt vmcnt(37)
	v_cvt_pk_f32_fp8_e32 v[214:215], v100
	v_cvt_pk_f32_fp8_sdwa v[216:217], v100 src0_sel:WORD_1
	v_pk_mul_f32 v[128:129], v[214:215], v[182:183]
	v_cvt_pk_f32_fp8_e32 v[218:219], v101
	v_add_f32_dpp v132, v132, v132 quad_perm:[1,0,3,2] row_mask:0xf bank_mask:0xf
	v_pk_fma_f32 v[128:129], v[184:185], v[216:217], v[128:129]
	v_cvt_pk_f32_fp8_sdwa v[220:221], v101 src0_sel:WORD_1
	v_pk_fma_f32 v[128:129], v[186:187], v[218:219], v[128:129]
	v_cvt_pk_f32_fp8_e32 v[222:223], v102
	v_pk_fma_f32 v[128:129], v[188:189], v[220:221], v[128:129]
	v_cvt_pk_f32_fp8_sdwa v[224:225], v102 src0_sel:WORD_1
	v_add_f32_dpp v132, v132, v132 quad_perm:[2,3,0,1] row_mask:0xf bank_mask:0xf
	v_pk_fma_f32 v[128:129], v[190:191], v[222:223], v[128:129]
	v_cvt_pk_f32_fp8_e32 v[226:227], v103
	v_pk_fma_f32 v[128:129], v[192:193], v[224:225], v[128:129]
	v_cvt_pk_f32_fp8_sdwa v[228:229], v103 src0_sel:WORD_1
	v_pk_fma_f32 v[128:129], v[194:195], v[226:227], v[128:129]
	v_pk_fma_f32 v[128:129], v[196:197], v[228:229], v[128:129]
	buffer_load_dwordx4 v[100:103], v175, s[16:19], s27 offen sc0
	v_add_f32_dpp v174, v132, v132 row_half_mirror row_mask:0xf bank_mask:0xf
	v_add_f32_e32 v133, v128, v129
	s_waitcnt vmcnt(37)
	v_cvt_pk_f32_fp8_e32 v[214:215], v104
	v_cvt_pk_f32_fp8_sdwa v[216:217], v104 src0_sel:WORD_1
	v_pk_mul_f32 v[128:129], v[214:215], v[182:183]
	v_cvt_pk_f32_fp8_e32 v[218:219], v105
	v_add_f32_dpp v133, v133, v133 quad_perm:[1,0,3,2] row_mask:0xf bank_mask:0xf
	v_pk_fma_f32 v[128:129], v[184:185], v[216:217], v[128:129]
	v_cvt_pk_f32_fp8_sdwa v[220:221], v105 src0_sel:WORD_1
	v_pk_fma_f32 v[128:129], v[186:187], v[218:219], v[128:129]
	v_cvt_pk_f32_fp8_e32 v[222:223], v106
	v_pk_fma_f32 v[128:129], v[188:189], v[220:221], v[128:129]
	v_cvt_pk_f32_fp8_sdwa v[224:225], v106 src0_sel:WORD_1
	v_add_f32_dpp v133, v133, v133 quad_perm:[2,3,0,1] row_mask:0xf bank_mask:0xf
	v_pk_fma_f32 v[128:129], v[190:191], v[222:223], v[128:129]
	v_cvt_pk_f32_fp8_e32 v[226:227], v107
	v_pk_fma_f32 v[128:129], v[192:193], v[224:225], v[128:129]
	v_cvt_pk_f32_fp8_sdwa v[228:229], v107 src0_sel:WORD_1
	v_pk_fma_f32 v[128:129], v[194:195], v[226:227], v[128:129]
	v_pk_fma_f32 v[128:129], v[196:197], v[228:229], v[128:129]
	buffer_load_dwordx4 v[104:107], v176, s[16:19], s27 offen sc0
	v_add_f32_dpp v175, v133, v133 row_half_mirror row_mask:0xf bank_mask:0xf
	v_add_f32_e32 v132, v128, v129
	s_waitcnt vmcnt(37)
	v_cvt_pk_f32_fp8_e32 v[214:215], v108
	v_cvt_pk_f32_fp8_sdwa v[216:217], v108 src0_sel:WORD_1
	v_pk_mul_f32 v[128:129], v[214:215], v[182:183]
	v_cvt_pk_f32_fp8_e32 v[218:219], v109
	v_add_f32_dpp v132, v132, v132 quad_perm:[1,0,3,2] row_mask:0xf bank_mask:0xf
	v_pk_fma_f32 v[128:129], v[184:185], v[216:217], v[128:129]
	v_cvt_pk_f32_fp8_sdwa v[220:221], v109 src0_sel:WORD_1
	v_pk_fma_f32 v[128:129], v[186:187], v[218:219], v[128:129]
	v_cvt_pk_f32_fp8_e32 v[222:223], v110
	v_pk_fma_f32 v[128:129], v[188:189], v[220:221], v[128:129]
	v_cvt_pk_f32_fp8_sdwa v[224:225], v110 src0_sel:WORD_1
	v_add_f32_dpp v132, v132, v132 quad_perm:[2,3,0,1] row_mask:0xf bank_mask:0xf
	v_pk_fma_f32 v[128:129], v[190:191], v[222:223], v[128:129]
	v_cvt_pk_f32_fp8_e32 v[226:227], v111
	v_pk_fma_f32 v[128:129], v[192:193], v[224:225], v[128:129]
	v_cvt_pk_f32_fp8_sdwa v[228:229], v111 src0_sel:WORD_1
	v_pk_fma_f32 v[128:129], v[194:195], v[226:227], v[128:129]
	v_pk_fma_f32 v[128:129], v[196:197], v[228:229], v[128:129]
	buffer_load_dwordx4 v[108:111], v177, s[16:19], s27 offen sc0
	v_add_f32_dpp v176, v132, v132 row_half_mirror row_mask:0xf bank_mask:0xf
	v_add_f32_e32 v133, v128, v129
	s_waitcnt vmcnt(37)
; #define LAS __attribute__((address_space(3)))
; __device__ __forceinline__ float red8(float v) { v += dpp_f<0xB1>(v); v += dpp_f<0x4E>(v); v += dpp_f<0x141>(v); return v; }
; __device__ __forceinline__ void kv8_qk(const u32x4 (&buf)[8], const f32x2v (&q2)[8], LAS float* srow, int b, int lane) {
; #pragma unroll
;     for (int u = 0; u < 8; ++u) {
;         const u32x4 k = buf[u];
;         f32x2v s0 = q2[0] * __builtin_amdgcn_cvt_pk_f32_fp8(k.x, false), s1 = q2[1] * __builtin_amdgcn_cvt_pk_f32_fp8(k.x, true);
;         s0 = __builtin_elementwise_fma(q2[2], __builtin_amdgcn_cvt_pk_f32_fp8(k.y, false), s0); s1 = __builtin_elementwise_fma(q2[3], __builtin_amdgcn_cvt_pk_f32_fp8(k.y, true), s1);
;         s0 = __builtin_elementwise_fma(q2[4], __builtin_amdgcn_cvt_pk_f32_fp8(k.z, false), s0); s1 = __builtin_elementwise_fma(q2[5], __builtin_amdgcn_cvt_pk_f32_fp8(k.z, true), s1);
;         s0 = __builtin_elementwise_fma(q2[6], __builtin_amdgcn_cvt_pk_f32_fp8(k.w, false), s0); s1 = __builtin_elementwise_fma(q2[7], __builtin_amdgcn_cvt_pk_f32_fp8(k.w, true), s1);
;         const f32x2v t = s0 + s1;
;         const float s = red8(t.x + t.y);
;         if ((lane & 7) == 0) srow[b * 8 + u] = s;
;     }
; }
	v_cvt_pk_f32_fp8_e32 v[214:215], v112
	v_cvt_pk_f32_fp8_sdwa v[216:217], v112 src0_sel:WORD_1
	v_pk_mul_f32 v[128:129], v[214:215], v[182:183]
	v_cvt_pk_f32_fp8_e32 v[218:219], v113
	v_add_f32_dpp v133, v133, v133 quad_perm:[1,0,3,2] row_mask:0xf bank_mask:0xf
	v_pk_fma_f32 v[128:129], v[184:185], v[216:217], v[128:129]
	v_cvt_pk_f32_fp8_sdwa v[220:221], v113 src0_sel:WORD_1
	v_pk_fma_f32 v[128:129], v[186:187], v[218:219], v[128:129]
	v_cvt_pk_f32_fp8_e32 v[222:223], v114
	v_pk_fma_f32 v[128:129], v[188:189], v[220:221], v[128:129]
	v_cvt_pk_f32_fp8_sdwa v[224:225], v114 src0_sel:WORD_1
	v_add_f32_dpp v133, v133, v133 quad_perm:[2,3,0,1] row_mask:0xf bank_mask:0xf
	v_pk_fma_f32 v[128:129], v[190:191], v[222:223], v[128:129]
	v_cvt_pk_f32_fp8_e32 v[226:227], v115
	v_pk_fma_f32 v[128:129], v[192:193], v[224:225], v[128:129]
	v_cvt_pk_f32_fp8_sdwa v[228:229], v115 src0_sel:WORD_1
	v_pk_fma_f32 v[128:129], v[194:195], v[226:227], v[128:129]
	v_pk_fma_f32 v[128:129], v[196:197], v[228:229], v[128:129]
	buffer_load_dwordx4 v[112:115], v178, s[16:19], s27 offen sc0
	v_add_f32_dpp v177, v133, v133 row_half_mirror row_mask:0xf bank_mask:0xf
	v_add_f32_e32 v132, v128, v129
	s_waitcnt vmcnt(37)
	v_cvt_pk_f32_fp8_e32 v[214:215], v116
	v_cvt_pk_f32_fp8_sdwa v[216:217], v116 src0_sel:WORD_1
	v_pk_mul_f32 v[128:129], v[214:215], v[182:183]
	v_cvt_pk_f32_fp8_e32 v[218:219], v117
	v_add_f32_dpp v132, v132, v132 quad_perm:[1,0,3,2] row_mask:0xf bank_mask:0xf
	v_pk_fma_f32 v[128:129], v[184:185], v[216:217], v[128:129]
	v_cvt_pk_f32_fp8_sdwa v[220:221], v117 src0_sel:WORD_1
	v_pk_fma_f32 v[128:129], v[186:187], v[218:219], v[128:129]
	v_cvt_pk_f32_fp8_e32 v[222:223], v118
	v_pk_fma_f32 v[128:129], v[188:189], v[220:221], v[128:129]
	v_cvt_pk_f32_fp8_sdwa v[224:225], v118 src0_sel:WORD_1
	v_add_f32_dpp v132, v132, v132 quad_perm:[2,3,0,1] row_mask:0xf bank_mask:0xf
	v_pk_fma_f32 v[128:129], v[190:191], v[222:223], v[128:129]
	v_cvt_pk_f32_fp8_e32 v[226:227], v119
	v_pk_fma_f32 v[128:129], v[192:193], v[224:225], v[128:129]
	v_cvt_pk_f32_fp8_sdwa v[228:229], v119 src0_sel:WORD_1
	v_pk_fma_f32 v[128:129], v[194:195], v[226:227], v[128:129]
	v_pk_fma_f32 v[128:129], v[196:197], v[228:229], v[128:129]
	buffer_load_dwordx4 v[116:119], v179, s[16:19], s27 offen sc0
	v_add_f32_dpp v178, v132, v132 row_half_mirror row_mask:0xf bank_mask:0xf
	v_add_f32_e32 v133, v128, v129
	s_waitcnt vmcnt(37)
	v_cvt_pk_f32_fp8_e32 v[214:215], v120
	v_cvt_pk_f32_fp8_sdwa v[216:217], v120 src0_sel:WORD_1
	v_pk_mul_f32 v[128:129], v[214:215], v[182:183]
	v_cvt_pk_f32_fp8_e32 v[218:219], v121
	v_add_f32_dpp v133, v133, v133 quad_perm:[1,0,3,2] row_mask:0xf bank_mask:0xf
	v_pk_fma_f32 v[128:129], v[184:185], v[216:217], v[128:129]
	v_cvt_pk_f32_fp8_sdwa v[220:221], v121 src0_sel:WORD_1
	v_pk_fma_f32 v[128:129], v[186:187], v[218:219], v[128:129]
	v_cvt_pk_f32_fp8_e32 v[222:223], v122
	v_pk_fma_f32 v[128:129], v[188:189], v[220:221], v[128:129]
	v_cvt_pk_f32_fp8_sdwa v[224:225], v122 src0_sel:WORD_1
	v_add_f32_dpp v133, v133, v133 quad_perm:[2,3,0,1] row_mask:0xf bank_mask:0xf
	v_pk_fma_f32 v[128:129], v[190:191], v[222:223], v[128:129]
	v_cvt_pk_f32_fp8_e32 v[226:227], v123
	v_pk_fma_f32 v[128:129], v[192:193], v[224:225], v[128:129]
	v_cvt_pk_f32_fp8_sdwa v[228:229], v123 src0_sel:WORD_1
	v_pk_fma_f32 v[128:129], v[194:195], v[226:227], v[128:129]
	v_pk_fma_f32 v[128:129], v[196:197], v[228:229], v[128:129]
	buffer_load_dwordx4 v[120:123], v180, s[16:19], s27 offen sc0
	v_add_f32_dpp v179, v133, v133 row_half_mirror row_mask:0xf bank_mask:0xf
	v_add_f32_e32 v132, v128, v129
	s_waitcnt vmcnt(37)
	v_cvt_pk_f32_fp8_e32 v[214:215], v124
	v_cvt_pk_f32_fp8_sdwa v[216:217], v124 src0_sel:WORD_1
	v_pk_mul_f32 v[128:129], v[214:215], v[182:183]
	v_cvt_pk_f32_fp8_e32 v[218:219], v125
	v_add_f32_dpp v132, v132, v132 quad_perm:[1,0,3,2] row_mask:0xf bank_mask:0xf
	v_pk_fma_f32 v[128:129], v[184:185], v[216:217], v[128:129]
	v_cvt_pk_f32_fp8_sdwa v[220:221], v125 src0_sel:WORD_1
	v_pk_fma_f32 v[128:129], v[186:187], v[218:219], v[128:129]
	v_cvt_pk_f32_fp8_e32 v[222:223], v126
	v_pk_fma_f32 v[128:129], v[188:189], v[220:221], v[128:129]
	v_cvt_pk_f32_fp8_sdwa v[224:225], v126 src0_sel:WORD_1
	v_add_f32_dpp v132, v132, v132 quad_perm:[2,3,0,1] row_mask:0xf bank_mask:0xf
	v_pk_fma_f32 v[128:129], v[190:191], v[222:223], v[128:129]
	v_cvt_pk_f32_fp8_e32 v[226:227], v127
	v_pk_fma_f32 v[128:129], v[192:193], v[224:225], v[128:129]
	v_cvt_pk_f32_fp8_sdwa v[228:229], v127 src0_sel:WORD_1
	v_pk_fma_f32 v[128:129], v[194:195], v[226:227], v[128:129]
	v_pk_fma_f32 v[128:129], v[196:197], v[228:229], v[128:129]
	buffer_load_dwordx4 v[124:127], v181, s[16:19], s27 offen sc0
	v_add_f32_dpp v180, v132, v132 row_half_mirror row_mask:0xf bank_mask:0xf
	v_add_f32_e32 v133, v128, v129
	s_nop 1
	v_add_f32_dpp v133, v133, v133 quad_perm:[1,0,3,2] row_mask:0xf bank_mask:0xf
	s_nop 1
	v_add_f32_dpp v133, v133, v133 quad_perm:[2,3,0,1] row_mask:0xf bank_mask:0xf
	s_nop 1
	v_add_f32_dpp v181, v133, v133 row_half_mirror row_mask:0xf bank_mask:0xf
	s_cmpk_eq_i32 s4, 0x100
	s_cbranch_scc1 .Latt_nomask
; __device__ __forceinline__ void attn_query8(const unsigned char* __restrict__ KV8, const bf16_t* __restrict__ Z, const int* __restrict__ SEL, bf16_t* __restrict__ YMIX, int t, LAS float* sbuf  ) {
;     ...
;     for (int h = 0; h < 8; ++h) {
;         float sv[4]; float mx = -__builtin_inff();
; #pragma unroll
;         for (int jj = 0; jj < 4; ++jj) { const int j = lane + 64 * jj; const float s = sbuf[h * 256 + j]; sv[jj] = (j < nsel) ? s : -__builtin_inff(); mx = fmaxf(mx, sv[jj]); }
;         mx = wave_max(mx); float sm = 0.f;
; #pragma unroll
;         for (int jj = 0; jj < 4; ++jj) { const int j = lane + 64 * jj; sv[jj] = (j < nsel) ? __expf(sv[jj] - mx) : 0.f; sm += sv[jj]; }
;         sm = wave_sum(sm); const float inv = 1.f / sm;
; #pragma unroll
;         for (int jj = 0; jj < 4; ++jj) sbuf[h * 256 + lane + 64 * jj] = sv[jj] * inv;
;     }
	v_cmp_lt_i32_e32 vcc, 0, v143
	s_nop 1
	v_cndmask_b32_e32 v150, v142, v150, vcc
	v_cmp_lt_i32_e32 vcc, 8, v143
	s_nop 1
	v_cndmask_b32_e32 v151, v142, v151, vcc
	v_cmp_lt_i32_e32 vcc, 16, v143
	s_nop 1
	v_cndmask_b32_e32 v152, v142, v152, vcc
	v_cmp_lt_i32_e32 vcc, 24, v143
	s_nop 1
	v_cndmask_b32_e32 v153, v142, v153, vcc
	v_cmp_lt_i32_e32 vcc, 32, v143
	s_nop 1
	v_cndmask_b32_e32 v154, v142, v154, vcc
	v_cmp_lt_i32_e32 vcc, 40, v143
	s_nop 1
	v_cndmask_b32_e32 v155, v142, v155, vcc
	v_cmp_lt_i32_e32 vcc, 48, v143
	s_nop 1
	v_cndmask_b32_e32 v156, v142, v156, vcc
	v_cmp_lt_i32_e32 vcc, 56, v143
	s_nop 1
	v_cndmask_b32_e32 v157, v142, v157, vcc
	v_cmp_lt_i32_e32 vcc, 64, v143
	s_nop 1
	v_cndmask_b32_e32 v158, v142, v158, vcc
	v_cmp_lt_i32_e32 vcc, 0x48, v143
	s_nop 1
	v_cndmask_b32_e32 v159, v142, v159, vcc
	v_cmp_lt_i32_e32 vcc, 0x50, v143
	s_nop 1
	v_cndmask_b32_e32 v160, v142, v160, vcc
	v_cmp_lt_i32_e32 vcc, 0x58, v143
	s_nop 1
	v_cndmask_b32_e32 v161, v142, v161, vcc
	v_cmp_lt_i32_e32 vcc, 0x60, v143
	s_nop 1
	v_cndmask_b32_e32 v162, v142, v162, vcc
	v_cmp_lt_i32_e32 vcc, 0x68, v143
	s_nop 1
	v_cndmask_b32_e32 v163, v142, v163, vcc
	v_cmp_lt_i32_e32 vcc, 0x70, v143
	s_nop 1
	v_cndmask_b32_e32 v164, v142, v164, vcc
	v_cmp_lt_i32_e32 vcc, 0x78, v143
	s_nop 1
	v_cndmask_b32_e32 v165, v142, v165, vcc
	v_cmp_lt_i32_e32 vcc, 0x80, v143
	s_nop 1
	v_cndmask_b32_e32 v166, v142, v166, vcc
	v_cmp_lt_i32_e32 vcc, 0x88, v143
	s_nop 1
	v_cndmask_b32_e32 v167, v142, v167, vcc
	v_cmp_lt_i32_e32 vcc, 0x90, v143
	s_nop 1
	v_cndmask_b32_e32 v168, v142, v168, vcc
	v_cmp_lt_i32_e32 vcc, 0x98, v143
	s_nop 1
	v_cndmask_b32_e32 v169, v142, v169, vcc
	v_cmp_lt_i32_e32 vcc, 0xa0, v143
	s_nop 1
	v_cndmask_b32_e32 v170, v142, v170, vcc
	v_cmp_lt_i32_e32 vcc, 0xa8, v143
	s_nop 1
	v_cndmask_b32_e32 v171, v142, v171, vcc
	v_cmp_lt_i32_e32 vcc, 0xb0, v143
	s_nop 1
	v_cndmask_b32_e32 v172, v142, v172, vcc
	v_cmp_lt_i32_e32 vcc, 0xb8, v143
	s_nop 1
	v_cndmask_b32_e32 v173, v142, v173, vcc
	v_cmp_lt_i32_e32 vcc, 0xc0, v143
	s_nop 1
	v_cndmask_b32_e32 v174, v142, v174, vcc
	v_cmp_lt_i32_e32 vcc, 0xc8, v143
	s_nop 1
	v_cndmask_b32_e32 v175, v142, v175, vcc
	v_cmp_lt_i32_e32 vcc, 0xd0, v143
	s_nop 1
	v_cndmask_b32_e32 v176, v142, v176, vcc
	v_cmp_lt_i32_e32 vcc, 0xd8, v143
	s_nop 1
	v_cndmask_b32_e32 v177, v142, v177, vcc
	v_cmp_lt_i32_e32 vcc, 0xe0, v143
	s_nop 1
	v_cndmask_b32_e32 v178, v142, v178, vcc
	v_cmp_lt_i32_e32 vcc, 0xe8, v143
	s_nop 1
	v_cndmask_b32_e32 v179, v142, v179, vcc
	v_cmp_lt_i32_e32 vcc, 0xf0, v143
	s_nop 1
	v_cndmask_b32_e32 v180, v142, v180, vcc
	v_cmp_lt_i32_e32 vcc, 0xf8, v143
	s_nop 1
	v_cndmask_b32_e32 v181, v142, v181, vcc
.Latt_nomask:
	v_max3_f32 v134, v150, v151, v152
	v_max3_f32 v134, v134, v153, v154
	v_max3_f32 v134, v134, v155, v156
	v_max3_f32 v134, v134, v157, v158
	v_max3_f32 v134, v134, v159, v160
	v_max3_f32 v134, v134, v161, v162
	v_max3_f32 v134, v134, v163, v164
	v_max3_f32 v134, v134, v165, v166
	v_max3_f32 v134, v134, v167, v168
	v_max3_f32 v134, v134, v169, v170
	v_max3_f32 v134, v134, v171, v172
	v_max3_f32 v134, v134, v173, v174
	v_max3_f32 v134, v134, v175, v176
	v_max3_f32 v134, v134, v177, v178
	v_max3_f32 v134, v134, v179, v180
	v_max_f32_e32 v134, v134, v181
	s_nop 1
	v_mov_b32_dpp v135, v134 row_ror:8 row_mask:0xf bank_mask:0xf
	s_nop 0
	v_max_f32_e32 v134, v134, v135
	ds_bpermute_b32 v135, v140, v134
	s_waitcnt lgkmcnt(0)
	v_max_f32_e32 v134, v134, v135
	ds_bpermute_b32 v135, v141, v134
	s_waitcnt lgkmcnt(0)
	v_max_f32_e32 v134, v134, v135
	v_mul_f32_e32 v134, 0xbfb8aa3b, v134
	v_fma_f32 v150, v150, s28, v134
	v_fma_f32 v151, v151, s28, v134
	v_fma_f32 v152, v152, s28, v134
	v_fma_f32 v153, v153, s28, v134
	v_fma_f32 v154, v154, s28, v134
	v_fma_f32 v155, v155, s28, v134
	v_fma_f32 v156, v156, s28, v134
	v_fma_f32 v157, v157, s28, v134
	v_fma_f32 v158, v158, s28, v134
	v_fma_f32 v159, v159, s28, v134
	v_fma_f32 v160, v160, s28, v134
	v_fma_f32 v161, v161, s28, v134
	v_fma_f32 v162, v162, s28, v134
	v_fma_f32 v163, v163, s28, v134
	v_fma_f32 v164, v164, s28, v134
	v_fma_f32 v165, v165, s28, v134
	v_fma_f32 v166, v166, s28, v134
	v_fma_f32 v167, v167, s28, v134
	v_fma_f32 v168, v168, s28, v134
	v_fma_f32 v169, v169, s28, v134
	v_fma_f32 v170, v170, s28, v134
	v_fma_f32 v171, v171, s28, v134
	v_fma_f32 v172, v172, s28, v134
	v_fma_f32 v173, v173, s28, v134
	v_fma_f32 v174, v174, s28, v134
	v_fma_f32 v175, v175, s28, v134
	v_fma_f32 v176, v176, s28, v134
	v_fma_f32 v177, v177, s28, v134
	v_fma_f32 v178, v178, s28, v134
	v_fma_f32 v179, v179, s28, v134
	v_fma_f32 v180, v180, s28, v134
	v_fma_f32 v181, v181, s28, v134
	v_exp_f32_e32 v150, v150
	v_exp_f32_e32 v151, v151
	v_exp_f32_e32 v152, v152
	v_exp_f32_e32 v153, v153
	v_exp_f32_e32 v154, v154
	v_exp_f32_e32 v155, v155
	v_exp_f32_e32 v156, v156
	v_exp_f32_e32 v157, v157
	v_exp_f32_e32 v158, v158
	v_exp_f32_e32 v159, v159
	v_exp_f32_e32 v160, v160
	v_exp_f32_e32 v161, v161
	v_exp_f32_e32 v162, v162
	v_exp_f32_e32 v163, v163
	v_exp_f32_e32 v164, v164
	v_exp_f32_e32 v165, v165
	v_exp_f32_e32 v166, v166
	v_exp_f32_e32 v167, v167
	v_exp_f32_e32 v168, v168
	v_exp_f32_e32 v169, v169
	v_exp_f32_e32 v170, v170
	v_exp_f32_e32 v171, v171
	v_exp_f32_e32 v172, v172
	v_exp_f32_e32 v173, v173
	v_exp_f32_e32 v174, v174
	v_exp_f32_e32 v175, v175
	v_exp_f32_e32 v176, v176
	v_exp_f32_e32 v177, v177
	v_exp_f32_e32 v178, v178
	v_exp_f32_e32 v179, v179
	v_exp_f32_e32 v180, v180
	v_exp_f32_e32 v181, v181
	s_nop 0
	v_add_f32_e32 v134, v150, v151
	v_add_f32_e32 v134, v134, v152
	v_add_f32_e32 v134, v134, v153
	v_add_f32_e32 v134, v134, v154
	v_add_f32_e32 v134, v134, v155
	v_add_f32_e32 v134, v134, v156
	v_add_f32_e32 v134, v134, v157
	v_add_f32_e32 v134, v134, v158
	v_add_f32_e32 v134, v134, v159
	v_add_f32_e32 v134, v134, v160
	v_add_f32_e32 v134, v134, v161
	v_add_f32_e32 v134, v134, v162
	v_add_f32_e32 v134, v134, v163
	v_add_f32_e32 v134, v134, v164
	v_add_f32_e32 v134, v134, v165
	v_add_f32_e32 v134, v134, v166
	v_add_f32_e32 v134, v134, v167
	v_add_f32_e32 v134, v134, v168
	v_add_f32_e32 v134, v134, v169
	v_add_f32_e32 v134, v134, v170
	v_add_f32_e32 v134, v134, v171
	v_add_f32_e32 v134, v134, v172
	v_add_f32_e32 v134, v134, v173
	v_add_f32_e32 v134, v134, v174
	v_add_f32_e32 v134, v134, v175
	v_add_f32_e32 v134, v134, v176
	v_add_f32_e32 v134, v134, v177
	v_add_f32_e32 v134, v134, v178
	v_add_f32_e32 v134, v134, v179
	v_add_f32_e32 v134, v134, v180
	v_add_f32_e32 v134, v134, v181
	s_nop 1
	v_mov_b32_dpp v135, v134 row_ror:8 row_mask:0xf bank_mask:0xf
	s_nop 0
	v_add_f32_e32 v134, v134, v135
	ds_bpermute_b32 v135, v140, v134
	s_waitcnt lgkmcnt(0)
; #define LAS __attribute__((address_space(3)))
; #define LDS_WAIT() asm volatile("s_waitcnt lgkmcnt(0)" ::: "memory")
; __device__ __forceinline__ void kv8_pv(const u32x4 (&buf)[8], f32x2v (&o2)[8], const LAS float* srow, int b) {
;     const LAS f32x4* p4 = (const LAS f32x4*)(srow + b * 8);
;     const f32x4 p0 = p4[0], p1 = p4[1];
;     const float p[8] = {p0.x, p0.y, p0.z, p0.w, p1.x, p1.y, p1.z, p1.w};
; #pragma unroll
;     for (int u = 0; u < 8; ++u) {
;         const u32x4 v = buf[u]; const f32x2v pp = {p[u], p[u]};
;         o2[0] = __builtin_elementwise_fma(pp, __builtin_amdgcn_cvt_pk_f32_fp8(v.x, false), o2[0]); o2[1] = __builtin_elementwise_fma(pp, __builtin_amdgcn_cvt_pk_f32_fp8(v.x, true), o2[1]);
;         o2[2] = __builtin_elementwise_fma(pp, __builtin_amdgcn_cvt_pk_f32_fp8(v.y, false), o2[2]); o2[3] = __builtin_elementwise_fma(pp, __builtin_amdgcn_cvt_pk_f32_fp8(v.y, true), o2[3]);
;         o2[4] = __builtin_elementwise_fma(pp, __builtin_amdgcn_cvt_pk_f32_fp8(v.z, false), o2[4]); o2[5] = __builtin_elementwise_fma(pp, __builtin_amdgcn_cvt_pk_f32_fp8(v.z, true), o2[5]);
;         o2[6] = __builtin_elementwise_fma(pp, __builtin_amdgcn_cvt_pk_f32_fp8(v.w, false), o2[6]); o2[7] = __builtin_elementwise_fma(pp, __builtin_amdgcn_cvt_pk_f32_fp8(v.w, true), o2[7]);
;     }
; }
; __device__ __forceinline__ void attn_query8(const unsigned char* __restrict__ KV8, const bf16_t* __restrict__ Z, const int* __restrict__ SEL, bf16_t* __restrict__ YMIX, int t, LAS float* sbuf  ) {
;     ...
;         sm = wave_sum(sm); const float inv = 1.f / sm;
; #pragma unroll
;         for (int jj = 0; jj < 4; ++jj) sbuf[h * 256 + lane + 64 * jj] = sv[jj] * inv;
;     }
;     LDS_WAIT();
;     f32x2v o[8];
; #pragma unroll
;     for (int i = 0; i < 8; ++i) o[i] = (f32x2v){0.f, 0.f};
; #pragma unroll 1
;     for (int b = 0; b < nb; b += 3) {
;         kv8_issue(C, rs, lvo, 1024, iv, CLAMPB(b + 2));
;         kv8_pv(A, o, srow, b);
;         kv8_issue(A, rs, lvo, 1024, iv, CLAMPB(b + 3));
;         if (b + 1 < nb) kv8_pv(B, o, srow, b + 1);
;         kv8_issue(B, rs, lvo, 1024, iv, CLAMPB(b + 4));
;         if (b + 2 < nb) kv8_pv(C, o, srow, b + 2);
;     }
	v_add_f32_e32 v134, v134, v135
	ds_bpermute_b32 v135, v141, v134
	s_waitcnt lgkmcnt(0)
	v_add_f32_e32 v134, v134, v135
	v_div_scale_f32 v132, s[8:9], v134, v134, 1.0
	v_rcp_f32_e32 v135, v132
	v_div_scale_f32 v133, vcc, 1.0, v134, 1.0
	v_fma_f32 v136, -v132, v135, 1.0
	v_fmac_f32_e32 v135, v136, v135
	v_mul_f32_e32 v136, v133, v135
	v_fma_f32 v137, -v132, v136, v133
	v_fmac_f32_e32 v136, v137, v135
	v_fma_f32 v132, -v132, v136, v133
	s_nop 1
	v_div_fmas_f32 v132, v132, v135, v136
	v_div_fixup_f32 v134, v132, v134, 1.0
	v_mov_b32_e32 v149, v134
	s_waitcnt vmcnt(31)
	ds_write_b32 v148, v240 offset:0
	ds_write_b32 v148, v241 offset:32
	ds_write_b32 v148, v242 offset:64
	ds_write_b32 v148, v243 offset:96
	v_cvt_pk_f32_fp8_e32 v[214:215], v0
	v_cvt_pk_f32_fp8_sdwa v[216:217], v0 src0_sel:WORD_1
	v_pk_mul_f32 v[198:199], v[150:151], v[214:215] op_sel_hi:[0,1]
	v_pk_mul_f32 v[200:201], v[150:151], v[216:217] op_sel_hi:[0,1]
	v_cvt_pk_f32_fp8_e32 v[218:219], v1
	v_cvt_pk_f32_fp8_sdwa v[220:221], v1 src0_sel:WORD_1
	v_pk_mul_f32 v[202:203], v[150:151], v[218:219] op_sel_hi:[0,1]
	v_pk_mul_f32 v[204:205], v[150:151], v[220:221] op_sel_hi:[0,1]
	v_cvt_pk_f32_fp8_e32 v[214:215], v2
	v_cvt_pk_f32_fp8_sdwa v[216:217], v2 src0_sel:WORD_1
	v_pk_mul_f32 v[206:207], v[150:151], v[214:215] op_sel_hi:[0,1]
	v_pk_mul_f32 v[208:209], v[150:151], v[216:217] op_sel_hi:[0,1]
	v_cvt_pk_f32_fp8_e32 v[218:219], v3
	v_cvt_pk_f32_fp8_sdwa v[220:221], v3 src0_sel:WORD_1
	v_pk_mul_f32 v[210:211], v[150:151], v[218:219] op_sel_hi:[0,1]
	v_pk_mul_f32 v[212:213], v[150:151], v[220:221] op_sel_hi:[0,1]
	s_waitcnt vmcnt(30)
	v_cvt_pk_f32_fp8_e32 v[214:215], v4
	v_cvt_pk_f32_fp8_sdwa v[216:217], v4 src0_sel:WORD_1
	v_pk_fma_f32 v[198:199], v[150:151], v[214:215], v[198:199] op_sel:[1,0,0]
	v_pk_fma_f32 v[200:201], v[150:151], v[216:217], v[200:201] op_sel:[1,0,0]
	v_cvt_pk_f32_fp8_e32 v[218:219], v5
	v_cvt_pk_f32_fp8_sdwa v[220:221], v5 src0_sel:WORD_1
	v_pk_fma_f32 v[202:203], v[150:151], v[218:219], v[202:203] op_sel:[1,0,0]
	v_pk_fma_f32 v[204:205], v[150:151], v[220:221], v[204:205] op_sel:[1,0,0]
	v_cvt_pk_f32_fp8_e32 v[214:215], v6
	v_cvt_pk_f32_fp8_sdwa v[216:217], v6 src0_sel:WORD_1
	v_pk_fma_f32 v[206:207], v[150:151], v[214:215], v[206:207] op_sel:[1,0,0]
	v_pk_fma_f32 v[208:209], v[150:151], v[216:217], v[208:209] op_sel:[1,0,0]
	v_cvt_pk_f32_fp8_e32 v[218:219], v7
	v_cvt_pk_f32_fp8_sdwa v[220:221], v7 src0_sel:WORD_1
	v_pk_fma_f32 v[210:211], v[150:151], v[218:219], v[210:211] op_sel:[1,0,0]
	v_pk_fma_f32 v[212:213], v[150:151], v[220:221], v[212:213] op_sel:[1,0,0]
	s_waitcnt vmcnt(29)
	v_cvt_pk_f32_fp8_e32 v[214:215], v8
	v_cvt_pk_f32_fp8_sdwa v[216:217], v8 src0_sel:WORD_1
	v_pk_fma_f32 v[198:199], v[152:153], v[214:215], v[198:199] op_sel_hi:[0,1,1]
	v_pk_fma_f32 v[200:201], v[152:153], v[216:217], v[200:201] op_sel_hi:[0,1,1]
	v_cvt_pk_f32_fp8_e32 v[218:219], v9
	v_cvt_pk_f32_fp8_sdwa v[220:221], v9 src0_sel:WORD_1
	v_pk_fma_f32 v[202:203], v[152:153], v[218:219], v[202:203] op_sel_hi:[0,1,1]
	v_pk_fma_f32 v[204:205], v[152:153], v[220:221], v[204:205] op_sel_hi:[0,1,1]
	v_cvt_pk_f32_fp8_e32 v[214:215], v10
	v_cvt_pk_f32_fp8_sdwa v[216:217], v10 src0_sel:WORD_1
	v_pk_fma_f32 v[206:207], v[152:153], v[214:215], v[206:207] op_sel_hi:[0,1,1]
	v_pk_fma_f32 v[208:209], v[152:153], v[216:217], v[208:209] op_sel_hi:[0,1,1]
	v_cvt_pk_f32_fp8_e32 v[218:219], v11
	v_cvt_pk_f32_fp8_sdwa v[220:221], v11 src0_sel:WORD_1
	v_pk_fma_f32 v[210:211], v[152:153], v[218:219], v[210:211] op_sel_hi:[0,1,1]
	v_pk_fma_f32 v[212:213], v[152:153], v[220:221], v[212:213] op_sel_hi:[0,1,1]
	s_waitcnt vmcnt(28)
	v_cvt_pk_f32_fp8_e32 v[214:215], v12
	v_cvt_pk_f32_fp8_sdwa v[216:217], v12 src0_sel:WORD_1
	v_pk_fma_f32 v[198:199], v[152:153], v[214:215], v[198:199] op_sel:[1,0,0]
	v_pk_fma_f32 v[200:201], v[152:153], v[216:217], v[200:201] op_sel:[1,0,0]
	v_cvt_pk_f32_fp8_e32 v[218:219], v13
	v_cvt_pk_f32_fp8_sdwa v[220:221], v13 src0_sel:WORD_1
	v_pk_fma_f32 v[202:203], v[152:153], v[218:219], v[202:203] op_sel:[1,0,0]
	v_pk_fma_f32 v[204:205], v[152:153], v[220:221], v[204:205] op_sel:[1,0,0]
	v_cvt_pk_f32_fp8_e32 v[214:215], v14
	v_cvt_pk_f32_fp8_sdwa v[216:217], v14 src0_sel:WORD_1
	v_pk_fma_f32 v[206:207], v[152:153], v[214:215], v[206:207] op_sel:[1,0,0]
	v_pk_fma_f32 v[208:209], v[152:153], v[216:217], v[208:209] op_sel:[1,0,0]
	v_cvt_pk_f32_fp8_e32 v[218:219], v15
	v_cvt_pk_f32_fp8_sdwa v[220:221], v15 src0_sel:WORD_1
	v_pk_fma_f32 v[210:211], v[152:153], v[218:219], v[210:211] op_sel:[1,0,0]
	v_pk_fma_f32 v[212:213], v[152:153], v[220:221], v[212:213] op_sel:[1,0,0]
	ds_read_b128 v[150:153], v139 offset:0
	s_waitcnt vmcnt(27)
	v_cvt_pk_f32_fp8_e32 v[214:215], v16
	v_cvt_pk_f32_fp8_sdwa v[216:217], v16 src0_sel:WORD_1
	v_pk_fma_f32 v[198:199], v[154:155], v[214:215], v[198:199] op_sel_hi:[0,1,1]
	v_pk_fma_f32 v[200:201], v[154:155], v[216:217], v[200:201] op_sel_hi:[0,1,1]
	v_cvt_pk_f32_fp8_e32 v[218:219], v17
	v_cvt_pk_f32_fp8_sdwa v[220:221], v17 src0_sel:WORD_1
	v_pk_fma_f32 v[202:203], v[154:155], v[218:219], v[202:203] op_sel_hi:[0,1,1]
	v_pk_fma_f32 v[204:205], v[154:155], v[220:221], v[204:205] op_sel_hi:[0,1,1]
	v_cvt_pk_f32_fp8_e32 v[214:215], v18
	v_cvt_pk_f32_fp8_sdwa v[216:217], v18 src0_sel:WORD_1
	v_pk_fma_f32 v[206:207], v[154:155], v[214:215], v[206:207] op_sel_hi:[0,1,1]
	v_pk_fma_f32 v[208:209], v[154:155], v[216:217], v[208:209] op_sel_hi:[0,1,1]
	v_cvt_pk_f32_fp8_e32 v[218:219], v19
	v_cvt_pk_f32_fp8_sdwa v[220:221], v19 src0_sel:WORD_1
	v_pk_fma_f32 v[210:211], v[154:155], v[218:219], v[210:211] op_sel_hi:[0,1,1]
	v_pk_fma_f32 v[212:213], v[154:155], v[220:221], v[212:213] op_sel_hi:[0,1,1]
	s_waitcnt vmcnt(26)
; #define LAS __attribute__((address_space(3)))
; __device__ __forceinline__ void kv8_issue(u32x4 (&buf)[8], __amdgpu_buffer_rsrc_t rs, int voff  , int sbase  , const int (&iv)[4], int b) {
;     const int jj = b >> 3, l0 = (b & 7) * 8;
;     const int ivb = (jj == 0) ? iv[0] : (jj == 1) ? iv[1] : (jj == 2) ? iv[2] : iv[3];
; #pragma unroll
;     for (int u = 0; u < 8; ++u) { const int si = __builtin_amdgcn_readlane(ivb, l0 + u); buf[u] = __builtin_amdgcn_raw_buffer_load_b128(rs, voff, si * 2048 + sbase, KV8_AUX); }
; }
; __device__ __forceinline__ void kv8_pv(const u32x4 (&buf)[8], f32x2v (&o2)[8], const LAS float* srow, int b) {
;     const LAS f32x4* p4 = (const LAS f32x4*)(srow + b * 8);
;     const f32x4 p0 = p4[0], p1 = p4[1];
;     const float p[8] = {p0.x, p0.y, p0.z, p0.w, p1.x, p1.y, p1.z, p1.w};
; #pragma unroll
;     for (int u = 0; u < 8; ++u) {
;         const u32x4 v = buf[u]; const f32x2v pp = {p[u], p[u]};
;         o2[0] = __builtin_elementwise_fma(pp, __builtin_amdgcn_cvt_pk_f32_fp8(v.x, false), o2[0]); o2[1] = __builtin_elementwise_fma(pp, __builtin_amdgcn_cvt_pk_f32_fp8(v.x, true), o2[1]);
;         o2[2] = __builtin_elementwise_fma(pp, __builtin_amdgcn_cvt_pk_f32_fp8(v.y, false), o2[2]); o2[3] = __builtin_elementwise_fma(pp, __builtin_amdgcn_cvt_pk_f32_fp8(v.y, true), o2[3]);
;         o2[4] = __builtin_elementwise_fma(pp, __builtin_amdgcn_cvt_pk_f32_fp8(v.z, false), o2[4]); o2[5] = __builtin_elementwise_fma(pp, __builtin_amdgcn_cvt_pk_f32_fp8(v.z, true), o2[5]);
;         o2[6] = __builtin_elementwise_fma(pp, __builtin_amdgcn_cvt_pk_f32_fp8(v.w, false), o2[6]); o2[7] = __builtin_elementwise_fma(pp, __builtin_amdgcn_cvt_pk_f32_fp8(v.w, true), o2[7]);
;     }
; }
	v_cvt_pk_f32_fp8_e32 v[214:215], v20
	v_cvt_pk_f32_fp8_sdwa v[216:217], v20 src0_sel:WORD_1
	v_pk_fma_f32 v[198:199], v[154:155], v[214:215], v[198:199] op_sel:[1,0,0]
	v_pk_fma_f32 v[200:201], v[154:155], v[216:217], v[200:201] op_sel:[1,0,0]
	v_cvt_pk_f32_fp8_e32 v[218:219], v21
	v_cvt_pk_f32_fp8_sdwa v[220:221], v21 src0_sel:WORD_1
	v_pk_fma_f32 v[202:203], v[154:155], v[218:219], v[202:203] op_sel:[1,0,0]
	v_pk_fma_f32 v[204:205], v[154:155], v[220:221], v[204:205] op_sel:[1,0,0]
	v_cvt_pk_f32_fp8_e32 v[214:215], v22
	v_cvt_pk_f32_fp8_sdwa v[216:217], v22 src0_sel:WORD_1
	v_pk_fma_f32 v[206:207], v[154:155], v[214:215], v[206:207] op_sel:[1,0,0]
	v_pk_fma_f32 v[208:209], v[154:155], v[216:217], v[208:209] op_sel:[1,0,0]
	v_cvt_pk_f32_fp8_e32 v[218:219], v23
	v_cvt_pk_f32_fp8_sdwa v[220:221], v23 src0_sel:WORD_1
	v_pk_fma_f32 v[210:211], v[154:155], v[218:219], v[210:211] op_sel:[1,0,0]
	v_pk_fma_f32 v[212:213], v[154:155], v[220:221], v[212:213] op_sel:[1,0,0]
	s_waitcnt lgkmcnt(0)
	v_lshl_add_u32 v150, v150, 8, v138
	v_lshl_add_u32 v151, v151, 8, v138
	v_lshl_add_u32 v152, v152, 8, v138
	v_lshl_add_u32 v153, v153, 8, v138
	buffer_load_dwordx4 v[0:3], v150, s[16:19], s26 offen sc0
	buffer_load_dwordx4 v[4:7], v151, s[16:19], s26 offen sc0
	buffer_load_dwordx4 v[8:11], v152, s[16:19], s26 offen sc0
	buffer_load_dwordx4 v[12:15], v153, s[16:19], s26 offen sc0
	s_waitcnt vmcnt(29)
	v_cvt_pk_f32_fp8_e32 v[214:215], v24
	v_cvt_pk_f32_fp8_sdwa v[216:217], v24 src0_sel:WORD_1
	v_pk_fma_f32 v[198:199], v[156:157], v[214:215], v[198:199] op_sel_hi:[0,1,1]
	v_pk_fma_f32 v[200:201], v[156:157], v[216:217], v[200:201] op_sel_hi:[0,1,1]
	v_cvt_pk_f32_fp8_e32 v[218:219], v25
	v_cvt_pk_f32_fp8_sdwa v[220:221], v25 src0_sel:WORD_1
	v_pk_fma_f32 v[202:203], v[156:157], v[218:219], v[202:203] op_sel_hi:[0,1,1]
	v_pk_fma_f32 v[204:205], v[156:157], v[220:221], v[204:205] op_sel_hi:[0,1,1]
	v_cvt_pk_f32_fp8_e32 v[214:215], v26
	v_cvt_pk_f32_fp8_sdwa v[216:217], v26 src0_sel:WORD_1
	v_pk_fma_f32 v[206:207], v[156:157], v[214:215], v[206:207] op_sel_hi:[0,1,1]
	v_pk_fma_f32 v[208:209], v[156:157], v[216:217], v[208:209] op_sel_hi:[0,1,1]
	v_cvt_pk_f32_fp8_e32 v[218:219], v27
	v_cvt_pk_f32_fp8_sdwa v[220:221], v27 src0_sel:WORD_1
	v_pk_fma_f32 v[210:211], v[156:157], v[218:219], v[210:211] op_sel_hi:[0,1,1]
	v_pk_fma_f32 v[212:213], v[156:157], v[220:221], v[212:213] op_sel_hi:[0,1,1]
	s_waitcnt vmcnt(28)
	v_cvt_pk_f32_fp8_e32 v[214:215], v28
	v_cvt_pk_f32_fp8_sdwa v[216:217], v28 src0_sel:WORD_1
	v_pk_fma_f32 v[198:199], v[156:157], v[214:215], v[198:199] op_sel:[1,0,0]
	v_pk_fma_f32 v[200:201], v[156:157], v[216:217], v[200:201] op_sel:[1,0,0]
	v_cvt_pk_f32_fp8_e32 v[218:219], v29
	v_cvt_pk_f32_fp8_sdwa v[220:221], v29 src0_sel:WORD_1
	v_pk_fma_f32 v[202:203], v[156:157], v[218:219], v[202:203] op_sel:[1,0,0]
	v_pk_fma_f32 v[204:205], v[156:157], v[220:221], v[204:205] op_sel:[1,0,0]
	v_cvt_pk_f32_fp8_e32 v[214:215], v30
	v_cvt_pk_f32_fp8_sdwa v[216:217], v30 src0_sel:WORD_1
	v_pk_fma_f32 v[206:207], v[156:157], v[214:215], v[206:207] op_sel:[1,0,0]
	v_pk_fma_f32 v[208:209], v[156:157], v[216:217], v[208:209] op_sel:[1,0,0]
	v_cvt_pk_f32_fp8_e32 v[218:219], v31
	v_cvt_pk_f32_fp8_sdwa v[220:221], v31 src0_sel:WORD_1
	v_pk_fma_f32 v[210:211], v[156:157], v[218:219], v[210:211] op_sel:[1,0,0]
	v_pk_fma_f32 v[212:213], v[156:157], v[220:221], v[212:213] op_sel:[1,0,0]
	ds_read_b128 v[154:157], v139 offset:16
	s_waitcnt vmcnt(27)
	v_cvt_pk_f32_fp8_e32 v[214:215], v32
	v_cvt_pk_f32_fp8_sdwa v[216:217], v32 src0_sel:WORD_1
	v_pk_fma_f32 v[198:199], v[158:159], v[214:215], v[198:199] op_sel_hi:[0,1,1]
	v_pk_fma_f32 v[200:201], v[158:159], v[216:217], v[200:201] op_sel_hi:[0,1,1]
	v_cvt_pk_f32_fp8_e32 v[218:219], v33
	v_cvt_pk_f32_fp8_sdwa v[220:221], v33 src0_sel:WORD_1
	v_pk_fma_f32 v[202:203], v[158:159], v[218:219], v[202:203] op_sel_hi:[0,1,1]
	v_pk_fma_f32 v[204:205], v[158:159], v[220:221], v[204:205] op_sel_hi:[0,1,1]
	v_cvt_pk_f32_fp8_e32 v[214:215], v34
	v_cvt_pk_f32_fp8_sdwa v[216:217], v34 src0_sel:WORD_1
	v_pk_fma_f32 v[206:207], v[158:159], v[214:215], v[206:207] op_sel_hi:[0,1,1]
	v_pk_fma_f32 v[208:209], v[158:159], v[216:217], v[208:209] op_sel_hi:[0,1,1]
	v_cvt_pk_f32_fp8_e32 v[218:219], v35
	v_cvt_pk_f32_fp8_sdwa v[220:221], v35 src0_sel:WORD_1
	v_pk_fma_f32 v[210:211], v[158:159], v[218:219], v[210:211] op_sel_hi:[0,1,1]
	v_pk_fma_f32 v[212:213], v[158:159], v[220:221], v[212:213] op_sel_hi:[0,1,1]
	s_waitcnt vmcnt(26)
	v_cvt_pk_f32_fp8_e32 v[214:215], v36
	v_cvt_pk_f32_fp8_sdwa v[216:217], v36 src0_sel:WORD_1
	v_pk_fma_f32 v[198:199], v[158:159], v[214:215], v[198:199] op_sel:[1,0,0]
	v_pk_fma_f32 v[200:201], v[158:159], v[216:217], v[200:201] op_sel:[1,0,0]
	v_cvt_pk_f32_fp8_e32 v[218:219], v37
	v_cvt_pk_f32_fp8_sdwa v[220:221], v37 src0_sel:WORD_1
	v_pk_fma_f32 v[202:203], v[158:159], v[218:219], v[202:203] op_sel:[1,0,0]
	v_pk_fma_f32 v[204:205], v[158:159], v[220:221], v[204:205] op_sel:[1,0,0]
	v_cvt_pk_f32_fp8_e32 v[214:215], v38
	v_cvt_pk_f32_fp8_sdwa v[216:217], v38 src0_sel:WORD_1
	v_pk_fma_f32 v[206:207], v[158:159], v[214:215], v[206:207] op_sel:[1,0,0]
	v_pk_fma_f32 v[208:209], v[158:159], v[216:217], v[208:209] op_sel:[1,0,0]
	v_cvt_pk_f32_fp8_e32 v[218:219], v39
	v_cvt_pk_f32_fp8_sdwa v[220:221], v39 src0_sel:WORD_1
	v_pk_fma_f32 v[210:211], v[158:159], v[218:219], v[210:211] op_sel:[1,0,0]
	v_pk_fma_f32 v[212:213], v[158:159], v[220:221], v[212:213] op_sel:[1,0,0]
	s_waitcnt lgkmcnt(0)
; #define LAS __attribute__((address_space(3)))
; __device__ __forceinline__ void kv8_issue(u32x4 (&buf)[8], __amdgpu_buffer_rsrc_t rs, int voff  , int sbase  , const int (&iv)[4], int b) {
;     const int jj = b >> 3, l0 = (b & 7) * 8;
;     const int ivb = (jj == 0) ? iv[0] : (jj == 1) ? iv[1] : (jj == 2) ? iv[2] : iv[3];
; #pragma unroll
;     for (int u = 0; u < 8; ++u) { const int si = __builtin_amdgcn_readlane(ivb, l0 + u); buf[u] = __builtin_amdgcn_raw_buffer_load_b128(rs, voff, si * 2048 + sbase, KV8_AUX); }
; }
; __device__ __forceinline__ void kv8_pv(const u32x4 (&buf)[8], f32x2v (&o2)[8], const LAS float* srow, int b) {
;     const LAS f32x4* p4 = (const LAS f32x4*)(srow + b * 8);
;     const f32x4 p0 = p4[0], p1 = p4[1];
;     const float p[8] = {p0.x, p0.y, p0.z, p0.w, p1.x, p1.y, p1.z, p1.w};
; #pragma unroll
;     for (int u = 0; u < 8; ++u) {
;         const u32x4 v = buf[u]; const f32x2v pp = {p[u], p[u]};
;         o2[0] = __builtin_elementwise_fma(pp, __builtin_amdgcn_cvt_pk_f32_fp8(v.x, false), o2[0]); o2[1] = __builtin_elementwise_fma(pp, __builtin_amdgcn_cvt_pk_f32_fp8(v.x, true), o2[1]);
;         o2[2] = __builtin_elementwise_fma(pp, __builtin_amdgcn_cvt_pk_f32_fp8(v.y, false), o2[2]); o2[3] = __builtin_elementwise_fma(pp, __builtin_amdgcn_cvt_pk_f32_fp8(v.y, true), o2[3]);
;         o2[4] = __builtin_elementwise_fma(pp, __builtin_amdgcn_cvt_pk_f32_fp8(v.z, false), o2[4]); o2[5] = __builtin_elementwise_fma(pp, __builtin_amdgcn_cvt_pk_f32_fp8(v.z, true), o2[5]);
;         o2[6] = __builtin_elementwise_fma(pp, __builtin_amdgcn_cvt_pk_f32_fp8(v.w, false), o2[6]); o2[7] = __builtin_elementwise_fma(pp, __builtin_amdgcn_cvt_pk_f32_fp8(v.w, true), o2[7]);
;     }
; }
	v_lshl_add_u32 v154, v154, 8, v138
	v_lshl_add_u32 v155, v155, 8, v138
	v_lshl_add_u32 v156, v156, 8, v138
	v_lshl_add_u32 v157, v157, 8, v138
	buffer_load_dwordx4 v[16:19], v154, s[16:19], s26 offen sc0
	buffer_load_dwordx4 v[20:23], v155, s[16:19], s26 offen sc0
	buffer_load_dwordx4 v[24:27], v156, s[16:19], s26 offen sc0
	buffer_load_dwordx4 v[28:31], v157, s[16:19], s26 offen sc0
	s_waitcnt vmcnt(29)
	v_cvt_pk_f32_fp8_e32 v[214:215], v40
	v_cvt_pk_f32_fp8_sdwa v[216:217], v40 src0_sel:WORD_1
	v_pk_fma_f32 v[198:199], v[160:161], v[214:215], v[198:199] op_sel_hi:[0,1,1]
	v_pk_fma_f32 v[200:201], v[160:161], v[216:217], v[200:201] op_sel_hi:[0,1,1]
	v_cvt_pk_f32_fp8_e32 v[218:219], v41
	v_cvt_pk_f32_fp8_sdwa v[220:221], v41 src0_sel:WORD_1
	v_pk_fma_f32 v[202:203], v[160:161], v[218:219], v[202:203] op_sel_hi:[0,1,1]
	v_pk_fma_f32 v[204:205], v[160:161], v[220:221], v[204:205] op_sel_hi:[0,1,1]
	v_cvt_pk_f32_fp8_e32 v[214:215], v42
	v_cvt_pk_f32_fp8_sdwa v[216:217], v42 src0_sel:WORD_1
	v_pk_fma_f32 v[206:207], v[160:161], v[214:215], v[206:207] op_sel_hi:[0,1,1]
	v_pk_fma_f32 v[208:209], v[160:161], v[216:217], v[208:209] op_sel_hi:[0,1,1]
	v_cvt_pk_f32_fp8_e32 v[218:219], v43
	v_cvt_pk_f32_fp8_sdwa v[220:221], v43 src0_sel:WORD_1
	v_pk_fma_f32 v[210:211], v[160:161], v[218:219], v[210:211] op_sel_hi:[0,1,1]
	v_pk_fma_f32 v[212:213], v[160:161], v[220:221], v[212:213] op_sel_hi:[0,1,1]
	s_waitcnt vmcnt(28)
	v_cvt_pk_f32_fp8_e32 v[214:215], v44
	v_cvt_pk_f32_fp8_sdwa v[216:217], v44 src0_sel:WORD_1
	v_pk_fma_f32 v[198:199], v[160:161], v[214:215], v[198:199] op_sel:[1,0,0]
	v_pk_fma_f32 v[200:201], v[160:161], v[216:217], v[200:201] op_sel:[1,0,0]
	v_cvt_pk_f32_fp8_e32 v[218:219], v45
	v_cvt_pk_f32_fp8_sdwa v[220:221], v45 src0_sel:WORD_1
	v_pk_fma_f32 v[202:203], v[160:161], v[218:219], v[202:203] op_sel:[1,0,0]
	v_pk_fma_f32 v[204:205], v[160:161], v[220:221], v[204:205] op_sel:[1,0,0]
	v_cvt_pk_f32_fp8_e32 v[214:215], v46
	v_cvt_pk_f32_fp8_sdwa v[216:217], v46 src0_sel:WORD_1
	v_pk_fma_f32 v[206:207], v[160:161], v[214:215], v[206:207] op_sel:[1,0,0]
	v_pk_fma_f32 v[208:209], v[160:161], v[216:217], v[208:209] op_sel:[1,0,0]
	v_cvt_pk_f32_fp8_e32 v[218:219], v47
	v_cvt_pk_f32_fp8_sdwa v[220:221], v47 src0_sel:WORD_1
	v_pk_fma_f32 v[210:211], v[160:161], v[218:219], v[210:211] op_sel:[1,0,0]
	v_pk_fma_f32 v[212:213], v[160:161], v[220:221], v[212:213] op_sel:[1,0,0]
	ds_read_b128 v[158:161], v139 offset:32
	s_waitcnt vmcnt(27)
	v_cvt_pk_f32_fp8_e32 v[214:215], v48
	v_cvt_pk_f32_fp8_sdwa v[216:217], v48 src0_sel:WORD_1
	v_pk_fma_f32 v[198:199], v[162:163], v[214:215], v[198:199] op_sel_hi:[0,1,1]
	v_pk_fma_f32 v[200:201], v[162:163], v[216:217], v[200:201] op_sel_hi:[0,1,1]
	v_cvt_pk_f32_fp8_e32 v[218:219], v49
	v_cvt_pk_f32_fp8_sdwa v[220:221], v49 src0_sel:WORD_1
	v_pk_fma_f32 v[202:203], v[162:163], v[218:219], v[202:203] op_sel_hi:[0,1,1]
	v_pk_fma_f32 v[204:205], v[162:163], v[220:221], v[204:205] op_sel_hi:[0,1,1]
	v_cvt_pk_f32_fp8_e32 v[214:215], v50
	v_cvt_pk_f32_fp8_sdwa v[216:217], v50 src0_sel:WORD_1
	v_pk_fma_f32 v[206:207], v[162:163], v[214:215], v[206:207] op_sel_hi:[0,1,1]
	v_pk_fma_f32 v[208:209], v[162:163], v[216:217], v[208:209] op_sel_hi:[0,1,1]
	v_cvt_pk_f32_fp8_e32 v[218:219], v51
	v_cvt_pk_f32_fp8_sdwa v[220:221], v51 src0_sel:WORD_1
	v_pk_fma_f32 v[210:211], v[162:163], v[218:219], v[210:211] op_sel_hi:[0,1,1]
	v_pk_fma_f32 v[212:213], v[162:163], v[220:221], v[212:213] op_sel_hi:[0,1,1]
	s_waitcnt vmcnt(26)
	v_cvt_pk_f32_fp8_e32 v[214:215], v52
	v_cvt_pk_f32_fp8_sdwa v[216:217], v52 src0_sel:WORD_1
	v_pk_fma_f32 v[198:199], v[162:163], v[214:215], v[198:199] op_sel:[1,0,0]
	v_pk_fma_f32 v[200:201], v[162:163], v[216:217], v[200:201] op_sel:[1,0,0]
	v_cvt_pk_f32_fp8_e32 v[218:219], v53
	v_cvt_pk_f32_fp8_sdwa v[220:221], v53 src0_sel:WORD_1
	v_pk_fma_f32 v[202:203], v[162:163], v[218:219], v[202:203] op_sel:[1,0,0]
	v_pk_fma_f32 v[204:205], v[162:163], v[220:221], v[204:205] op_sel:[1,0,0]
	v_cvt_pk_f32_fp8_e32 v[214:215], v54
	v_cvt_pk_f32_fp8_sdwa v[216:217], v54 src0_sel:WORD_1
	v_pk_fma_f32 v[206:207], v[162:163], v[214:215], v[206:207] op_sel:[1,0,0]
	v_pk_fma_f32 v[208:209], v[162:163], v[216:217], v[208:209] op_sel:[1,0,0]
	v_cvt_pk_f32_fp8_e32 v[218:219], v55
	v_cvt_pk_f32_fp8_sdwa v[220:221], v55 src0_sel:WORD_1
	v_pk_fma_f32 v[210:211], v[162:163], v[218:219], v[210:211] op_sel:[1,0,0]
	v_pk_fma_f32 v[212:213], v[162:163], v[220:221], v[212:213] op_sel:[1,0,0]
	s_waitcnt lgkmcnt(0)
	v_lshl_add_u32 v158, v158, 8, v138
	v_lshl_add_u32 v159, v159, 8, v138
	v_lshl_add_u32 v160, v160, 8, v138
	v_lshl_add_u32 v161, v161, 8, v138
	buffer_load_dwordx4 v[32:35], v158, s[16:19], s26 offen sc0
	buffer_load_dwordx4 v[36:39], v159, s[16:19], s26 offen sc0
	buffer_load_dwordx4 v[40:43], v160, s[16:19], s26 offen sc0
	buffer_load_dwordx4 v[44:47], v161, s[16:19], s26 offen sc0
	s_waitcnt vmcnt(29)
	v_cvt_pk_f32_fp8_e32 v[214:215], v56
	v_cvt_pk_f32_fp8_sdwa v[216:217], v56 src0_sel:WORD_1
	v_pk_fma_f32 v[198:199], v[164:165], v[214:215], v[198:199] op_sel_hi:[0,1,1]
	v_pk_fma_f32 v[200:201], v[164:165], v[216:217], v[200:201] op_sel_hi:[0,1,1]
	v_cvt_pk_f32_fp8_e32 v[218:219], v57
	v_cvt_pk_f32_fp8_sdwa v[220:221], v57 src0_sel:WORD_1
	v_pk_fma_f32 v[202:203], v[164:165], v[218:219], v[202:203] op_sel_hi:[0,1,1]
	v_pk_fma_f32 v[204:205], v[164:165], v[220:221], v[204:205] op_sel_hi:[0,1,1]
	v_cvt_pk_f32_fp8_e32 v[214:215], v58
	v_cvt_pk_f32_fp8_sdwa v[216:217], v58 src0_sel:WORD_1
	v_pk_fma_f32 v[206:207], v[164:165], v[214:215], v[206:207] op_sel_hi:[0,1,1]
	v_pk_fma_f32 v[208:209], v[164:165], v[216:217], v[208:209] op_sel_hi:[0,1,1]
	v_cvt_pk_f32_fp8_e32 v[218:219], v59
	v_cvt_pk_f32_fp8_sdwa v[220:221], v59 src0_sel:WORD_1
	v_pk_fma_f32 v[210:211], v[164:165], v[218:219], v[210:211] op_sel_hi:[0,1,1]
	v_pk_fma_f32 v[212:213], v[164:165], v[220:221], v[212:213] op_sel_hi:[0,1,1]
	s_waitcnt vmcnt(28)
; #define LAS __attribute__((address_space(3)))
; __device__ __forceinline__ void kv8_issue(u32x4 (&buf)[8], __amdgpu_buffer_rsrc_t rs, int voff  , int sbase  , const int (&iv)[4], int b) {
;     const int jj = b >> 3, l0 = (b & 7) * 8;
;     const int ivb = (jj == 0) ? iv[0] : (jj == 1) ? iv[1] : (jj == 2) ? iv[2] : iv[3];
; #pragma unroll
;     for (int u = 0; u < 8; ++u) { const int si = __builtin_amdgcn_readlane(ivb, l0 + u); buf[u] = __builtin_amdgcn_raw_buffer_load_b128(rs, voff, si * 2048 + sbase, KV8_AUX); }
; }
; __device__ __forceinline__ void kv8_pv(const u32x4 (&buf)[8], f32x2v (&o2)[8], const LAS float* srow, int b) {
;     const LAS f32x4* p4 = (const LAS f32x4*)(srow + b * 8);
;     const f32x4 p0 = p4[0], p1 = p4[1];
;     const float p[8] = {p0.x, p0.y, p0.z, p0.w, p1.x, p1.y, p1.z, p1.w};
; #pragma unroll
;     for (int u = 0; u < 8; ++u) {
;         const u32x4 v = buf[u]; const f32x2v pp = {p[u], p[u]};
;         o2[0] = __builtin_elementwise_fma(pp, __builtin_amdgcn_cvt_pk_f32_fp8(v.x, false), o2[0]); o2[1] = __builtin_elementwise_fma(pp, __builtin_amdgcn_cvt_pk_f32_fp8(v.x, true), o2[1]);
;         o2[2] = __builtin_elementwise_fma(pp, __builtin_amdgcn_cvt_pk_f32_fp8(v.y, false), o2[2]); o2[3] = __builtin_elementwise_fma(pp, __builtin_amdgcn_cvt_pk_f32_fp8(v.y, true), o2[3]);
;         o2[4] = __builtin_elementwise_fma(pp, __builtin_amdgcn_cvt_pk_f32_fp8(v.z, false), o2[4]); o2[5] = __builtin_elementwise_fma(pp, __builtin_amdgcn_cvt_pk_f32_fp8(v.z, true), o2[5]);
;         o2[6] = __builtin_elementwise_fma(pp, __builtin_amdgcn_cvt_pk_f32_fp8(v.w, false), o2[6]); o2[7] = __builtin_elementwise_fma(pp, __builtin_amdgcn_cvt_pk_f32_fp8(v.w, true), o2[7]);
;     }
; }
	v_cvt_pk_f32_fp8_e32 v[214:215], v60
	v_cvt_pk_f32_fp8_sdwa v[216:217], v60 src0_sel:WORD_1
	v_pk_fma_f32 v[198:199], v[164:165], v[214:215], v[198:199] op_sel:[1,0,0]
	v_pk_fma_f32 v[200:201], v[164:165], v[216:217], v[200:201] op_sel:[1,0,0]
	v_cvt_pk_f32_fp8_e32 v[218:219], v61
	v_cvt_pk_f32_fp8_sdwa v[220:221], v61 src0_sel:WORD_1
	v_pk_fma_f32 v[202:203], v[164:165], v[218:219], v[202:203] op_sel:[1,0,0]
	v_pk_fma_f32 v[204:205], v[164:165], v[220:221], v[204:205] op_sel:[1,0,0]
	v_cvt_pk_f32_fp8_e32 v[214:215], v62
	v_cvt_pk_f32_fp8_sdwa v[216:217], v62 src0_sel:WORD_1
	v_pk_fma_f32 v[206:207], v[164:165], v[214:215], v[206:207] op_sel:[1,0,0]
	v_pk_fma_f32 v[208:209], v[164:165], v[216:217], v[208:209] op_sel:[1,0,0]
	v_cvt_pk_f32_fp8_e32 v[218:219], v63
	v_cvt_pk_f32_fp8_sdwa v[220:221], v63 src0_sel:WORD_1
	v_pk_fma_f32 v[210:211], v[164:165], v[218:219], v[210:211] op_sel:[1,0,0]
	v_pk_fma_f32 v[212:213], v[164:165], v[220:221], v[212:213] op_sel:[1,0,0]
	ds_read_b128 v[162:165], v139 offset:48
	s_waitcnt vmcnt(27)
	v_cvt_pk_f32_fp8_e32 v[214:215], v64
	v_cvt_pk_f32_fp8_sdwa v[216:217], v64 src0_sel:WORD_1
	v_pk_fma_f32 v[198:199], v[166:167], v[214:215], v[198:199] op_sel_hi:[0,1,1]
	v_pk_fma_f32 v[200:201], v[166:167], v[216:217], v[200:201] op_sel_hi:[0,1,1]
	v_cvt_pk_f32_fp8_e32 v[218:219], v65
	v_cvt_pk_f32_fp8_sdwa v[220:221], v65 src0_sel:WORD_1
	v_pk_fma_f32 v[202:203], v[166:167], v[218:219], v[202:203] op_sel_hi:[0,1,1]
	v_pk_fma_f32 v[204:205], v[166:167], v[220:221], v[204:205] op_sel_hi:[0,1,1]
	v_cvt_pk_f32_fp8_e32 v[214:215], v66
	v_cvt_pk_f32_fp8_sdwa v[216:217], v66 src0_sel:WORD_1
	v_pk_fma_f32 v[206:207], v[166:167], v[214:215], v[206:207] op_sel_hi:[0,1,1]
	v_pk_fma_f32 v[208:209], v[166:167], v[216:217], v[208:209] op_sel_hi:[0,1,1]
	v_cvt_pk_f32_fp8_e32 v[218:219], v67
	v_cvt_pk_f32_fp8_sdwa v[220:221], v67 src0_sel:WORD_1
	v_pk_fma_f32 v[210:211], v[166:167], v[218:219], v[210:211] op_sel_hi:[0,1,1]
	v_pk_fma_f32 v[212:213], v[166:167], v[220:221], v[212:213] op_sel_hi:[0,1,1]
	s_waitcnt vmcnt(26)
	v_cvt_pk_f32_fp8_e32 v[214:215], v68
	v_cvt_pk_f32_fp8_sdwa v[216:217], v68 src0_sel:WORD_1
	v_pk_fma_f32 v[198:199], v[166:167], v[214:215], v[198:199] op_sel:[1,0,0]
	v_pk_fma_f32 v[200:201], v[166:167], v[216:217], v[200:201] op_sel:[1,0,0]
	v_cvt_pk_f32_fp8_e32 v[218:219], v69
	v_cvt_pk_f32_fp8_sdwa v[220:221], v69 src0_sel:WORD_1
	v_pk_fma_f32 v[202:203], v[166:167], v[218:219], v[202:203] op_sel:[1,0,0]
	v_pk_fma_f32 v[204:205], v[166:167], v[220:221], v[204:205] op_sel:[1,0,0]
	v_cvt_pk_f32_fp8_e32 v[214:215], v70
	v_cvt_pk_f32_fp8_sdwa v[216:217], v70 src0_sel:WORD_1
	v_pk_fma_f32 v[206:207], v[166:167], v[214:215], v[206:207] op_sel:[1,0,0]
	v_pk_fma_f32 v[208:209], v[166:167], v[216:217], v[208:209] op_sel:[1,0,0]
	v_cvt_pk_f32_fp8_e32 v[218:219], v71
	v_cvt_pk_f32_fp8_sdwa v[220:221], v71 src0_sel:WORD_1
	v_pk_fma_f32 v[210:211], v[166:167], v[218:219], v[210:211] op_sel:[1,0,0]
	v_pk_fma_f32 v[212:213], v[166:167], v[220:221], v[212:213] op_sel:[1,0,0]
	s_waitcnt lgkmcnt(0)
	v_lshl_add_u32 v162, v162, 8, v138
	v_lshl_add_u32 v163, v163, 8, v138
	v_lshl_add_u32 v164, v164, 8, v138
	v_lshl_add_u32 v165, v165, 8, v138
	buffer_load_dwordx4 v[48:51], v162, s[16:19], s26 offen sc0
	buffer_load_dwordx4 v[52:55], v163, s[16:19], s26 offen sc0
	buffer_load_dwordx4 v[56:59], v164, s[16:19], s26 offen sc0
	buffer_load_dwordx4 v[60:63], v165, s[16:19], s26 offen sc0
	s_waitcnt vmcnt(29)
	v_cvt_pk_f32_fp8_e32 v[214:215], v72
	v_cvt_pk_f32_fp8_sdwa v[216:217], v72 src0_sel:WORD_1
	v_pk_fma_f32 v[198:199], v[168:169], v[214:215], v[198:199] op_sel_hi:[0,1,1]
	v_pk_fma_f32 v[200:201], v[168:169], v[216:217], v[200:201] op_sel_hi:[0,1,1]
	v_cvt_pk_f32_fp8_e32 v[218:219], v73
	v_cvt_pk_f32_fp8_sdwa v[220:221], v73 src0_sel:WORD_1
	v_pk_fma_f32 v[202:203], v[168:169], v[218:219], v[202:203] op_sel_hi:[0,1,1]
	v_pk_fma_f32 v[204:205], v[168:169], v[220:221], v[204:205] op_sel_hi:[0,1,1]
	v_cvt_pk_f32_fp8_e32 v[214:215], v74
	v_cvt_pk_f32_fp8_sdwa v[216:217], v74 src0_sel:WORD_1
	v_pk_fma_f32 v[206:207], v[168:169], v[214:215], v[206:207] op_sel_hi:[0,1,1]
	v_pk_fma_f32 v[208:209], v[168:169], v[216:217], v[208:209] op_sel_hi:[0,1,1]
	v_cvt_pk_f32_fp8_e32 v[218:219], v75
	v_cvt_pk_f32_fp8_sdwa v[220:221], v75 src0_sel:WORD_1
	v_pk_fma_f32 v[210:211], v[168:169], v[218:219], v[210:211] op_sel_hi:[0,1,1]
	v_pk_fma_f32 v[212:213], v[168:169], v[220:221], v[212:213] op_sel_hi:[0,1,1]
	s_waitcnt vmcnt(28)
	v_cvt_pk_f32_fp8_e32 v[214:215], v76
	v_cvt_pk_f32_fp8_sdwa v[216:217], v76 src0_sel:WORD_1
	v_pk_fma_f32 v[198:199], v[168:169], v[214:215], v[198:199] op_sel:[1,0,0]
	v_pk_fma_f32 v[200:201], v[168:169], v[216:217], v[200:201] op_sel:[1,0,0]
	v_cvt_pk_f32_fp8_e32 v[218:219], v77
	v_cvt_pk_f32_fp8_sdwa v[220:221], v77 src0_sel:WORD_1
	v_pk_fma_f32 v[202:203], v[168:169], v[218:219], v[202:203] op_sel:[1,0,0]
	v_pk_fma_f32 v[204:205], v[168:169], v[220:221], v[204:205] op_sel:[1,0,0]
	v_cvt_pk_f32_fp8_e32 v[214:215], v78
	v_cvt_pk_f32_fp8_sdwa v[216:217], v78 src0_sel:WORD_1
	v_pk_fma_f32 v[206:207], v[168:169], v[214:215], v[206:207] op_sel:[1,0,0]
	v_pk_fma_f32 v[208:209], v[168:169], v[216:217], v[208:209] op_sel:[1,0,0]
	v_cvt_pk_f32_fp8_e32 v[218:219], v79
	v_cvt_pk_f32_fp8_sdwa v[220:221], v79 src0_sel:WORD_1
	v_pk_fma_f32 v[210:211], v[168:169], v[218:219], v[210:211] op_sel:[1,0,0]
	v_pk_fma_f32 v[212:213], v[168:169], v[220:221], v[212:213] op_sel:[1,0,0]
	ds_read_b128 v[166:169], v139 offset:64
	s_waitcnt vmcnt(27)
; #define LAS __attribute__((address_space(3)))
; __device__ __forceinline__ void kv8_issue(u32x4 (&buf)[8], __amdgpu_buffer_rsrc_t rs, int voff  , int sbase  , const int (&iv)[4], int b) {
;     const int jj = b >> 3, l0 = (b & 7) * 8;
;     const int ivb = (jj == 0) ? iv[0] : (jj == 1) ? iv[1] : (jj == 2) ? iv[2] : iv[3];
; #pragma unroll
;     for (int u = 0; u < 8; ++u) { const int si = __builtin_amdgcn_readlane(ivb, l0 + u); buf[u] = __builtin_amdgcn_raw_buffer_load_b128(rs, voff, si * 2048 + sbase, KV8_AUX); }
; }
; __device__ __forceinline__ void kv8_pv(const u32x4 (&buf)[8], f32x2v (&o2)[8], const LAS float* srow, int b) {
;     const LAS f32x4* p4 = (const LAS f32x4*)(srow + b * 8);
;     const f32x4 p0 = p4[0], p1 = p4[1];
;     const float p[8] = {p0.x, p0.y, p0.z, p0.w, p1.x, p1.y, p1.z, p1.w};
; #pragma unroll
;     for (int u = 0; u < 8; ++u) {
;         const u32x4 v = buf[u]; const f32x2v pp = {p[u], p[u]};
;         o2[0] = __builtin_elementwise_fma(pp, __builtin_amdgcn_cvt_pk_f32_fp8(v.x, false), o2[0]); o2[1] = __builtin_elementwise_fma(pp, __builtin_amdgcn_cvt_pk_f32_fp8(v.x, true), o2[1]);
;         o2[2] = __builtin_elementwise_fma(pp, __builtin_amdgcn_cvt_pk_f32_fp8(v.y, false), o2[2]); o2[3] = __builtin_elementwise_fma(pp, __builtin_amdgcn_cvt_pk_f32_fp8(v.y, true), o2[3]);
;         o2[4] = __builtin_elementwise_fma(pp, __builtin_amdgcn_cvt_pk_f32_fp8(v.z, false), o2[4]); o2[5] = __builtin_elementwise_fma(pp, __builtin_amdgcn_cvt_pk_f32_fp8(v.z, true), o2[5]);
;         o2[6] = __builtin_elementwise_fma(pp, __builtin_amdgcn_cvt_pk_f32_fp8(v.w, false), o2[6]); o2[7] = __builtin_elementwise_fma(pp, __builtin_amdgcn_cvt_pk_f32_fp8(v.w, true), o2[7]);
;     }
; }
	v_cvt_pk_f32_fp8_e32 v[214:215], v80
	v_cvt_pk_f32_fp8_sdwa v[216:217], v80 src0_sel:WORD_1
	v_pk_fma_f32 v[198:199], v[170:171], v[214:215], v[198:199] op_sel_hi:[0,1,1]
	v_pk_fma_f32 v[200:201], v[170:171], v[216:217], v[200:201] op_sel_hi:[0,1,1]
	v_cvt_pk_f32_fp8_e32 v[218:219], v81
	v_cvt_pk_f32_fp8_sdwa v[220:221], v81 src0_sel:WORD_1
	v_pk_fma_f32 v[202:203], v[170:171], v[218:219], v[202:203] op_sel_hi:[0,1,1]
	v_pk_fma_f32 v[204:205], v[170:171], v[220:221], v[204:205] op_sel_hi:[0,1,1]
	v_cvt_pk_f32_fp8_e32 v[214:215], v82
	v_cvt_pk_f32_fp8_sdwa v[216:217], v82 src0_sel:WORD_1
	v_pk_fma_f32 v[206:207], v[170:171], v[214:215], v[206:207] op_sel_hi:[0,1,1]
	v_pk_fma_f32 v[208:209], v[170:171], v[216:217], v[208:209] op_sel_hi:[0,1,1]
	v_cvt_pk_f32_fp8_e32 v[218:219], v83
	v_cvt_pk_f32_fp8_sdwa v[220:221], v83 src0_sel:WORD_1
	v_pk_fma_f32 v[210:211], v[170:171], v[218:219], v[210:211] op_sel_hi:[0,1,1]
	v_pk_fma_f32 v[212:213], v[170:171], v[220:221], v[212:213] op_sel_hi:[0,1,1]
	s_waitcnt vmcnt(26)
	v_cvt_pk_f32_fp8_e32 v[214:215], v84
	v_cvt_pk_f32_fp8_sdwa v[216:217], v84 src0_sel:WORD_1
	v_pk_fma_f32 v[198:199], v[170:171], v[214:215], v[198:199] op_sel:[1,0,0]
	v_pk_fma_f32 v[200:201], v[170:171], v[216:217], v[200:201] op_sel:[1,0,0]
	v_cvt_pk_f32_fp8_e32 v[218:219], v85
	v_cvt_pk_f32_fp8_sdwa v[220:221], v85 src0_sel:WORD_1
	v_pk_fma_f32 v[202:203], v[170:171], v[218:219], v[202:203] op_sel:[1,0,0]
	v_pk_fma_f32 v[204:205], v[170:171], v[220:221], v[204:205] op_sel:[1,0,0]
	v_cvt_pk_f32_fp8_e32 v[214:215], v86
	v_cvt_pk_f32_fp8_sdwa v[216:217], v86 src0_sel:WORD_1
	v_pk_fma_f32 v[206:207], v[170:171], v[214:215], v[206:207] op_sel:[1,0,0]
	v_pk_fma_f32 v[208:209], v[170:171], v[216:217], v[208:209] op_sel:[1,0,0]
	v_cvt_pk_f32_fp8_e32 v[218:219], v87
	v_cvt_pk_f32_fp8_sdwa v[220:221], v87 src0_sel:WORD_1
	v_pk_fma_f32 v[210:211], v[170:171], v[218:219], v[210:211] op_sel:[1,0,0]
	v_pk_fma_f32 v[212:213], v[170:171], v[220:221], v[212:213] op_sel:[1,0,0]
	s_waitcnt lgkmcnt(0)
	v_lshl_add_u32 v166, v166, 8, v138
	v_lshl_add_u32 v167, v167, 8, v138
	v_lshl_add_u32 v168, v168, 8, v138
	v_lshl_add_u32 v169, v169, 8, v138
	buffer_load_dwordx4 v[64:67], v166, s[16:19], s26 offen sc0
	buffer_load_dwordx4 v[68:71], v167, s[16:19], s26 offen sc0
	buffer_load_dwordx4 v[72:75], v168, s[16:19], s26 offen sc0
	buffer_load_dwordx4 v[76:79], v169, s[16:19], s26 offen sc0
	s_waitcnt vmcnt(29)
	v_cvt_pk_f32_fp8_e32 v[214:215], v88
	v_cvt_pk_f32_fp8_sdwa v[216:217], v88 src0_sel:WORD_1
	v_pk_fma_f32 v[198:199], v[172:173], v[214:215], v[198:199] op_sel_hi:[0,1,1]
	v_pk_fma_f32 v[200:201], v[172:173], v[216:217], v[200:201] op_sel_hi:[0,1,1]
	v_cvt_pk_f32_fp8_e32 v[218:219], v89
	v_cvt_pk_f32_fp8_sdwa v[220:221], v89 src0_sel:WORD_1
	v_pk_fma_f32 v[202:203], v[172:173], v[218:219], v[202:203] op_sel_hi:[0,1,1]
	v_pk_fma_f32 v[204:205], v[172:173], v[220:221], v[204:205] op_sel_hi:[0,1,1]
	v_cvt_pk_f32_fp8_e32 v[214:215], v90
	v_cvt_pk_f32_fp8_sdwa v[216:217], v90 src0_sel:WORD_1
	v_pk_fma_f32 v[206:207], v[172:173], v[214:215], v[206:207] op_sel_hi:[0,1,1]
	v_pk_fma_f32 v[208:209], v[172:173], v[216:217], v[208:209] op_sel_hi:[0,1,1]
	v_cvt_pk_f32_fp8_e32 v[218:219], v91
	v_cvt_pk_f32_fp8_sdwa v[220:221], v91 src0_sel:WORD_1
	v_pk_fma_f32 v[210:211], v[172:173], v[218:219], v[210:211] op_sel_hi:[0,1,1]
	v_pk_fma_f32 v[212:213], v[172:173], v[220:221], v[212:213] op_sel_hi:[0,1,1]
	s_waitcnt vmcnt(28)
	v_cvt_pk_f32_fp8_e32 v[214:215], v92
	v_cvt_pk_f32_fp8_sdwa v[216:217], v92 src0_sel:WORD_1
	v_pk_fma_f32 v[198:199], v[172:173], v[214:215], v[198:199] op_sel:[1,0,0]
	v_pk_fma_f32 v[200:201], v[172:173], v[216:217], v[200:201] op_sel:[1,0,0]
	v_cvt_pk_f32_fp8_e32 v[218:219], v93
	v_cvt_pk_f32_fp8_sdwa v[220:221], v93 src0_sel:WORD_1
	v_pk_fma_f32 v[202:203], v[172:173], v[218:219], v[202:203] op_sel:[1,0,0]
	v_pk_fma_f32 v[204:205], v[172:173], v[220:221], v[204:205] op_sel:[1,0,0]
	v_cvt_pk_f32_fp8_e32 v[214:215], v94
	v_cvt_pk_f32_fp8_sdwa v[216:217], v94 src0_sel:WORD_1
	v_pk_fma_f32 v[206:207], v[172:173], v[214:215], v[206:207] op_sel:[1,0,0]
	v_pk_fma_f32 v[208:209], v[172:173], v[216:217], v[208:209] op_sel:[1,0,0]
	v_cvt_pk_f32_fp8_e32 v[218:219], v95
	v_cvt_pk_f32_fp8_sdwa v[220:221], v95 src0_sel:WORD_1
	v_pk_fma_f32 v[210:211], v[172:173], v[218:219], v[210:211] op_sel:[1,0,0]
	v_pk_fma_f32 v[212:213], v[172:173], v[220:221], v[212:213] op_sel:[1,0,0]
	ds_read_b128 v[170:173], v139 offset:80
	s_waitcnt vmcnt(27)
	v_cvt_pk_f32_fp8_e32 v[214:215], v96
	v_cvt_pk_f32_fp8_sdwa v[216:217], v96 src0_sel:WORD_1
	v_pk_fma_f32 v[198:199], v[174:175], v[214:215], v[198:199] op_sel_hi:[0,1,1]
	v_pk_fma_f32 v[200:201], v[174:175], v[216:217], v[200:201] op_sel_hi:[0,1,1]
	v_cvt_pk_f32_fp8_e32 v[218:219], v97
	v_cvt_pk_f32_fp8_sdwa v[220:221], v97 src0_sel:WORD_1
	v_pk_fma_f32 v[202:203], v[174:175], v[218:219], v[202:203] op_sel_hi:[0,1,1]
	v_pk_fma_f32 v[204:205], v[174:175], v[220:221], v[204:205] op_sel_hi:[0,1,1]
	v_cvt_pk_f32_fp8_e32 v[214:215], v98
	v_cvt_pk_f32_fp8_sdwa v[216:217], v98 src0_sel:WORD_1
	v_pk_fma_f32 v[206:207], v[174:175], v[214:215], v[206:207] op_sel_hi:[0,1,1]
	v_pk_fma_f32 v[208:209], v[174:175], v[216:217], v[208:209] op_sel_hi:[0,1,1]
	v_cvt_pk_f32_fp8_e32 v[218:219], v99
	v_cvt_pk_f32_fp8_sdwa v[220:221], v99 src0_sel:WORD_1
	v_pk_fma_f32 v[210:211], v[174:175], v[218:219], v[210:211] op_sel_hi:[0,1,1]
	v_pk_fma_f32 v[212:213], v[174:175], v[220:221], v[212:213] op_sel_hi:[0,1,1]
	s_waitcnt vmcnt(26)
; #define LAS __attribute__((address_space(3)))
; __device__ __forceinline__ void kv8_issue(u32x4 (&buf)[8], __amdgpu_buffer_rsrc_t rs, int voff  , int sbase  , const int (&iv)[4], int b) {
;     const int jj = b >> 3, l0 = (b & 7) * 8;
;     const int ivb = (jj == 0) ? iv[0] : (jj == 1) ? iv[1] : (jj == 2) ? iv[2] : iv[3];
; #pragma unroll
;     for (int u = 0; u < 8; ++u) { const int si = __builtin_amdgcn_readlane(ivb, l0 + u); buf[u] = __builtin_amdgcn_raw_buffer_load_b128(rs, voff, si * 2048 + sbase, KV8_AUX); }
; }
; __device__ __forceinline__ void kv8_pv(const u32x4 (&buf)[8], f32x2v (&o2)[8], const LAS float* srow, int b) {
;     const LAS f32x4* p4 = (const LAS f32x4*)(srow + b * 8);
;     const f32x4 p0 = p4[0], p1 = p4[1];
;     const float p[8] = {p0.x, p0.y, p0.z, p0.w, p1.x, p1.y, p1.z, p1.w};
; #pragma unroll
;     for (int u = 0; u < 8; ++u) {
;         const u32x4 v = buf[u]; const f32x2v pp = {p[u], p[u]};
;         o2[0] = __builtin_elementwise_fma(pp, __builtin_amdgcn_cvt_pk_f32_fp8(v.x, false), o2[0]); o2[1] = __builtin_elementwise_fma(pp, __builtin_amdgcn_cvt_pk_f32_fp8(v.x, true), o2[1]);
;         o2[2] = __builtin_elementwise_fma(pp, __builtin_amdgcn_cvt_pk_f32_fp8(v.y, false), o2[2]); o2[3] = __builtin_elementwise_fma(pp, __builtin_amdgcn_cvt_pk_f32_fp8(v.y, true), o2[3]);
;         o2[4] = __builtin_elementwise_fma(pp, __builtin_amdgcn_cvt_pk_f32_fp8(v.z, false), o2[4]); o2[5] = __builtin_elementwise_fma(pp, __builtin_amdgcn_cvt_pk_f32_fp8(v.z, true), o2[5]);
;         o2[6] = __builtin_elementwise_fma(pp, __builtin_amdgcn_cvt_pk_f32_fp8(v.w, false), o2[6]); o2[7] = __builtin_elementwise_fma(pp, __builtin_amdgcn_cvt_pk_f32_fp8(v.w, true), o2[7]);
;     }
; }
	v_cvt_pk_f32_fp8_e32 v[214:215], v100
	v_cvt_pk_f32_fp8_sdwa v[216:217], v100 src0_sel:WORD_1
	v_pk_fma_f32 v[198:199], v[174:175], v[214:215], v[198:199] op_sel:[1,0,0]
	v_pk_fma_f32 v[200:201], v[174:175], v[216:217], v[200:201] op_sel:[1,0,0]
	v_cvt_pk_f32_fp8_e32 v[218:219], v101
	v_cvt_pk_f32_fp8_sdwa v[220:221], v101 src0_sel:WORD_1
	v_pk_fma_f32 v[202:203], v[174:175], v[218:219], v[202:203] op_sel:[1,0,0]
	v_pk_fma_f32 v[204:205], v[174:175], v[220:221], v[204:205] op_sel:[1,0,0]
	v_cvt_pk_f32_fp8_e32 v[214:215], v102
	v_cvt_pk_f32_fp8_sdwa v[216:217], v102 src0_sel:WORD_1
	v_pk_fma_f32 v[206:207], v[174:175], v[214:215], v[206:207] op_sel:[1,0,0]
	v_pk_fma_f32 v[208:209], v[174:175], v[216:217], v[208:209] op_sel:[1,0,0]
	v_cvt_pk_f32_fp8_e32 v[218:219], v103
	v_cvt_pk_f32_fp8_sdwa v[220:221], v103 src0_sel:WORD_1
	v_pk_fma_f32 v[210:211], v[174:175], v[218:219], v[210:211] op_sel:[1,0,0]
	v_pk_fma_f32 v[212:213], v[174:175], v[220:221], v[212:213] op_sel:[1,0,0]
	s_waitcnt lgkmcnt(0)
	v_lshl_add_u32 v170, v170, 8, v138
	v_lshl_add_u32 v171, v171, 8, v138
	v_lshl_add_u32 v172, v172, 8, v138
	v_lshl_add_u32 v173, v173, 8, v138
	buffer_load_dwordx4 v[80:83], v170, s[16:19], s26 offen sc0
	buffer_load_dwordx4 v[84:87], v171, s[16:19], s26 offen sc0
	buffer_load_dwordx4 v[88:91], v172, s[16:19], s26 offen sc0
	buffer_load_dwordx4 v[92:95], v173, s[16:19], s26 offen sc0
	s_waitcnt vmcnt(29)
	v_cvt_pk_f32_fp8_e32 v[214:215], v104
	v_cvt_pk_f32_fp8_sdwa v[216:217], v104 src0_sel:WORD_1
	v_pk_fma_f32 v[198:199], v[176:177], v[214:215], v[198:199] op_sel_hi:[0,1,1]
	v_pk_fma_f32 v[200:201], v[176:177], v[216:217], v[200:201] op_sel_hi:[0,1,1]
	v_cvt_pk_f32_fp8_e32 v[218:219], v105
	v_cvt_pk_f32_fp8_sdwa v[220:221], v105 src0_sel:WORD_1
	v_pk_fma_f32 v[202:203], v[176:177], v[218:219], v[202:203] op_sel_hi:[0,1,1]
	v_pk_fma_f32 v[204:205], v[176:177], v[220:221], v[204:205] op_sel_hi:[0,1,1]
	v_cvt_pk_f32_fp8_e32 v[214:215], v106
	v_cvt_pk_f32_fp8_sdwa v[216:217], v106 src0_sel:WORD_1
	v_pk_fma_f32 v[206:207], v[176:177], v[214:215], v[206:207] op_sel_hi:[0,1,1]
	v_pk_fma_f32 v[208:209], v[176:177], v[216:217], v[208:209] op_sel_hi:[0,1,1]
	v_cvt_pk_f32_fp8_e32 v[218:219], v107
	v_cvt_pk_f32_fp8_sdwa v[220:221], v107 src0_sel:WORD_1
	v_pk_fma_f32 v[210:211], v[176:177], v[218:219], v[210:211] op_sel_hi:[0,1,1]
	v_pk_fma_f32 v[212:213], v[176:177], v[220:221], v[212:213] op_sel_hi:[0,1,1]
	s_waitcnt vmcnt(28)
	v_cvt_pk_f32_fp8_e32 v[214:215], v108
	v_cvt_pk_f32_fp8_sdwa v[216:217], v108 src0_sel:WORD_1
	v_pk_fma_f32 v[198:199], v[176:177], v[214:215], v[198:199] op_sel:[1,0,0]
	v_pk_fma_f32 v[200:201], v[176:177], v[216:217], v[200:201] op_sel:[1,0,0]
	v_cvt_pk_f32_fp8_e32 v[218:219], v109
	v_cvt_pk_f32_fp8_sdwa v[220:221], v109 src0_sel:WORD_1
	v_pk_fma_f32 v[202:203], v[176:177], v[218:219], v[202:203] op_sel:[1,0,0]
	v_pk_fma_f32 v[204:205], v[176:177], v[220:221], v[204:205] op_sel:[1,0,0]
	v_cvt_pk_f32_fp8_e32 v[214:215], v110
	v_cvt_pk_f32_fp8_sdwa v[216:217], v110 src0_sel:WORD_1
	v_pk_fma_f32 v[206:207], v[176:177], v[214:215], v[206:207] op_sel:[1,0,0]
	v_pk_fma_f32 v[208:209], v[176:177], v[216:217], v[208:209] op_sel:[1,0,0]
	v_cvt_pk_f32_fp8_e32 v[218:219], v111
	v_cvt_pk_f32_fp8_sdwa v[220:221], v111 src0_sel:WORD_1
	v_pk_fma_f32 v[210:211], v[176:177], v[218:219], v[210:211] op_sel:[1,0,0]
	v_pk_fma_f32 v[212:213], v[176:177], v[220:221], v[212:213] op_sel:[1,0,0]
	ds_read_b128 v[174:177], v139 offset:96
	s_waitcnt vmcnt(27)
	v_cvt_pk_f32_fp8_e32 v[214:215], v112
	v_cvt_pk_f32_fp8_sdwa v[216:217], v112 src0_sel:WORD_1
	v_pk_fma_f32 v[198:199], v[178:179], v[214:215], v[198:199] op_sel_hi:[0,1,1]
	v_pk_fma_f32 v[200:201], v[178:179], v[216:217], v[200:201] op_sel_hi:[0,1,1]
	v_cvt_pk_f32_fp8_e32 v[218:219], v113
	v_cvt_pk_f32_fp8_sdwa v[220:221], v113 src0_sel:WORD_1
	v_pk_fma_f32 v[202:203], v[178:179], v[218:219], v[202:203] op_sel_hi:[0,1,1]
	v_pk_fma_f32 v[204:205], v[178:179], v[220:221], v[204:205] op_sel_hi:[0,1,1]
	v_cvt_pk_f32_fp8_e32 v[214:215], v114
	v_cvt_pk_f32_fp8_sdwa v[216:217], v114 src0_sel:WORD_1
	v_pk_fma_f32 v[206:207], v[178:179], v[214:215], v[206:207] op_sel_hi:[0,1,1]
	v_pk_fma_f32 v[208:209], v[178:179], v[216:217], v[208:209] op_sel_hi:[0,1,1]
	v_cvt_pk_f32_fp8_e32 v[218:219], v115
	v_cvt_pk_f32_fp8_sdwa v[220:221], v115 src0_sel:WORD_1
	v_pk_fma_f32 v[210:211], v[178:179], v[218:219], v[210:211] op_sel_hi:[0,1,1]
	v_pk_fma_f32 v[212:213], v[178:179], v[220:221], v[212:213] op_sel_hi:[0,1,1]
	s_waitcnt vmcnt(26)
	v_cvt_pk_f32_fp8_e32 v[214:215], v116
	v_cvt_pk_f32_fp8_sdwa v[216:217], v116 src0_sel:WORD_1
	v_pk_fma_f32 v[198:199], v[178:179], v[214:215], v[198:199] op_sel:[1,0,0]
	v_pk_fma_f32 v[200:201], v[178:179], v[216:217], v[200:201] op_sel:[1,0,0]
	v_cvt_pk_f32_fp8_e32 v[218:219], v117
	v_cvt_pk_f32_fp8_sdwa v[220:221], v117 src0_sel:WORD_1
	v_pk_fma_f32 v[202:203], v[178:179], v[218:219], v[202:203] op_sel:[1,0,0]
	v_pk_fma_f32 v[204:205], v[178:179], v[220:221], v[204:205] op_sel:[1,0,0]
	v_cvt_pk_f32_fp8_e32 v[214:215], v118
	v_cvt_pk_f32_fp8_sdwa v[216:217], v118 src0_sel:WORD_1
	v_pk_fma_f32 v[206:207], v[178:179], v[214:215], v[206:207] op_sel:[1,0,0]
	v_pk_fma_f32 v[208:209], v[178:179], v[216:217], v[208:209] op_sel:[1,0,0]
	v_cvt_pk_f32_fp8_e32 v[218:219], v119
	v_cvt_pk_f32_fp8_sdwa v[220:221], v119 src0_sel:WORD_1
	v_pk_fma_f32 v[210:211], v[178:179], v[218:219], v[210:211] op_sel:[1,0,0]
	v_pk_fma_f32 v[212:213], v[178:179], v[220:221], v[212:213] op_sel:[1,0,0]
	s_waitcnt lgkmcnt(0)
; __device__ __forceinline__ unsigned cvt_pk_bf16(float lo, float hi) { unsigned r; asm volatile("v_cvt_pk_bf16_f32 %0, %1, %2" : "=v"(r) : "v"(lo), "v"(hi)); return r; }
; #define LAS __attribute__((address_space(3)))
; __device__ __forceinline__ void kv8_pv(const u32x4 (&buf)[8], f32x2v (&o2)[8], const LAS float* srow, int b) {
;     const LAS f32x4* p4 = (const LAS f32x4*)(srow + b * 8);
;     const f32x4 p0 = p4[0], p1 = p4[1];
;     const float p[8] = {p0.x, p0.y, p0.z, p0.w, p1.x, p1.y, p1.z, p1.w};
; #pragma unroll
;     for (int u = 0; u < 8; ++u) {
;         const u32x4 v = buf[u]; const f32x2v pp = {p[u], p[u]};
;         o2[0] = __builtin_elementwise_fma(pp, __builtin_amdgcn_cvt_pk_f32_fp8(v.x, false), o2[0]); o2[1] = __builtin_elementwise_fma(pp, __builtin_amdgcn_cvt_pk_f32_fp8(v.x, true), o2[1]);
;         o2[2] = __builtin_elementwise_fma(pp, __builtin_amdgcn_cvt_pk_f32_fp8(v.y, false), o2[2]); o2[3] = __builtin_elementwise_fma(pp, __builtin_amdgcn_cvt_pk_f32_fp8(v.y, true), o2[3]);
;         o2[4] = __builtin_elementwise_fma(pp, __builtin_amdgcn_cvt_pk_f32_fp8(v.z, false), o2[4]); o2[5] = __builtin_elementwise_fma(pp, __builtin_amdgcn_cvt_pk_f32_fp8(v.z, true), o2[5]);
;         o2[6] = __builtin_elementwise_fma(pp, __builtin_amdgcn_cvt_pk_f32_fp8(v.w, false), o2[6]); o2[7] = __builtin_elementwise_fma(pp, __builtin_amdgcn_cvt_pk_f32_fp8(v.w, true), o2[7]);
;     }
; }
; __device__ __forceinline__ void attn_query8(const unsigned char* __restrict__ KV8, const bf16_t* __restrict__ Z, const int* __restrict__ SEL, bf16_t* __restrict__ YMIX, int t, LAS float* sbuf  ) {
;     ...
;     u32x4 o0, o1;
;     o0.x = cvt_pk_bf16(o[0].x, o[0].y); o0.y = cvt_pk_bf16(o[1].x, o[1].y); o0.z = cvt_pk_bf16(o[2].x, o[2].y); o0.w = cvt_pk_bf16(o[3].x, o[3].y);
;     o1.x = cvt_pk_bf16(o[4].x, o[4].y); o1.y = cvt_pk_bf16(o[5].x, o[5].y); o1.z = cvt_pk_bf16(o[6].x, o[6].y); o1.w = cvt_pk_bf16(o[7].x, o[7].y);
	v_lshl_add_u32 v174, v174, 8, v138
	v_lshl_add_u32 v175, v175, 8, v138
	v_lshl_add_u32 v176, v176, 8, v138
	v_lshl_add_u32 v177, v177, 8, v138
	buffer_load_dwordx4 v[96:99], v174, s[16:19], s26 offen sc0
	buffer_load_dwordx4 v[100:103], v175, s[16:19], s26 offen sc0
	buffer_load_dwordx4 v[104:107], v176, s[16:19], s26 offen sc0
	buffer_load_dwordx4 v[108:111], v177, s[16:19], s26 offen sc0
	s_waitcnt vmcnt(29)
	v_cvt_pk_f32_fp8_e32 v[214:215], v120
	v_cvt_pk_f32_fp8_sdwa v[216:217], v120 src0_sel:WORD_1
	v_pk_fma_f32 v[198:199], v[180:181], v[214:215], v[198:199] op_sel_hi:[0,1,1]
	v_pk_fma_f32 v[200:201], v[180:181], v[216:217], v[200:201] op_sel_hi:[0,1,1]
	v_cvt_pk_f32_fp8_e32 v[218:219], v121
	v_cvt_pk_f32_fp8_sdwa v[220:221], v121 src0_sel:WORD_1
	v_pk_fma_f32 v[202:203], v[180:181], v[218:219], v[202:203] op_sel_hi:[0,1,1]
	v_pk_fma_f32 v[204:205], v[180:181], v[220:221], v[204:205] op_sel_hi:[0,1,1]
	v_cvt_pk_f32_fp8_e32 v[214:215], v122
	v_cvt_pk_f32_fp8_sdwa v[216:217], v122 src0_sel:WORD_1
	v_pk_fma_f32 v[206:207], v[180:181], v[214:215], v[206:207] op_sel_hi:[0,1,1]
	v_pk_fma_f32 v[208:209], v[180:181], v[216:217], v[208:209] op_sel_hi:[0,1,1]
	v_cvt_pk_f32_fp8_e32 v[218:219], v123
	v_cvt_pk_f32_fp8_sdwa v[220:221], v123 src0_sel:WORD_1
	v_pk_fma_f32 v[210:211], v[180:181], v[218:219], v[210:211] op_sel_hi:[0,1,1]
	v_pk_fma_f32 v[212:213], v[180:181], v[220:221], v[212:213] op_sel_hi:[0,1,1]
	s_waitcnt vmcnt(28)
	v_cvt_pk_f32_fp8_e32 v[214:215], v124
	v_cvt_pk_f32_fp8_sdwa v[216:217], v124 src0_sel:WORD_1
	v_pk_fma_f32 v[198:199], v[180:181], v[214:215], v[198:199] op_sel:[1,0,0]
	v_pk_fma_f32 v[200:201], v[180:181], v[216:217], v[200:201] op_sel:[1,0,0]
	v_cvt_pk_f32_fp8_e32 v[218:219], v125
	v_cvt_pk_f32_fp8_sdwa v[220:221], v125 src0_sel:WORD_1
	v_pk_fma_f32 v[202:203], v[180:181], v[218:219], v[202:203] op_sel:[1,0,0]
	v_pk_fma_f32 v[204:205], v[180:181], v[220:221], v[204:205] op_sel:[1,0,0]
	v_cvt_pk_f32_fp8_e32 v[214:215], v126
	v_cvt_pk_f32_fp8_sdwa v[216:217], v126 src0_sel:WORD_1
	v_pk_fma_f32 v[206:207], v[180:181], v[214:215], v[206:207] op_sel:[1,0,0]
	v_pk_fma_f32 v[208:209], v[180:181], v[216:217], v[208:209] op_sel:[1,0,0]
	v_cvt_pk_f32_fp8_e32 v[218:219], v127
	v_cvt_pk_f32_fp8_sdwa v[220:221], v127 src0_sel:WORD_1
	v_pk_fma_f32 v[210:211], v[180:181], v[218:219], v[210:211] op_sel:[1,0,0]
	v_pk_fma_f32 v[212:213], v[180:181], v[220:221], v[212:213] op_sel:[1,0,0]
	ds_read_b128 v[178:181], v139 offset:112
	v_add_f32_dpp v198, v198, v198 row_ror:8 row_mask:0xf bank_mask:0xf
	v_add_f32_dpp v199, v199, v199 row_ror:8 row_mask:0xf bank_mask:0xf
	v_add_f32_dpp v200, v200, v200 row_ror:8 row_mask:0xf bank_mask:0xf
	v_add_f32_dpp v201, v201, v201 row_ror:8 row_mask:0xf bank_mask:0xf
	v_add_f32_dpp v202, v202, v202 row_ror:8 row_mask:0xf bank_mask:0xf
	v_add_f32_dpp v203, v203, v203 row_ror:8 row_mask:0xf bank_mask:0xf
	v_add_f32_dpp v204, v204, v204 row_ror:8 row_mask:0xf bank_mask:0xf
	v_add_f32_dpp v205, v205, v205 row_ror:8 row_mask:0xf bank_mask:0xf
	v_add_f32_dpp v206, v206, v206 row_ror:8 row_mask:0xf bank_mask:0xf
	v_add_f32_dpp v207, v207, v207 row_ror:8 row_mask:0xf bank_mask:0xf
	v_add_f32_dpp v208, v208, v208 row_ror:8 row_mask:0xf bank_mask:0xf
	v_add_f32_dpp v209, v209, v209 row_ror:8 row_mask:0xf bank_mask:0xf
	v_add_f32_dpp v210, v210, v210 row_ror:8 row_mask:0xf bank_mask:0xf
	v_add_f32_dpp v211, v211, v211 row_ror:8 row_mask:0xf bank_mask:0xf
	v_add_f32_dpp v212, v212, v212 row_ror:8 row_mask:0xf bank_mask:0xf
	v_add_f32_dpp v213, v213, v213 row_ror:8 row_mask:0xf bank_mask:0xf
	s_waitcnt lgkmcnt(0)
; __device__ __forceinline__ unsigned cvt_pk_bf16(float lo, float hi) { unsigned r; asm volatile("v_cvt_pk_bf16_f32 %0, %1, %2" : "=v"(r) : "v"(lo), "v"(hi)); return r; }
; #define LDS_WAIT() asm volatile("s_waitcnt lgkmcnt(0)" ::: "memory")
; __device__ __forceinline__ void attn_query8(const unsigned char* __restrict__ KV8, const bf16_t* __restrict__ Z, const int* __restrict__ SEL, bf16_t* __restrict__ YMIX, int t, LAS float* sbuf  ) {
;     ...
;     u32x4 o0, o1;
;     o0.x = cvt_pk_bf16(o[0].x, o[0].y); o0.y = cvt_pk_bf16(o[1].x, o[1].y); o0.z = cvt_pk_bf16(o[2].x, o[2].y); o0.w = cvt_pk_bf16(o[3].x, o[3].y);
;     o1.x = cvt_pk_bf16(o[4].x, o[4].y); o1.y = cvt_pk_bf16(o[5].x, o[5].y); o1.z = cvt_pk_bf16(o[6].x, o[6].y); o1.w = cvt_pk_bf16(o[7].x, o[7].y);
;     u32x4* yp = (u32x4*)(YMIX + (size_t)t * D_ + 1024 + lane * 16);
;     yp[0] = o0; yp[1] = o1;
;     LDS_WAIT();
; __global__ void __launch_bounds__(512, 2) mega(Params p) {
;     ...
;         for (int t = gw; t < S_; t += ngw) attn_query8(KV8, Z, SEL, YMIX, t, sbuf);
	v_lshl_add_u32 v178, v178, 8, v138
	v_lshl_add_u32 v179, v179, 8, v138
	v_lshl_add_u32 v180, v180, 8, v138
	v_lshl_add_u32 v181, v181, 8, v138
	buffer_load_dwordx4 v[112:115], v178, s[16:19], s26 offen sc0
	buffer_load_dwordx4 v[116:119], v179, s[16:19], s26 offen sc0
	buffer_load_dwordx4 v[120:123], v180, s[16:19], s26 offen sc0
	buffer_load_dwordx4 v[124:127], v181, s[16:19], s26 offen sc0
	ds_bpermute_b32 v214, v140, v198
	ds_bpermute_b32 v215, v140, v199
	ds_bpermute_b32 v216, v140, v200
	ds_bpermute_b32 v217, v140, v201
	ds_bpermute_b32 v218, v140, v202
	ds_bpermute_b32 v219, v140, v203
	ds_bpermute_b32 v220, v140, v204
	ds_bpermute_b32 v221, v140, v205
	ds_bpermute_b32 v222, v140, v206
	ds_bpermute_b32 v223, v140, v207
	ds_bpermute_b32 v224, v140, v208
	ds_bpermute_b32 v225, v140, v209
	ds_bpermute_b32 v226, v140, v210
	ds_bpermute_b32 v227, v140, v211
	ds_bpermute_b32 v228, v140, v212
	ds_bpermute_b32 v229, v140, v213
	s_waitcnt lgkmcnt(0)
	v_add_f32_e32 v198, v198, v214
	v_add_f32_e32 v199, v199, v215
	v_add_f32_e32 v200, v200, v216
	v_add_f32_e32 v201, v201, v217
	v_add_f32_e32 v202, v202, v218
	v_add_f32_e32 v203, v203, v219
	v_add_f32_e32 v204, v204, v220
	v_add_f32_e32 v205, v205, v221
	v_add_f32_e32 v206, v206, v222
	v_add_f32_e32 v207, v207, v223
	v_add_f32_e32 v208, v208, v224
	v_add_f32_e32 v209, v209, v225
	v_add_f32_e32 v210, v210, v226
	v_add_f32_e32 v211, v211, v227
	v_add_f32_e32 v212, v212, v228
	v_add_f32_e32 v213, v213, v229
	ds_bpermute_b32 v214, v141, v198
	ds_bpermute_b32 v215, v141, v199
	ds_bpermute_b32 v216, v141, v200
	ds_bpermute_b32 v217, v141, v201
	ds_bpermute_b32 v218, v141, v202
	ds_bpermute_b32 v219, v141, v203
	ds_bpermute_b32 v220, v141, v204
	ds_bpermute_b32 v221, v141, v205
	ds_bpermute_b32 v222, v141, v206
	ds_bpermute_b32 v223, v141, v207
	ds_bpermute_b32 v224, v141, v208
	ds_bpermute_b32 v225, v141, v209
	ds_bpermute_b32 v226, v141, v210
	ds_bpermute_b32 v227, v141, v211
	ds_bpermute_b32 v228, v141, v212
	ds_bpermute_b32 v229, v141, v213
	s_waitcnt lgkmcnt(0)
	v_add_f32_e32 v198, v198, v214
	v_add_f32_e32 v199, v199, v215
	v_add_f32_e32 v200, v200, v216
	v_add_f32_e32 v201, v201, v217
	v_add_f32_e32 v202, v202, v218
	v_add_f32_e32 v203, v203, v219
	v_add_f32_e32 v204, v204, v220
	v_add_f32_e32 v205, v205, v221
	v_add_f32_e32 v206, v206, v222
	v_add_f32_e32 v207, v207, v223
	v_add_f32_e32 v208, v208, v224
	v_add_f32_e32 v209, v209, v225
	v_add_f32_e32 v210, v210, v226
	v_add_f32_e32 v211, v211, v227
	v_add_f32_e32 v212, v212, v228
	v_add_f32_e32 v213, v213, v229
	s_ashr_i32 s81, s80, 31
	s_lshl_b64 s[10:11], s[80:81], 12
	s_add_u32 s10, s14, s10
	s_addc_u32 s11, s15, s11
	v_mul_f32_e32 v198, v198, v149
	v_mul_f32_e32 v199, v199, v149
	v_mul_f32_e32 v200, v200, v149
	v_mul_f32_e32 v201, v201, v149
	v_mul_f32_e32 v202, v202, v149
	v_mul_f32_e32 v203, v203, v149
	v_mul_f32_e32 v204, v204, v149
	v_mul_f32_e32 v205, v205, v149
	v_mul_f32_e32 v206, v206, v149
	v_mul_f32_e32 v207, v207, v149
	v_mul_f32_e32 v208, v208, v149
	v_mul_f32_e32 v209, v209, v149
	v_mul_f32_e32 v210, v210, v149
	v_mul_f32_e32 v211, v211, v149
	v_mul_f32_e32 v212, v212, v149
	v_mul_f32_e32 v213, v213, v149
	v_cvt_pk_bf16_f32 v214, v198, v199
	v_cvt_pk_bf16_f32 v215, v200, v201
	v_cvt_pk_bf16_f32 v216, v202, v203
	v_cvt_pk_bf16_f32 v217, v204, v205
	v_cvt_pk_bf16_f32 v218, v206, v207
	v_cvt_pk_bf16_f32 v219, v208, v209
	v_cvt_pk_bf16_f32 v220, v210, v211
	v_cvt_pk_bf16_f32 v221, v212, v213
	v_cmp_gt_u32_e32 vcc, 8, v144
	s_and_saveexec_b64 s[12:13], vcc
	global_store_dwordx4 v146, v[214:217], s[10:11] offset:2048
	global_store_dwordx4 v146, v[218:221], s[10:11] offset:2064
	s_mov_b64 exec, s[12:13]
	s_addk_i32 s80, 0x100
	s_cmpk_gt_i32 s80, 0x3fff
	s_cbranch_scc0 .Latt_unit
	s_waitcnt vmcnt(0)
